# s_setprio 2 around QK and PV MFMA runs in the attention tile loops (on top of barrier and attention fixes)
# baseline (speedup 1.0000x reference)
; __device__ __forceinline__ unsigned pk2(float lo, float hi) { f32x2 v = {lo, hi}; bf16x2_t b = __builtin_convertvector(v, bf16x2_t); return __builtin_bit_cast(unsigned, b); }
; template <int TYPE, int ND0, int KSTR> __device__ __forceinline__ void tile(LAS unsigned char* lds, int buf, int t, int w_lo, int w_hi, int n, int qrel, int lane, int r32, int hi,
;         const bf16x8 (&qr)[ND0], float& m_run, float& l_run, f32x16& o0, f32x16& o1, f32x16& negm) {
;     ...
; #pragma unroll
;     for (int ks = 0; ks < 4; ++ks) {
;         u32x4 pw;
;         if (ks < 2) { pw.x = pk2(p0[8 * ks], p0[8 * ks + 1]); pw.y = pk2(p0[8 * ks + 2], p0[8 * ks + 3]); pw.z = pk2(p0[8 * ks + 4], p0[8 * ks + 5]); pw.w = pk2(p0[8 * ks + 6], p0[8 * ks + 7]); }
;         else { const int k2 = ks - 2; pw.x = pk2(p1[8 * k2], p1[8 * k2 + 1]); pw.y = pk2(p1[8 * k2 + 2], p1[8 * k2 + 3]); pw.z = pk2(p1[8 * k2 + 4], p1[8 * k2 + 5]); pw.w = pk2(p1[8 * k2 + 6], p1[8 * k2 + 7]); }
;         const bf16x8 pb = __builtin_bit_cast(bf16x8, pw);
;         const bf16x8 va0 = __builtin_shufflevector(vf[ks][0], vf[ks][1], 0, 1, 2, 3, 4, 5, 6, 7), va1 = __builtin_shufflevector(vf[ks][2], vf[ks][3], 0, 1, 2, 3, 4, 5, 6, 7);
;         o0 = __builtin_amdgcn_mfma_f32_32x32x16_bf16(va0, pb, o0, 0, 0, 0);
;         o1 = __builtin_amdgcn_mfma_f32_32x32x16_bf16(va1, pb, o1, 0, 0, 0);
;     }
.LBB0_586:
	v_cvt_pk_bf16_f32 v106, v106, v132
	v_cvt_pk_bf16_f32 v107, v108, v136
	v_cvt_pk_bf16_f32 v108, v110, v140
	v_cvt_pk_bf16_f32 v109, v114, v142
	v_add_f32_e32 v166, v166, v152
	s_waitcnt lgkmcnt(14)
	s_setprio 2
	v_mfma_f32_32x32x16_bf16 v[32:47], v[96:99], v[106:109], v[32:47]
	s_waitcnt lgkmcnt(12)
	v_mfma_f32_32x32x16_bf16 v[16:31], v[92:95], v[106:109], v[16:31]
	v_cvt_pk_bf16_f32 v92, v112, v144
	v_cvt_pk_bf16_f32 v93, v116, v146
	v_cvt_pk_bf16_f32 v94, v118, v148
	v_cvt_pk_bf16_f32 v95, v120, v150
	s_waitcnt lgkmcnt(10)
	s_nop 0
	v_mfma_f32_32x32x16_bf16 v[32:47], v[68:71], v[92:95], v[32:47]
	s_waitcnt lgkmcnt(8)
	v_mfma_f32_32x32x16_bf16 v[16:31], v[64:67], v[92:95], v[16:31]
	v_cvt_pk_bf16_f32 v64, v14, v0
	v_cvt_pk_bf16_f32 v65, v100, v122
	v_cvt_pk_bf16_f32 v66, v102, v124
	v_cvt_pk_bf16_f32 v67, v104, v126
	s_waitcnt lgkmcnt(6)
	s_nop 0
	v_mfma_f32_32x32x16_bf16 v[32:47], v[52:55], v[64:67], v[32:47]
	s_waitcnt lgkmcnt(4)
	v_mfma_f32_32x32x16_bf16 v[16:31], v[48:51], v[64:67], v[16:31]
	v_cvt_pk_bf16_f32 v48, v72, v128
	v_cvt_pk_bf16_f32 v49, v74, v130
	v_cvt_pk_bf16_f32 v50, v76, v134
	v_cvt_pk_bf16_f32 v51, v78, v138
	s_waitcnt lgkmcnt(2)
	s_nop 0
	v_mfma_f32_32x32x16_bf16 v[32:47], v[60:63], v[48:51], v[32:47]
	s_waitcnt lgkmcnt(0)
	v_mfma_f32_32x32x16_bf16 v[16:31], v[56:59], v[48:51], v[16:31]
	s_setprio 0

; #define LAS __attribute__((address_space(3)))
; template <int TYPE, int ND0, int KSTR> __device__ __forceinline__ void tile(LAS unsigned char* lds, int buf, int t, int w_lo, int w_hi, int n, int qrel, int lane, int r32, int hi,
;         const bf16x8 (&qr)[ND0], float& m_run, float& l_run, f32x16& o0, f32x16& o1, f32x16& negm) {
;     ...
;     for (int d0 = 0; d0 < ND0; ++d0) {
;         p0 = __builtin_amdgcn_mfma_f32_32x32x16_bf16(ka[d0], qr[d0], p0, 0, 0, 0);
;         p1 = __builtin_amdgcn_mfma_f32_32x32x16_bf16(kc[d0], qr[d0], p1, 0, 0, 0);
;     }
;     ...
;     if (TYPE == 2 && rel < 5) {
;         const LAS float* rb = (const LAS float*)(lds + RELOFF) + (qrel + 64 * rel + 256 - 4 * hi - 59);
; #pragma unroll
;         for (int r = 0; r < 16; ++r) { p0[r] += rb[59 - ((r & 3) + 8 * (r >> 2))]; p1[r] += rb[27 - ((r & 3) + 8 * (r >> 2))]; }
;     }
.LBB0_610:
	s_waitcnt lgkmcnt(14)
	s_nop 0
	s_setprio 2
	v_mfma_f32_32x32x16_bf16 v[80:95], v[196:199], v[132:135], v[64:79]
	s_cmp_gt_i32 s38, 4
	v_mfma_f32_32x32x16_bf16 v[64:79], v[200:203], v[132:135], v[64:79]
	v_mfma_f32_32x32x16_bf16 v[80:95], v[184:187], v[128:131], v[80:95]
	v_mfma_f32_32x32x16_bf16 v[64:79], v[188:191], v[128:131], v[64:79]
	s_waitcnt vmcnt(3)
	v_mfma_f32_32x32x16_bf16 v[80:95], v[180:183], v[124:127], v[80:95]
	v_mfma_f32_32x32x16_bf16 v[64:79], v[192:195], v[124:127], v[64:79]
	s_waitcnt vmcnt(2)
	v_mfma_f32_32x32x16_bf16 v[80:95], v[176:179], v[120:123], v[80:95]
	v_mfma_f32_32x32x16_bf16 v[64:79], v[172:175], v[120:123], v[64:79]
	s_setprio 0
	s_cbranch_scc1 .LBB0_612
	ds_read2_b32 v[196:197], v247 offset0:122 offset1:123
	ds_read2_b32 v[198:199], v247 offset0:90 offset1:91
	ds_read2_b32 v[200:201], v247 offset0:120 offset1:121
	ds_read2_b32 v[202:203], v247 offset0:88 offset1:89
	ds_read2_b32 v[184:185], v247 offset0:114 offset1:115
	ds_read2_b32 v[186:187], v247 offset0:82 offset1:83
	ds_read2_b32 v[188:189], v247 offset0:112 offset1:113
	ds_read2_b32 v[190:191], v247 offset0:80 offset1:81
	ds_read2_b32 v[180:181], v247 offset0:106 offset1:107
	ds_read2_b32 v[182:183], v247 offset0:74 offset1:75
	ds_read2_b32 v[192:193], v247 offset0:104 offset1:105
	ds_read2_b32 v[194:195], v247 offset0:72 offset1:73
	ds_read2_b32 v[176:177], v247 offset0:98 offset1:99
	ds_read2_b32 v[178:179], v247 offset0:66 offset1:67
	ds_read2_b32 v[172:173], v247 offset0:96 offset1:97
	ds_read2_b32 v[174:175], v247 offset0:64 offset1:65
	s_waitcnt lgkmcnt(15)
	s_nop 7
	v_pk_add_f32 v[80:81], v[80:81], v[196:197] op_sel:[0,1] op_sel_hi:[1,0]
	s_waitcnt lgkmcnt(14)
	v_pk_add_f32 v[64:65], v[64:65], v[198:199] op_sel:[0,1] op_sel_hi:[1,0]
	s_waitcnt lgkmcnt(13)
	v_pk_add_f32 v[82:83], v[82:83], v[200:201] op_sel:[0,1] op_sel_hi:[1,0]
	s_waitcnt lgkmcnt(12)
	v_pk_add_f32 v[66:67], v[66:67], v[202:203] op_sel:[0,1] op_sel_hi:[1,0]
	s_waitcnt lgkmcnt(11)
	v_pk_add_f32 v[84:85], v[84:85], v[184:185] op_sel:[0,1] op_sel_hi:[1,0]
	s_waitcnt lgkmcnt(10)
	v_pk_add_f32 v[68:69], v[68:69], v[186:187] op_sel:[0,1] op_sel_hi:[1,0]
	s_waitcnt lgkmcnt(9)
	v_pk_add_f32 v[86:87], v[86:87], v[188:189] op_sel:[0,1] op_sel_hi:[1,0]
	s_waitcnt lgkmcnt(8)
	v_pk_add_f32 v[70:71], v[70:71], v[190:191] op_sel:[0,1] op_sel_hi:[1,0]
	s_waitcnt lgkmcnt(7)
	v_pk_add_f32 v[88:89], v[88:89], v[180:181] op_sel:[0,1] op_sel_hi:[1,0]
	s_waitcnt lgkmcnt(6)
	v_pk_add_f32 v[72:73], v[72:73], v[182:183] op_sel:[0,1] op_sel_hi:[1,0]
	s_waitcnt lgkmcnt(5)
	v_pk_add_f32 v[90:91], v[90:91], v[192:193] op_sel:[0,1] op_sel_hi:[1,0]
	s_waitcnt lgkmcnt(4)
	v_pk_add_f32 v[74:75], v[74:75], v[194:195] op_sel:[0,1] op_sel_hi:[1,0]
	s_waitcnt lgkmcnt(3)
	v_pk_add_f32 v[92:93], v[92:93], v[176:177] op_sel:[0,1] op_sel_hi:[1,0]
	s_waitcnt lgkmcnt(2)
	v_pk_add_f32 v[76:77], v[76:77], v[178:179] op_sel:[0,1] op_sel_hi:[1,0]
	s_waitcnt lgkmcnt(1)
	v_pk_add_f32 v[94:95], v[94:95], v[172:173] op_sel:[0,1] op_sel_hi:[1,0]
	s_waitcnt lgkmcnt(0)
	v_pk_add_f32 v[78:79], v[78:79], v[174:175] op_sel:[0,1] op_sel_hi:[1,0]

; __device__ __forceinline__ unsigned pk2(float lo, float hi) { f32x2 v = {lo, hi}; bf16x2_t b = __builtin_convertvector(v, bf16x2_t); return __builtin_bit_cast(unsigned, b); }
; template <int TYPE, int ND0, int KSTR> __device__ __forceinline__ void tile(LAS unsigned char* lds, int buf, int t, int w_lo, int w_hi, int n, int qrel, int lane, int r32, int hi,
;         const bf16x8 (&qr)[ND0], float& m_run, float& l_run, f32x16& o0, f32x16& o1, f32x16& negm) {
;     ...
; #pragma unroll
;     for (int ks = 0; ks < 4; ++ks) {
;         u32x4 pw;
;         if (ks < 2) { pw.x = pk2(p0[8 * ks], p0[8 * ks + 1]); pw.y = pk2(p0[8 * ks + 2], p0[8 * ks + 3]); pw.z = pk2(p0[8 * ks + 4], p0[8 * ks + 5]); pw.w = pk2(p0[8 * ks + 6], p0[8 * ks + 7]); }
;         else { const int k2 = ks - 2; pw.x = pk2(p1[8 * k2], p1[8 * k2 + 1]); pw.y = pk2(p1[8 * k2 + 2], p1[8 * k2 + 3]); pw.z = pk2(p1[8 * k2 + 4], p1[8 * k2 + 5]); pw.w = pk2(p1[8 * k2 + 6], p1[8 * k2 + 7]); }
;         const bf16x8 pb = __builtin_bit_cast(bf16x8, pw);
;         const bf16x8 va0 = __builtin_shufflevector(vf[ks][0], vf[ks][1], 0, 1, 2, 3, 4, 5, 6, 7), va1 = __builtin_shufflevector(vf[ks][2], vf[ks][3], 0, 1, 2, 3, 4, 5, 6, 7);
;         o0 = __builtin_amdgcn_mfma_f32_32x32x16_bf16(va0, pb, o0, 0, 0, 0);
;         o1 = __builtin_amdgcn_mfma_f32_32x32x16_bf16(va1, pb, o1, 0, 0, 0);
;     }
.LBB0_616:
	v_cvt_pk_bf16_f32 v80, v80, v0
	v_cvt_pk_bf16_f32 v81, v82, v188
	v_cvt_pk_bf16_f32 v82, v84, v190
	v_cvt_pk_bf16_f32 v83, v172, v194
	v_cvt_pk_bf16_f32 v65, v72, v184
	v_cvt_pk_bf16_f32 v67, v76, v78
	s_setprio 2
	v_mfma_f32_32x32x16_bf16 v[32:47], v[164:167], v[80:83], v[32:47]
	v_add_f32_e32 v222, v222, v94
	s_waitcnt lgkmcnt(12)
	v_mfma_f32_32x32x16_bf16 v[16:31], v[168:171], v[80:83], v[16:31]
	v_cvt_pk_bf16_f32 v80, v86, v192
	v_cvt_pk_bf16_f32 v81, v88, v196
	v_cvt_pk_bf16_f32 v82, v90, v198
	v_cvt_pk_bf16_f32 v83, v92, v200
	s_waitcnt lgkmcnt(10)
	s_nop 0
	v_mfma_f32_32x32x16_bf16 v[32:47], v[156:159], v[80:83], v[32:47]
	s_waitcnt lgkmcnt(8)
	v_mfma_f32_32x32x16_bf16 v[16:31], v[160:163], v[80:83], v[16:31]
	v_cvt_pk_bf16_f32 v80, v14, v174
	v_cvt_pk_bf16_f32 v81, v64, v176
	v_cvt_pk_bf16_f32 v82, v66, v178
	v_cvt_pk_bf16_f32 v83, v70, v182
	v_cvt_pk_bf16_f32 v64, v68, v180
	v_cvt_pk_bf16_f32 v66, v74, v186
	s_waitcnt lgkmcnt(6)
	v_mfma_f32_32x32x16_bf16 v[32:47], v[148:151], v[80:83], v[32:47]
	s_waitcnt lgkmcnt(4)
	v_mfma_f32_32x32x16_bf16 v[16:31], v[152:155], v[80:83], v[16:31]
	s_waitcnt lgkmcnt(2)
	v_mfma_f32_32x32x16_bf16 v[32:47], v[144:147], v[64:67], v[32:47]
	s_waitcnt lgkmcnt(0)
	v_mfma_f32_32x32x16_bf16 v[16:31], v[10:13], v[64:67], v[16:31]
	s_setprio 0

; #define LAS __attribute__((address_space(3)))
; template <int TYPE, int ND0, int KSTR> __device__ __forceinline__ void tile(LAS unsigned char* lds, int buf, int t, int w_lo, int w_hi, int n, int qrel, int lane, int r32, int hi,
;         const bf16x8 (&qr)[ND0], float& m_run, float& l_run, f32x16& o0, f32x16& o1, f32x16& negm) {
;     ...
;     for (int d0 = 0; d0 < ND0; ++d0) {
;         p0 = __builtin_amdgcn_mfma_f32_32x32x16_bf16(ka[d0], qr[d0], p0, 0, 0, 0);
;         p1 = __builtin_amdgcn_mfma_f32_32x32x16_bf16(kc[d0], qr[d0], p1, 0, 0, 0);
;     }
;     ...
;     if (TYPE == 2 && rel < 5) {
;         const LAS float* rb = (const LAS float*)(lds + RELOFF) + (qrel + 64 * rel + 256 - 4 * hi - 59);
; #pragma unroll
;         for (int r = 0; r < 16; ++r) { p0[r] += rb[59 - ((r & 3) + 8 * (r >> 2))]; p1[r] += rb[27 - ((r & 3) + 8 * (r >> 2))]; }
;     }
.LBB0_620:
	s_waitcnt lgkmcnt(14)
	s_nop 0
	s_setprio 2
	v_mfma_f32_32x32x16_bf16 v[80:95], v[196:199], v[132:135], v[64:79]
	s_cmp_gt_i32 s2, 4
	v_mfma_f32_32x32x16_bf16 v[64:79], v[200:203], v[132:135], v[64:79]
	v_mfma_f32_32x32x16_bf16 v[80:95], v[184:187], v[128:131], v[80:95]
	v_mfma_f32_32x32x16_bf16 v[64:79], v[188:191], v[128:131], v[64:79]
	v_mfma_f32_32x32x16_bf16 v[80:95], v[180:183], v[124:127], v[80:95]
	v_mfma_f32_32x32x16_bf16 v[64:79], v[192:195], v[124:127], v[64:79]
	v_mfma_f32_32x32x16_bf16 v[80:95], v[176:179], v[120:123], v[80:95]
	v_mfma_f32_32x32x16_bf16 v[64:79], v[172:175], v[120:123], v[64:79]
	s_setprio 0
	s_cbranch_scc1 .LBB0_622
	ds_read2_b32 v[196:197], v247 offset0:58 offset1:59
	ds_read2_b32 v[198:199], v247 offset0:26 offset1:27
	ds_read2_b32 v[200:201], v247 offset0:56 offset1:57
	ds_read2_b32 v[202:203], v247 offset0:24 offset1:25
	ds_read2_b32 v[184:185], v247 offset0:50 offset1:51
	ds_read2_b32 v[186:187], v247 offset0:18 offset1:19
	ds_read2_b32 v[188:189], v247 offset0:48 offset1:49
	ds_read2_b32 v[190:191], v247 offset0:16 offset1:17
	ds_read2_b32 v[180:181], v247 offset0:42 offset1:43
	ds_read2_b32 v[182:183], v247 offset0:10 offset1:11
	ds_read2_b32 v[192:193], v247 offset0:40 offset1:41
	ds_read2_b32 v[194:195], v247 offset0:8 offset1:9
	ds_read2_b32 v[176:177], v247 offset0:34 offset1:35
	ds_read2_b32 v[178:179], v247 offset0:2 offset1:3
	ds_read2_b32 v[172:173], v247 offset0:32 offset1:33
	ds_read2_b32 v[174:175], v247 offset1:1
	s_waitcnt lgkmcnt(15)
	s_nop 7
	v_pk_add_f32 v[80:81], v[80:81], v[196:197] op_sel:[0,1] op_sel_hi:[1,0]
	s_waitcnt lgkmcnt(14)
	v_pk_add_f32 v[64:65], v[64:65], v[198:199] op_sel:[0,1] op_sel_hi:[1,0]
	s_waitcnt lgkmcnt(13)
	v_pk_add_f32 v[82:83], v[82:83], v[200:201] op_sel:[0,1] op_sel_hi:[1,0]
	s_waitcnt lgkmcnt(12)
	v_pk_add_f32 v[66:67], v[66:67], v[202:203] op_sel:[0,1] op_sel_hi:[1,0]
	s_waitcnt lgkmcnt(11)
	v_pk_add_f32 v[84:85], v[84:85], v[184:185] op_sel:[0,1] op_sel_hi:[1,0]
	s_waitcnt lgkmcnt(10)
	v_pk_add_f32 v[68:69], v[68:69], v[186:187] op_sel:[0,1] op_sel_hi:[1,0]
	s_waitcnt lgkmcnt(9)
	v_pk_add_f32 v[86:87], v[86:87], v[188:189] op_sel:[0,1] op_sel_hi:[1,0]
	s_waitcnt lgkmcnt(8)
	v_pk_add_f32 v[70:71], v[70:71], v[190:191] op_sel:[0,1] op_sel_hi:[1,0]
	s_waitcnt lgkmcnt(7)
	v_pk_add_f32 v[88:89], v[88:89], v[180:181] op_sel:[0,1] op_sel_hi:[1,0]
	s_waitcnt lgkmcnt(6)
	v_pk_add_f32 v[72:73], v[72:73], v[182:183] op_sel:[0,1] op_sel_hi:[1,0]
	s_waitcnt lgkmcnt(5)
	v_pk_add_f32 v[90:91], v[90:91], v[192:193] op_sel:[0,1] op_sel_hi:[1,0]
	s_waitcnt lgkmcnt(4)
	v_pk_add_f32 v[74:75], v[74:75], v[194:195] op_sel:[0,1] op_sel_hi:[1,0]
	s_waitcnt lgkmcnt(3)
	v_pk_add_f32 v[92:93], v[92:93], v[176:177] op_sel:[0,1] op_sel_hi:[1,0]
	s_waitcnt lgkmcnt(2)
	v_pk_add_f32 v[76:77], v[76:77], v[178:179] op_sel:[0,1] op_sel_hi:[1,0]
	s_waitcnt lgkmcnt(1)
	v_pk_add_f32 v[94:95], v[94:95], v[172:173] op_sel:[0,1] op_sel_hi:[1,0]
	s_waitcnt lgkmcnt(0)
	v_pk_add_f32 v[78:79], v[78:79], v[174:175] op_sel:[0,1] op_sel_hi:[1,0]

; #define LAS __attribute__((address_space(3)))
; template <int TYPE, int ND0, int KSTR> __device__ __forceinline__ void tile(LAS unsigned char* lds, int buf, int t, int w_lo, int w_hi, int n, int qrel, int lane, int r32, int hi,
;         const bf16x8 (&qr)[ND0], float& m_run, float& l_run, f32x16& o0, f32x16& o1, f32x16& negm) {
;     ...
;     for (int d0 = 0; d0 < ND0; ++d0) {
;         p0 = __builtin_amdgcn_mfma_f32_32x32x16_bf16(ka[d0], qr[d0], p0, 0, 0, 0);
;         p1 = __builtin_amdgcn_mfma_f32_32x32x16_bf16(kc[d0], qr[d0], p1, 0, 0, 0);
;     }
;     ...
;     if (TYPE == 2 && rel < 5) {
;         const LAS float* rb = (const LAS float*)(lds + RELOFF) + (qrel + 64 * rel + 256 - 4 * hi - 59);
; #pragma unroll
;         for (int r = 0; r < 16; ++r) { p0[r] += rb[59 - ((r & 3) + 8 * (r >> 2))]; p1[r] += rb[27 - ((r & 3) + 8 * (r >> 2))]; }
;     }
.LBB0_634:
	s_waitcnt lgkmcnt(14)
	s_nop 0
	s_setprio 2
	v_mfma_f32_32x32x16_bf16 v[80:95], v[200:203], v[132:135], v[64:79]
	s_cmp_gt_i32 s3, 4
	v_mfma_f32_32x32x16_bf16 v[64:79], v[204:207], v[132:135], v[64:79]
	v_mfma_f32_32x32x16_bf16 v[80:95], v[188:191], v[128:131], v[80:95]
	v_mfma_f32_32x32x16_bf16 v[64:79], v[192:195], v[128:131], v[64:79]
	v_mfma_f32_32x32x16_bf16 v[80:95], v[184:187], v[124:127], v[80:95]
	v_mfma_f32_32x32x16_bf16 v[64:79], v[196:199], v[124:127], v[64:79]
	v_mfma_f32_32x32x16_bf16 v[80:95], v[180:183], v[120:123], v[80:95]
	v_mfma_f32_32x32x16_bf16 v[64:79], v[176:179], v[120:123], v[64:79]
	s_setprio 0
	s_cbranch_scc1 .LBB0_636
	v_lshl_add_u32 v0, s3, 8, v231
	v_add_u32_e32 v176, 0xcdfc, v0
	ds_read2_b32 v[176:177], v176 offset1:1
	v_add_u32_e32 v178, 0xcd14, v0
	s_waitcnt lgkmcnt(0)
	s_nop 4
	v_pk_add_f32 v[80:81], v[80:81], v[176:177] op_sel:[0,1] op_sel_hi:[1,0]
	v_add_u32_e32 v176, 0xcd7c, v0
	ds_read2_b32 v[176:177], v176 offset1:1
	s_waitcnt lgkmcnt(0)
	v_pk_add_f32 v[64:65], v[64:65], v[176:177] op_sel:[0,1] op_sel_hi:[1,0]
	v_add_u32_e32 v176, 0xcdf4, v0
	ds_read2_b32 v[176:177], v176 offset1:1
	s_waitcnt lgkmcnt(0)
	v_pk_add_f32 v[82:83], v[82:83], v[176:177] op_sel:[0,1] op_sel_hi:[1,0]
	v_add_u32_e32 v176, 0xcd74, v0
	ds_read2_b32 v[176:177], v176 offset1:1
	s_waitcnt lgkmcnt(0)
	v_pk_add_f32 v[66:67], v[66:67], v[176:177] op_sel:[0,1] op_sel_hi:[1,0]
	v_add_u32_e32 v176, 0xcddc, v0
	ds_read2_b32 v[176:177], v176 offset1:1
	s_waitcnt lgkmcnt(0)
	v_pk_add_f32 v[84:85], v[84:85], v[176:177] op_sel:[0,1] op_sel_hi:[1,0]
	v_add_u32_e32 v176, 0xcd5c, v0
	ds_read2_b32 v[176:177], v176 offset1:1
	s_waitcnt lgkmcnt(0)
	v_pk_add_f32 v[68:69], v[68:69], v[176:177] op_sel:[0,1] op_sel_hi:[1,0]
	v_add_u32_e32 v176, 0xcdd4, v0
	ds_read2_b32 v[176:177], v176 offset1:1
	s_waitcnt lgkmcnt(0)
	v_pk_add_f32 v[86:87], v[86:87], v[176:177] op_sel:[0,1] op_sel_hi:[1,0]
	v_add_u32_e32 v176, 0xcd54, v0
	ds_read2_b32 v[176:177], v176 offset1:1
	s_waitcnt lgkmcnt(0)
	v_pk_add_f32 v[70:71], v[70:71], v[176:177] op_sel:[0,1] op_sel_hi:[1,0]
	v_add_u32_e32 v176, 0xcdbc, v0
	ds_read2_b32 v[176:177], v176 offset1:1
	s_waitcnt lgkmcnt(0)
	v_pk_add_f32 v[88:89], v[88:89], v[176:177] op_sel:[0,1] op_sel_hi:[1,0]
	v_add_u32_e32 v176, 0xcd3c, v0
	ds_read2_b32 v[176:177], v176 offset1:1
	s_waitcnt lgkmcnt(0)
	v_pk_add_f32 v[72:73], v[72:73], v[176:177] op_sel:[0,1] op_sel_hi:[1,0]
	v_add_u32_e32 v176, 0xcdb4, v0
	ds_read2_b32 v[176:177], v176 offset1:1
	s_waitcnt lgkmcnt(0)
	v_pk_add_f32 v[90:91], v[90:91], v[176:177] op_sel:[0,1] op_sel_hi:[1,0]
	v_add_u32_e32 v176, 0xcd34, v0
	ds_read2_b32 v[176:177], v176 offset1:1
	s_waitcnt lgkmcnt(0)
	v_pk_add_f32 v[74:75], v[74:75], v[176:177] op_sel:[0,1] op_sel_hi:[1,0]
	v_add_u32_e32 v176, 0xcd9c, v0
	ds_read2_b32 v[176:177], v176 offset1:1
	s_waitcnt lgkmcnt(0)
	v_pk_add_f32 v[92:93], v[92:93], v[176:177] op_sel:[0,1] op_sel_hi:[1,0]
	v_add_u32_e32 v176, 0xcd1c, v0
	ds_read2_b32 v[176:177], v176 offset1:1
	v_add_u32_e32 v0, 0xcd94, v0
	s_waitcnt lgkmcnt(0)
	v_pk_add_f32 v[76:77], v[76:77], v[176:177] op_sel:[0,1] op_sel_hi:[1,0]
	ds_read2_b32 v[176:177], v0 offset1:1
	s_waitcnt lgkmcnt(0)
	v_pk_add_f32 v[94:95], v[94:95], v[176:177] op_sel:[0,1] op_sel_hi:[1,0]
	ds_read2_b32 v[176:177], v178 offset1:1
	s_waitcnt lgkmcnt(0)
	v_pk_add_f32 v[78:79], v[78:79], v[176:177] op_sel:[0,1] op_sel_hi:[1,0]

; __device__ __forceinline__ unsigned pk2(float lo, float hi) { f32x2 v = {lo, hi}; bf16x2_t b = __builtin_convertvector(v, bf16x2_t); return __builtin_bit_cast(unsigned, b); }
; template <int TYPE, int ND0, int KSTR> __device__ __forceinline__ void tile(LAS unsigned char* lds, int buf, int t, int w_lo, int w_hi, int n, int qrel, int lane, int r32, int hi,
;         const bf16x8 (&qr)[ND0], float& m_run, float& l_run, f32x16& o0, f32x16& o1, f32x16& negm) {
;     ...
; #pragma unroll
;     for (int ks = 0; ks < 4; ++ks) {
;         u32x4 pw;
;         if (ks < 2) { pw.x = pk2(p0[8 * ks], p0[8 * ks + 1]); pw.y = pk2(p0[8 * ks + 2], p0[8 * ks + 3]); pw.z = pk2(p0[8 * ks + 4], p0[8 * ks + 5]); pw.w = pk2(p0[8 * ks + 6], p0[8 * ks + 7]); }
;         else { const int k2 = ks - 2; pw.x = pk2(p1[8 * k2], p1[8 * k2 + 1]); pw.y = pk2(p1[8 * k2 + 2], p1[8 * k2 + 3]); pw.z = pk2(p1[8 * k2 + 4], p1[8 * k2 + 5]); pw.w = pk2(p1[8 * k2 + 6], p1[8 * k2 + 7]); }
;         const bf16x8 pb = __builtin_bit_cast(bf16x8, pw);
;         const bf16x8 va0 = __builtin_shufflevector(vf[ks][0], vf[ks][1], 0, 1, 2, 3, 4, 5, 6, 7), va1 = __builtin_shufflevector(vf[ks][2], vf[ks][3], 0, 1, 2, 3, 4, 5, 6, 7);
;         o0 = __builtin_amdgcn_mfma_f32_32x32x16_bf16(va0, pb, o0, 0, 0, 0);
;         o1 = __builtin_amdgcn_mfma_f32_32x32x16_bf16(va1, pb, o1, 0, 0, 0);
;     }
.LBB0_640:
	v_cvt_pk_bf16_f32 v208, v176, v0
	v_cvt_pk_bf16_f32 v209, v82, v194
	v_cvt_pk_bf16_f32 v210, v84, v196
	v_cvt_pk_bf16_f32 v211, v178, v200
	v_cvt_pk_bf16_f32 v82, v86, v198
	v_cvt_pk_bf16_f32 v83, v88, v202
	s_setprio 2
	v_mfma_f32_32x32x16_bf16 v[32:47], v[168:171], v[208:211], v[32:47]
	v_cvt_pk_bf16_f32 v84, v90, v204
	v_cvt_pk_bf16_f32 v85, v92, v206
	v_cvt_pk_bf16_f32 v64, v64, v180
	v_cvt_pk_bf16_f32 v65, v66, v182
	v_cvt_pk_bf16_f32 v66, v68, v184
	v_cvt_pk_bf16_f32 v67, v80, v188
	v_add_f32_e32 v222, v222, v94
	s_waitcnt lgkmcnt(12)
	v_mfma_f32_32x32x16_bf16 v[16:31], v[172:175], v[208:211], v[16:31]
	s_waitcnt lgkmcnt(10)
	v_mfma_f32_32x32x16_bf16 v[32:47], v[160:163], v[82:85], v[32:47]
	s_waitcnt lgkmcnt(8)
	v_mfma_f32_32x32x16_bf16 v[16:31], v[164:167], v[82:85], v[16:31]
	s_waitcnt lgkmcnt(6)
	v_mfma_f32_32x32x16_bf16 v[32:47], v[152:155], v[64:67], v[32:47]
	s_waitcnt lgkmcnt(4)
	v_mfma_f32_32x32x16_bf16 v[16:31], v[156:159], v[64:67], v[16:31]
	v_cvt_pk_bf16_f32 v64, v70, v186
	v_cvt_pk_bf16_f32 v65, v72, v190
	v_cvt_pk_bf16_f32 v66, v74, v192
	v_cvt_pk_bf16_f32 v67, v76, v78
	s_waitcnt lgkmcnt(2)
	s_nop 0
	v_mfma_f32_32x32x16_bf16 v[32:47], v[148:151], v[64:67], v[32:47]
	s_waitcnt lgkmcnt(0)
	v_mfma_f32_32x32x16_bf16 v[16:31], v[144:147], v[64:67], v[16:31]
	s_setprio 0

; #define LAS __attribute__((address_space(3)))
; __device__ __forceinline__ int crow(int r, int hi) { return (r & 3) + 8 * (r >> 2) + 4 * hi; }
; template <int TYPE, int ND0, int KSTR> __device__ __forceinline__ void tile(LAS unsigned char* lds, int buf, int t, int w_lo, int w_hi, int n, int qrel, int lane, int r32, int hi,
;         const bf16x8 (&qr)[ND0], float& m_run, float& l_run, f32x16& o0, f32x16& o1, f32x16& negm) {
;     ...
;     for (int d0 = 0; d0 < ND0; ++d0) {
;         p0 = __builtin_amdgcn_mfma_f32_32x32x16_bf16(ka[d0], qr[d0], p0, 0, 0, 0);
;         p1 = __builtin_amdgcn_mfma_f32_32x32x16_bf16(kc[d0], qr[d0], p1, 0, 0, 0);
;     }
;     if (TYPE == 0) {
; #pragma unroll
;         for (int g = 0; g < 4; ++g)
; #pragma unroll
;             for (int j = 0; j < 4; ++j) { p0[4 * g + j] += kbv[g][j]; p1[4 * g + j] += kbv[4 + g][j]; }
;         if (t == w_hi) {
; #pragma unroll
;             for (int r = 0; r < 16; ++r) { const int kr_ = crow(r, hi); if (kr_ > qrel) p0[r] = -1e30f; if (kr_ + 32 > qrel) p1[r] = -1e30f; }
;         }
;     }
;     if (TYPE == 2 && rel < 5) {
;         const LAS float* rb = (const LAS float*)(lds + RELOFF) + (qrel + 64 * rel + 256 - 4 * hi - 59);
; #pragma unroll
;         for (int r = 0; r < 16; ++r) { p0[r] += rb[59 - ((r & 3) + 8 * (r >> 2))]; p1[r] += rb[27 - ((r & 3) + 8 * (r >> 2))]; }
;     }
.LBB0_644:
	s_waitcnt lgkmcnt(14)
	s_nop 0
	s_setprio 2
	v_mfma_f32_32x32x16_bf16 v[64:79], v[188:191], v[132:135], v[48:63]
	s_cmp_gt_i32 s1, 4
	v_mfma_f32_32x32x16_bf16 v[48:63], v[192:195], v[132:135], v[48:63]
	v_mfma_f32_32x32x16_bf16 v[64:79], v[176:179], v[128:131], v[64:79]
	v_mfma_f32_32x32x16_bf16 v[48:63], v[180:183], v[128:131], v[48:63]
	v_mfma_f32_32x32x16_bf16 v[64:79], v[172:175], v[124:127], v[64:79]
	v_mfma_f32_32x32x16_bf16 v[48:63], v[184:187], v[124:127], v[48:63]
	v_mfma_f32_32x32x16_bf16 v[64:79], v[168:171], v[120:123], v[64:79]
	v_mfma_f32_32x32x16_bf16 v[48:63], v[164:167], v[120:123], v[48:63]
	s_setprio 0
	s_cbranch_scc1 .LBB0_646
	v_lshl_add_u32 v0, s1, 8, v231
	v_add_u32_e32 v14, 0xcdfc, v0
	ds_read2_b32 v[14:15], v14 offset1:1
	v_add_u32_e32 v120, 0xcd14, v0
	s_waitcnt lgkmcnt(0)
	s_nop 4
	v_pk_add_f32 v[64:65], v[64:65], v[14:15] op_sel:[0,1] op_sel_hi:[1,0]
	v_add_u32_e32 v14, 0xcd7c, v0
	ds_read2_b32 v[14:15], v14 offset1:1
	s_waitcnt lgkmcnt(0)
	v_pk_add_f32 v[48:49], v[48:49], v[14:15] op_sel:[0,1] op_sel_hi:[1,0]
	v_add_u32_e32 v14, 0xcdf4, v0
	ds_read2_b32 v[14:15], v14 offset1:1
	s_waitcnt lgkmcnt(0)
	v_pk_add_f32 v[66:67], v[66:67], v[14:15] op_sel:[0,1] op_sel_hi:[1,0]
	v_add_u32_e32 v14, 0xcd74, v0
	ds_read2_b32 v[14:15], v14 offset1:1
	s_waitcnt lgkmcnt(0)
	v_pk_add_f32 v[50:51], v[50:51], v[14:15] op_sel:[0,1] op_sel_hi:[1,0]
	v_add_u32_e32 v14, 0xcddc, v0
	ds_read2_b32 v[14:15], v14 offset1:1
	s_waitcnt lgkmcnt(0)
	v_pk_add_f32 v[68:69], v[68:69], v[14:15] op_sel:[0,1] op_sel_hi:[1,0]
	v_add_u32_e32 v14, 0xcd5c, v0
	ds_read2_b32 v[14:15], v14 offset1:1
	s_waitcnt lgkmcnt(0)
	v_pk_add_f32 v[52:53], v[52:53], v[14:15] op_sel:[0,1] op_sel_hi:[1,0]
	v_add_u32_e32 v14, 0xcdd4, v0
	ds_read2_b32 v[14:15], v14 offset1:1
	s_waitcnt lgkmcnt(0)
	v_pk_add_f32 v[70:71], v[70:71], v[14:15] op_sel:[0,1] op_sel_hi:[1,0]
	v_add_u32_e32 v14, 0xcd54, v0
	ds_read2_b32 v[14:15], v14 offset1:1
	s_waitcnt lgkmcnt(0)
	v_pk_add_f32 v[54:55], v[54:55], v[14:15] op_sel:[0,1] op_sel_hi:[1,0]
	v_add_u32_e32 v14, 0xcdbc, v0
	ds_read2_b32 v[14:15], v14 offset1:1
	s_waitcnt lgkmcnt(0)
	v_pk_add_f32 v[72:73], v[72:73], v[14:15] op_sel:[0,1] op_sel_hi:[1,0]
	v_add_u32_e32 v14, 0xcd3c, v0
	ds_read2_b32 v[14:15], v14 offset1:1
	s_waitcnt lgkmcnt(0)
	v_pk_add_f32 v[56:57], v[56:57], v[14:15] op_sel:[0,1] op_sel_hi:[1,0]
	v_add_u32_e32 v14, 0xcdb4, v0
	ds_read2_b32 v[14:15], v14 offset1:1
	s_waitcnt lgkmcnt(0)
	v_pk_add_f32 v[74:75], v[74:75], v[14:15] op_sel:[0,1] op_sel_hi:[1,0]
	v_add_u32_e32 v14, 0xcd34, v0
	ds_read2_b32 v[14:15], v14 offset1:1
	s_waitcnt lgkmcnt(0)
	v_pk_add_f32 v[58:59], v[58:59], v[14:15] op_sel:[0,1] op_sel_hi:[1,0]
	v_add_u32_e32 v14, 0xcd9c, v0
	ds_read2_b32 v[14:15], v14 offset1:1
	s_waitcnt lgkmcnt(0)
	v_pk_add_f32 v[76:77], v[76:77], v[14:15] op_sel:[0,1] op_sel_hi:[1,0]
	v_add_u32_e32 v14, 0xcd1c, v0
	ds_read2_b32 v[14:15], v14 offset1:1
	v_add_u32_e32 v0, 0xcd94, v0
	s_waitcnt lgkmcnt(0)
	v_pk_add_f32 v[60:61], v[60:61], v[14:15] op_sel:[0,1] op_sel_hi:[1,0]
	ds_read2_b32 v[14:15], v0 offset1:1
	s_waitcnt lgkmcnt(0)
	v_pk_add_f32 v[78:79], v[78:79], v[14:15] op_sel:[0,1] op_sel_hi:[1,0]
	ds_read2_b32 v[14:15], v120 offset1:1
	s_waitcnt lgkmcnt(0)
	v_pk_add_f32 v[62:63], v[62:63], v[14:15] op_sel:[0,1] op_sel_hi:[1,0]

; __device__ __forceinline__ unsigned pk2(float lo, float hi) { f32x2 v = {lo, hi}; bf16x2_t b = __builtin_convertvector(v, bf16x2_t); return __builtin_bit_cast(unsigned, b); }
; template <int TYPE, int ND0, int KSTR> __device__ __forceinline__ void tile(LAS unsigned char* lds, int buf, int t, int w_lo, int w_hi, int n, int qrel, int lane, int r32, int hi,
;         const bf16x8 (&qr)[ND0], float& m_run, float& l_run, f32x16& o0, f32x16& o1, f32x16& negm) {
;     ...
; #pragma unroll
;     for (int ks = 0; ks < 4; ++ks) {
;         u32x4 pw;
;         if (ks < 2) { pw.x = pk2(p0[8 * ks], p0[8 * ks + 1]); pw.y = pk2(p0[8 * ks + 2], p0[8 * ks + 3]); pw.z = pk2(p0[8 * ks + 4], p0[8 * ks + 5]); pw.w = pk2(p0[8 * ks + 6], p0[8 * ks + 7]); }
;         else { const int k2 = ks - 2; pw.x = pk2(p1[8 * k2], p1[8 * k2 + 1]); pw.y = pk2(p1[8 * k2 + 2], p1[8 * k2 + 3]); pw.z = pk2(p1[8 * k2 + 4], p1[8 * k2 + 5]); pw.w = pk2(p1[8 * k2 + 6], p1[8 * k2 + 7]); }
;         const bf16x8 pb = __builtin_bit_cast(bf16x8, pw);
;         const bf16x8 va0 = __builtin_shufflevector(vf[ks][0], vf[ks][1], 0, 1, 2, 3, 4, 5, 6, 7), va1 = __builtin_shufflevector(vf[ks][2], vf[ks][3], 0, 1, 2, 3, 4, 5, 6, 7);
;         o0 = __builtin_amdgcn_mfma_f32_32x32x16_bf16(va0, pb, o0, 0, 0, 0);
;         o1 = __builtin_amdgcn_mfma_f32_32x32x16_bf16(va1, pb, o1, 0, 0, 0);
;     }
.LBB0_650:
	v_cvt_pk_bf16_f32 v64, v64, v0
	v_cvt_pk_bf16_f32 v65, v66, v164
	v_cvt_pk_bf16_f32 v66, v68, v166
	v_cvt_pk_bf16_f32 v67, v120, v170
	v_cvt_pk_bf16_f32 v49, v56, v132
	v_cvt_pk_bf16_f32 v51, v60, v62
	s_setprio 2
	v_mfma_f32_32x32x16_bf16 v[32:47], v[156:159], v[64:67], v[32:47]
	v_add_f32_e32 v222, v222, v78
	s_waitcnt lgkmcnt(12)
	v_mfma_f32_32x32x16_bf16 v[16:31], v[160:163], v[64:67], v[16:31]
	v_cvt_pk_bf16_f32 v64, v70, v168
	v_cvt_pk_bf16_f32 v65, v72, v172
	v_cvt_pk_bf16_f32 v66, v74, v174
	v_cvt_pk_bf16_f32 v67, v76, v176
	s_waitcnt lgkmcnt(10)
	s_nop 0
	v_mfma_f32_32x32x16_bf16 v[32:47], v[148:151], v[64:67], v[32:47]
	s_waitcnt lgkmcnt(8)
	v_mfma_f32_32x32x16_bf16 v[16:31], v[152:155], v[64:67], v[16:31]
	v_cvt_pk_bf16_f32 v64, v14, v122
	v_cvt_pk_bf16_f32 v65, v48, v124
	v_cvt_pk_bf16_f32 v66, v50, v126
	v_cvt_pk_bf16_f32 v67, v54, v130
	v_cvt_pk_bf16_f32 v48, v52, v128
	v_cvt_pk_bf16_f32 v50, v58, v134
	s_waitcnt lgkmcnt(6)
	v_mfma_f32_32x32x16_bf16 v[32:47], v[140:143], v[64:67], v[32:47]
	s_waitcnt lgkmcnt(4)
	v_mfma_f32_32x32x16_bf16 v[16:31], v[144:147], v[64:67], v[16:31]
	s_waitcnt lgkmcnt(2)
	v_mfma_f32_32x32x16_bf16 v[32:47], v[136:139], v[48:51], v[32:47]
	s_waitcnt lgkmcnt(0)
	v_mfma_f32_32x32x16_bf16 v[16:31], v[92:95], v[48:51], v[16:31]
	s_setprio 0

; #define LAS __attribute__((address_space(3)))
; __device__ __forceinline__ int crow(int r, int hi) { return (r & 3) + 8 * (r >> 2) + 4 * hi; }
; template <int TYPE, int ND0, int KSTR> __device__ __forceinline__ void tile(LAS unsigned char* lds, int buf, int t, int w_lo, int w_hi, int n, int qrel, int lane, int r32, int hi,
;         const bf16x8 (&qr)[ND0], float& m_run, float& l_run, f32x16& o0, f32x16& o1, f32x16& negm) {
;     const LAS unsigned char* kb = lds + KOFF + buf * KBUF + r32 * KSTR + hi * 16;
;     bf16x8 ka[ND0], kc[ND0];
; #pragma unroll
;     for (int d0 = 0; d0 < ND0; ++d0) { ka[d0] = *(const LAS bf16x8*)(kb + d0 * 32); kc[d0] = *(const LAS bf16x8*)(kb + 32 * KSTR + d0 * 32); }
;     const LAS unsigned char* vb = lds + VOFF + buf * VBUF + (4 * hi + ((lane & 15) >> 2)) * VSTR + (16 * ((lane >> 4) & 1) + 4 * (lane & 3)) * 2;
;     s16x4 vf[4][4];
; #pragma unroll
;     for (int ks = 0; ks < 4; ++ks) { vf[ks][0] = vtr(vb + (16 * ks) * VSTR); vf[ks][1] = vtr(vb + (16 * ks + 8) * VSTR); vf[ks][2] = vtr(vb + (16 * ks) * VSTR + 64); vf[ks][3] = vtr(vb + (16 * ks + 8) * VSTR + 64); }
;     f32x4 kbv[8];
;     if (TYPE == 0) { const LAS f32x4* kbi = (const LAS f32x4*)(lds + KBOFF + buf * 256);
; #pragma unroll
;         for (int g = 0; g < 4; ++g) { kbv[g] = kbi[2 * g + hi]; kbv[4 + g] = kbi[8 + 2 * g + hi]; } }
;     asm volatile("" ::: "memory");
;     const int rel = n - t;
;     f32x16 cin = negm;
;     if (TYPE == 2 && rel >= 5) { const float c = ((const LAS float*)(lds + RELOFF))[512];
; #pragma unroll
;         for (int r = 0; r < 16; ++r) cin[r] += c; }
;     f32x16 p0 = cin, p1 = cin;
; #pragma unroll
;     for (int d0 = 0; d0 < ND0; ++d0) {
;         p0 = __builtin_amdgcn_mfma_f32_32x32x16_bf16(ka[d0], qr[d0], p0, 0, 0, 0);
;         p1 = __builtin_amdgcn_mfma_f32_32x32x16_bf16(kc[d0], qr[d0], p1, 0, 0, 0);
;     }
;     if (TYPE == 0) {
; #pragma unroll
;         for (int g = 0; g < 4; ++g)
; #pragma unroll
;             for (int j = 0; j < 4; ++j) { p0[4 * g + j] += kbv[g][j]; p1[4 * g + j] += kbv[4 + g][j]; }
;         if (t == w_hi) {
; #pragma unroll
;             for (int r = 0; r < 16; ++r) { const int kr_ = crow(r, hi); if (kr_ > qrel) p0[r] = -1e30f; if (kr_ + 32 > qrel) p1[r] = -1e30f; }
;         }
.LBB0_657:
	s_add_i32 s44, s28, 0x80
	s_lshl_b64 s[2:3], s[44:45], 10
	v_lshl_add_u64 v[2:3], v[184:185], 0, s[2:3]
	v_lshl_add_u64 v[6:7], v[182:183], 0, s[2:3]
	v_lshl_add_u64 v[10:11], s[44:45], 2, v[186:187]
	global_load_dwordx4 v[2:5], v[2:3], off
	s_nop 0
	global_load_dwordx4 v[6:9], v[6:7], off
	s_add_i32 s2, s30, s29
	global_load_dword v247, v[10:11], off
	s_add_i32 s3, s29, 2
	s_cmp_gt_i32 s3, s41
	s_cbranch_scc1 .LBB0_665
	v_add_u32_e32 v0, v173, v172
	ds_read_b128 v[10:13], v0
	ds_read_b128 v[144:147], v0 offset:32
	s_cmp_lg_u32 s2, 26
	s_waitcnt lgkmcnt(1)
	s_setprio 2
	v_mfma_f32_32x32x16_bf16 v[80:95], v[10:13], v[132:135], v[48:63]
	ds_read_b128 v[10:13], v0 offset:4608
	ds_read_b128 v[148:151], v0 offset:4640
	s_waitcnt lgkmcnt(1)
	v_mfma_f32_32x32x16_bf16 v[64:79], v[10:13], v[132:135], v[48:63]
	ds_read_b128 v[10:13], v0 offset:64
	ds_read_b128 v[188:191], v0 offset:96
	ds_read_b128 v[192:195], v0 offset:4672
	ds_read_b128 v[196:199], v0 offset:4704
	v_add_u32_e32 v0, v239, v243
	ds_read_b64_tr_b16 v[168:169], v0 offset:26624
	ds_read_b64_tr_b16 v[170:171], v0 offset:28160
	ds_read_b64_tr_b16 v[166:167], v0 offset:28224
	ds_read_b64_tr_b16 v[164:165], v0 offset:26688
	ds_read_b64_tr_b16 v[156:157], v0 offset:29696
	ds_read_b64_tr_b16 v[158:159], v0 offset:31232
	ds_read_b64_tr_b16 v[162:163], v0 offset:31296
	ds_read_b64_tr_b16 v[160:161], v0 offset:29760
	v_mfma_f32_32x32x16_bf16 v[80:95], v[144:147], v[128:131], v[80:95]
	s_waitcnt lgkmcnt(12)
	v_mfma_f32_32x32x16_bf16 v[64:79], v[148:151], v[128:131], v[64:79]
	s_waitcnt vmcnt(4) lgkmcnt(11)
	v_mfma_f32_32x32x16_bf16 v[80:95], v[10:13], v[124:127], v[80:95]
	ds_read_b64_tr_b16 v[152:153], v0 offset:32768
	ds_read_b64_tr_b16 v[154:155], v0 offset:34304
	ds_read_b64_tr_b16 v[150:151], v0 offset:34368
	ds_read_b64_tr_b16 v[148:149], v0 offset:32832
	ds_read_b64_tr_b16 v[144:145], v0 offset:35840
	ds_read_b64_tr_b16 v[146:147], v0 offset:37376
	ds_read_b64_tr_b16 v[12:13], v0 offset:37440
	ds_read_b64_tr_b16 v[10:11], v0 offset:35904
	ds_read_b128 v[200:203], v231 offset:51200
	ds_read_b128 v[204:207], v231 offset:51232
	s_waitcnt lgkmcnt(14)
	v_mfma_f32_32x32x16_bf16 v[64:79], v[192:195], v[124:127], v[64:79]
	s_waitcnt vmcnt(3)
	v_mfma_f32_32x32x16_bf16 v[80:95], v[188:191], v[120:123], v[80:95]
	ds_read_b128 v[188:191], v231 offset:51264
	ds_read_b128 v[208:211], v231 offset:51296
	ds_read_b128 v[212:215], v231 offset:51328
	ds_read_b128 v[220:223], v231 offset:51360
	ds_read_b128 v[224:227], v231 offset:51392
	ds_read_b128 v[232:235], v231 offset:51424
	s_waitcnt lgkmcnt(4)
	s_nop 4
	v_pk_add_f32 v[94:95], v[210:211], v[94:95]
	v_mfma_f32_32x32x16_bf16 v[64:79], v[196:199], v[120:123], v[64:79]
	s_setprio 0
	v_add_f32_e64 v92, v208, v92
	v_add_f32_e64 v93, v209, v93
	v_add_f32_e64 v90, v190, v90
	v_add_f32_e64 v91, v191, v91
	v_add_f32_e64 v88, v188, v88
	v_add_f32_e64 v89, v189, v89
	v_pk_add_f32 v[86:87], v[206:207], v[86:87]
	v_pk_add_f32 v[84:85], v[204:205], v[84:85]
	v_pk_add_f32 v[82:83], v[202:203], v[82:83]
	v_pk_add_f32 v[14:15], v[200:201], v[80:81]
	s_waitcnt lgkmcnt(0)
	s_nop 0
	v_pk_add_f32 v[80:81], v[234:235], v[78:79]
	v_pk_add_f32 v[76:77], v[232:233], v[76:77]
	v_pk_add_f32 v[194:195], v[226:227], v[74:75]
	v_pk_add_f32 v[72:73], v[224:225], v[72:73]
	v_pk_add_f32 v[70:71], v[222:223], v[70:71]
	v_pk_add_f32 v[68:69], v[220:221], v[68:69]
	v_pk_add_f32 v[66:67], v[214:215], v[66:67]
	v_pk_add_f32 v[64:65], v[212:213], v[64:65]
	s_cbranch_scc1 .LBB0_660
	v_cndmask_b32_e64 v0, v14, v237, s[42:43]
	v_cndmask_b32_e64 v64, v64, v237, s[46:47]
	v_cndmask_b32_e64 v15, v237, v15, s[38:39]
	v_cndmask_b32_e64 v14, v0, v14, s[38:39]
	v_cndmask_b32_e64 v65, v65, v237, s[48:49]
	v_cndmask_b32_e64 v82, v82, v237, s[50:51]
	v_cndmask_b32_e64 v66, v66, v237, s[52:53]
	v_cndmask_b32_e64 v83, v83, v237, s[54:55]
	v_cndmask_b32_e64 v67, v67, v237, s[56:57]
	v_cndmask_b32_e64 v84, v84, v237, s[58:59]
	v_cndmask_b32_e64 v68, v68, v237, s[60:61]
	v_cndmask_b32_e64 v85, v85, v237, s[62:63]
	v_cndmask_b32_e64 v69, v69, v237, s[64:65]
	v_cndmask_b32_e64 v86, v86, v237, s[66:67]
	v_cndmask_b32_e64 v70, v70, v237, s[68:69]
	v_cndmask_b32_e64 v87, v87, v237, s[70:71]
	v_cndmask_b32_e64 v71, v71, v237, s[74:75]
	v_cndmask_b32_e64 v88, v88, v237, s[76:77]
	v_cndmask_b32_e64 v72, v72, v237, s[78:79]
	v_cndmask_b32_e64 v89, v89, v237, s[80:81]
	v_cndmask_b32_e64 v73, v73, v237, s[82:83]
	v_cndmask_b32_e64 v90, v90, v237, s[84:85]
	v_cndmask_b32_e64 v194, v194, v237, s[86:87]
	v_cndmask_b32_e64 v91, v91, v237, s[88:89]
	v_cndmask_b32_e64 v195, v195, v237, s[90:91]
	v_cndmask_b32_e64 v92, v92, v237, s[92:93]
	v_cndmask_b32_e64 v76, v76, v237, s[94:95]
	v_cndmask_b32_e64 v93, v93, v237, s[96:97]
	v_cndmask_b32_e64 v77, v77, v237, s[0:1]
	v_cndmask_b32_e64 v94, v94, v237, s[4:5]
	v_cndmask_b32_e64 v80, v80, v237, s[6:7]
	v_cndmask_b32_e64 v95, v95, v237, s[8:9]
	v_cndmask_b32_e64 v81, v81, v237, s[72:73]

; __device__ __forceinline__ unsigned pk2(float lo, float hi) { f32x2 v = {lo, hi}; bf16x2_t b = __builtin_convertvector(v, bf16x2_t); return __builtin_bit_cast(unsigned, b); }
; template <int TYPE, int ND0, int KSTR> __device__ __forceinline__ void tile(LAS unsigned char* lds, int buf, int t, int w_lo, int w_hi, int n, int qrel, int lane, int r32, int hi,
;         const bf16x8 (&qr)[ND0], float& m_run, float& l_run, f32x16& o0, f32x16& o1, f32x16& negm) {
;     ...
; #pragma unroll
;     for (int ks = 0; ks < 4; ++ks) {
;         u32x4 pw;
;         if (ks < 2) { pw.x = pk2(p0[8 * ks], p0[8 * ks + 1]); pw.y = pk2(p0[8 * ks + 2], p0[8 * ks + 3]); pw.z = pk2(p0[8 * ks + 4], p0[8 * ks + 5]); pw.w = pk2(p0[8 * ks + 6], p0[8 * ks + 7]); }
;         else { const int k2 = ks - 2; pw.x = pk2(p1[8 * k2], p1[8 * k2 + 1]); pw.y = pk2(p1[8 * k2 + 2], p1[8 * k2 + 3]); pw.z = pk2(p1[8 * k2 + 4], p1[8 * k2 + 5]); pw.w = pk2(p1[8 * k2 + 6], p1[8 * k2 + 7]); }
;         const bf16x8 pb = __builtin_bit_cast(bf16x8, pw);
;         const bf16x8 va0 = __builtin_shufflevector(vf[ks][0], vf[ks][1], 0, 1, 2, 3, 4, 5, 6, 7), va1 = __builtin_shufflevector(vf[ks][2], vf[ks][3], 0, 1, 2, 3, 4, 5, 6, 7);
;         o0 = __builtin_amdgcn_mfma_f32_32x32x16_bf16(va0, pb, o0, 0, 0, 0);
;         o1 = __builtin_amdgcn_mfma_f32_32x32x16_bf16(va1, pb, o1, 0, 0, 0);
;     }
.LBB0_664:
	v_cvt_pk_bf16_f32 v208, v74, v0
	v_cvt_pk_bf16_f32 v209, v78, v202
	v_cvt_pk_bf16_f32 v210, v82, v204
	v_cvt_pk_bf16_f32 v211, v86, v220
	v_cvt_pk_bf16_f32 v82, v84, v206
	v_cvt_pk_bf16_f32 v83, v88, v222
	s_setprio 2
	v_mfma_f32_32x32x16_bf16 v[32:47], v[168:171], v[208:211], v[32:47]
	v_cvt_pk_bf16_f32 v84, v90, v224
	v_cvt_pk_bf16_f32 v85, v92, v226
	v_cvt_pk_bf16_f32 v65, v72, v194
	v_cvt_pk_bf16_f32 v67, v80, v94
	v_add_f32_e32 v178, v178, v228
	v_mfma_f32_32x32x16_bf16 v[16:31], v[164:167], v[208:211], v[16:31]
	v_mfma_f32_32x32x16_bf16 v[32:47], v[156:159], v[82:85], v[32:47]
	v_mfma_f32_32x32x16_bf16 v[16:31], v[160:163], v[82:85], v[16:31]
	v_cvt_pk_bf16_f32 v82, v14, v188
	v_cvt_pk_bf16_f32 v83, v64, v190
	v_cvt_pk_bf16_f32 v84, v66, v192
	v_cvt_pk_bf16_f32 v85, v70, v198
	v_cvt_pk_bf16_f32 v64, v68, v196
	v_cvt_pk_bf16_f32 v66, v76, v200
	v_mfma_f32_32x32x16_bf16 v[32:47], v[152:155], v[82:85], v[32:47]
	v_mfma_f32_32x32x16_bf16 v[16:31], v[148:151], v[82:85], v[16:31]
	v_mfma_f32_32x32x16_bf16 v[32:47], v[144:147], v[64:67], v[32:47]
	v_mfma_f32_32x32x16_bf16 v[16:31], v[10:13], v[64:67], v[16:31]
	s_setprio 0

; #define LAS __attribute__((address_space(3)))
; __device__ __forceinline__ int crow(int r, int hi) { return (r & 3) + 8 * (r >> 2) + 4 * hi; }
; template <int TYPE, int ND0, int KSTR> __device__ __forceinline__ void tile(LAS unsigned char* lds, int buf, int t, int w_lo, int w_hi, int n, int qrel, int lane, int r32, int hi,
;         const bf16x8 (&qr)[ND0], float& m_run, float& l_run, f32x16& o0, f32x16& o1, f32x16& negm) {
;     const LAS unsigned char* kb = lds + KOFF + buf * KBUF + r32 * KSTR + hi * 16;
;     bf16x8 ka[ND0], kc[ND0];
; #pragma unroll
;     for (int d0 = 0; d0 < ND0; ++d0) { ka[d0] = *(const LAS bf16x8*)(kb + d0 * 32); kc[d0] = *(const LAS bf16x8*)(kb + 32 * KSTR + d0 * 32); }
;     const LAS unsigned char* vb = lds + VOFF + buf * VBUF + (4 * hi + ((lane & 15) >> 2)) * VSTR + (16 * ((lane >> 4) & 1) + 4 * (lane & 3)) * 2;
;     s16x4 vf[4][4];
; #pragma unroll
;     for (int ks = 0; ks < 4; ++ks) { vf[ks][0] = vtr(vb + (16 * ks) * VSTR); vf[ks][1] = vtr(vb + (16 * ks + 8) * VSTR); vf[ks][2] = vtr(vb + (16 * ks) * VSTR + 64); vf[ks][3] = vtr(vb + (16 * ks + 8) * VSTR + 64); }
;     f32x4 kbv[8];
;     if (TYPE == 0) { const LAS f32x4* kbi = (const LAS f32x4*)(lds + KBOFF + buf * 256);
; #pragma unroll
;         for (int g = 0; g < 4; ++g) { kbv[g] = kbi[2 * g + hi]; kbv[4 + g] = kbi[8 + 2 * g + hi]; } }
;     asm volatile("" ::: "memory");
;     const int rel = n - t;
;     f32x16 cin = negm;
;     if (TYPE == 2 && rel >= 5) { const float c = ((const LAS float*)(lds + RELOFF))[512];
; #pragma unroll
;         for (int r = 0; r < 16; ++r) cin[r] += c; }
;     f32x16 p0 = cin, p1 = cin;
; #pragma unroll
;     for (int d0 = 0; d0 < ND0; ++d0) {
;         p0 = __builtin_amdgcn_mfma_f32_32x32x16_bf16(ka[d0], qr[d0], p0, 0, 0, 0);
;         p1 = __builtin_amdgcn_mfma_f32_32x32x16_bf16(kc[d0], qr[d0], p1, 0, 0, 0);
;     }
;     if (TYPE == 0) {
; #pragma unroll
;         for (int g = 0; g < 4; ++g)
; #pragma unroll
;             for (int j = 0; j < 4; ++j) { p0[4 * g + j] += kbv[g][j]; p1[4 * g + j] += kbv[4 + g][j]; }
;         if (t == w_hi) {
; #pragma unroll
;             for (int r = 0; r < 16; ++r) { const int kr_ = crow(r, hi); if (kr_ > qrel) p0[r] = -1e30f; if (kr_ + 32 > qrel) p1[r] = -1e30f; }
;         }
.LBB0_667:
	s_or_b64 exec, exec, vcc
	s_add_i32 s22, s28, 0xc0
	s_mov_b32 s23, s45
	s_lshl_b64 s[22:23], s[22:23], 10
	v_lshl_add_u64 v[10:11], v[184:185], 0, s[22:23]
	s_mov_b32 s29, s45
	s_waitcnt lgkmcnt(0)
	s_barrier
	v_lshl_add_u64 v[12:13], v[182:183], 0, s[22:23]
	global_load_dwordx4 v[140:143], v[10:11], off
	global_load_dwordx4 v[136:139], v[12:13], off
	v_lshl_add_u64 v[10:11], s[28:29], 2, v[186:187]
	global_load_dword v238, v[10:11], off offset:768
	s_cmp_ge_i32 s3, s41
	s_cbranch_scc1 .LBB0_673
	v_add_u32_e32 v0, v173, v172
	ds_read_b128 v[10:13], v0 offset:13312
	ds_read_b128 v[144:147], v0 offset:13344
	s_cmp_lg_u32 s2, 25
	s_waitcnt lgkmcnt(1)
	s_setprio 2
	v_mfma_f32_32x32x16_bf16 v[80:95], v[10:13], v[132:135], v[48:63]
	ds_read_b128 v[10:13], v0 offset:17920
	ds_read_b128 v[148:151], v0 offset:17952
	s_waitcnt lgkmcnt(1)
	v_mfma_f32_32x32x16_bf16 v[64:79], v[10:13], v[132:135], v[48:63]
	ds_read_b128 v[10:13], v0 offset:13376
	ds_read_b128 v[188:191], v0 offset:13408
	ds_read_b128 v[192:195], v0 offset:17984
	ds_read_b128 v[196:199], v0 offset:18016
	v_add_u32_e32 v0, v239, v243
	ds_read_b64_tr_b16 v[168:169], v0 offset:38912
	ds_read_b64_tr_b16 v[170:171], v0 offset:40448
	ds_read_b64_tr_b16 v[166:167], v0 offset:40512
	ds_read_b64_tr_b16 v[164:165], v0 offset:38976
	ds_read_b64_tr_b16 v[156:157], v0 offset:41984
	ds_read_b64_tr_b16 v[158:159], v0 offset:43520
	ds_read_b64_tr_b16 v[162:163], v0 offset:43584
	ds_read_b64_tr_b16 v[160:161], v0 offset:42048
	v_mfma_f32_32x32x16_bf16 v[80:95], v[144:147], v[128:131], v[80:95]
	s_waitcnt lgkmcnt(12)
	v_mfma_f32_32x32x16_bf16 v[64:79], v[148:151], v[128:131], v[64:79]
	s_waitcnt lgkmcnt(11)
	v_mfma_f32_32x32x16_bf16 v[80:95], v[10:13], v[124:127], v[80:95]
	ds_read_b64_tr_b16 v[152:153], v0 offset:45056
	ds_read_b64_tr_b16 v[154:155], v0 offset:46592
	ds_read_b64_tr_b16 v[150:151], v0 offset:46656
	ds_read_b64_tr_b16 v[148:149], v0 offset:45120
	ds_read_b64_tr_b16 v[144:145], v0 offset:48128
	ds_read_b64_tr_b16 v[146:147], v0 offset:49664
	ds_read_b64_tr_b16 v[12:13], v0 offset:49728
	ds_read_b64_tr_b16 v[10:11], v0 offset:48192
	ds_read_b128 v[204:207], v231 offset:51456
	ds_read_b128 v[208:211], v231 offset:51488
	s_waitcnt lgkmcnt(14)
	v_mfma_f32_32x32x16_bf16 v[64:79], v[192:195], v[124:127], v[64:79]
	s_waitcnt vmcnt(6)
	v_mfma_f32_32x32x16_bf16 v[80:95], v[188:191], v[120:123], v[80:95]
	ds_read_b128 v[188:191], v231 offset:51520
	ds_read_b128 v[200:203], v231 offset:51552
	ds_read_b128 v[212:215], v231 offset:51584
	ds_read_b128 v[220:223], v231 offset:51616
	ds_read_b128 v[224:227], v231 offset:51648
	ds_read_b128 v[232:235], v231 offset:51680
	s_waitcnt lgkmcnt(4)
	s_nop 4
	v_pk_add_f32 v[202:203], v[202:203], v[94:95]
	v_mfma_f32_32x32x16_bf16 v[64:79], v[196:199], v[120:123], v[64:79]
	s_setprio 0
	v_add_f32_e64 v92, v200, v92
	v_add_f32_e64 v93, v201, v93
	v_add_f32_e64 v90, v190, v90
	v_add_f32_e64 v91, v191, v91
	v_add_f32_e64 v88, v188, v88
	v_add_f32_e64 v89, v189, v89
	v_pk_add_f32 v[86:87], v[210:211], v[86:87]
	v_pk_add_f32 v[84:85], v[208:209], v[84:85]
	v_pk_add_f32 v[82:83], v[206:207], v[82:83]
	v_pk_add_f32 v[14:15], v[204:205], v[80:81]
	s_waitcnt lgkmcnt(0)
	s_nop 0
	v_pk_add_f32 v[80:81], v[234:235], v[78:79]
	v_pk_add_f32 v[76:77], v[232:233], v[76:77]
	v_pk_add_f32 v[196:197], v[226:227], v[74:75]
	v_pk_add_f32 v[72:73], v[224:225], v[72:73]
	v_pk_add_f32 v[70:71], v[222:223], v[70:71]
	v_pk_add_f32 v[68:69], v[220:221], v[68:69]
	v_pk_add_f32 v[66:67], v[214:215], v[66:67]
	v_pk_add_f32 v[64:65], v[212:213], v[64:65]
	s_cbranch_scc1 .LBB0_670
	v_cndmask_b32_e64 v0, v14, v237, s[42:43]
	v_cndmask_b32_e64 v64, v64, v237, s[46:47]
	v_cndmask_b32_e64 v15, v237, v15, s[38:39]
	v_cndmask_b32_e64 v14, v0, v14, s[38:39]
	v_cndmask_b32_e64 v65, v65, v237, s[48:49]
	v_cndmask_b32_e64 v82, v82, v237, s[50:51]
	v_cndmask_b32_e64 v66, v66, v237, s[52:53]
	v_cndmask_b32_e64 v83, v83, v237, s[54:55]
	v_cndmask_b32_e64 v67, v67, v237, s[56:57]
	v_cndmask_b32_e64 v84, v84, v237, s[58:59]
	v_cndmask_b32_e64 v68, v68, v237, s[60:61]
	v_cndmask_b32_e64 v85, v85, v237, s[62:63]
	v_cndmask_b32_e64 v69, v69, v237, s[64:65]
	v_cndmask_b32_e64 v86, v86, v237, s[66:67]
	v_cndmask_b32_e64 v70, v70, v237, s[68:69]
	v_cndmask_b32_e64 v87, v87, v237, s[70:71]
	v_cndmask_b32_e64 v71, v71, v237, s[74:75]
	v_cndmask_b32_e64 v88, v88, v237, s[76:77]
	v_cndmask_b32_e64 v72, v72, v237, s[78:79]
	v_cndmask_b32_e64 v89, v89, v237, s[80:81]
	v_cndmask_b32_e64 v73, v73, v237, s[82:83]
	v_cndmask_b32_e64 v90, v90, v237, s[84:85]
	v_cndmask_b32_e64 v196, v196, v237, s[86:87]
	v_cndmask_b32_e64 v91, v91, v237, s[88:89]
	v_cndmask_b32_e64 v197, v197, v237, s[90:91]
	v_cndmask_b32_e64 v92, v92, v237, s[92:93]
	v_cndmask_b32_e64 v76, v76, v237, s[94:95]
	v_cndmask_b32_e64 v93, v93, v237, s[96:97]
	v_cndmask_b32_e64 v77, v77, v237, s[0:1]
	v_cndmask_b32_e64 v202, v202, v237, s[4:5]
	v_cndmask_b32_e64 v80, v80, v237, s[6:7]
	v_cndmask_b32_e64 v203, v203, v237, s[8:9]
	v_cndmask_b32_e64 v81, v81, v237, s[72:73]

; __device__ __forceinline__ unsigned pk2(float lo, float hi) { f32x2 v = {lo, hi}; bf16x2_t b = __builtin_convertvector(v, bf16x2_t); return __builtin_bit_cast(unsigned, b); }
; template <int TYPE, int ND0, int KSTR> __device__ __forceinline__ void tile(LAS unsigned char* lds, int buf, int t, int w_lo, int w_hi, int n, int qrel, int lane, int r32, int hi,
;         const bf16x8 (&qr)[ND0], float& m_run, float& l_run, f32x16& o0, f32x16& o1, f32x16& negm) {
;     ...
; #pragma unroll
;     for (int ks = 0; ks < 4; ++ks) {
;         u32x4 pw;
;         if (ks < 2) { pw.x = pk2(p0[8 * ks], p0[8 * ks + 1]); pw.y = pk2(p0[8 * ks + 2], p0[8 * ks + 3]); pw.z = pk2(p0[8 * ks + 4], p0[8 * ks + 5]); pw.w = pk2(p0[8 * ks + 6], p0[8 * ks + 7]); }
;         else { const int k2 = ks - 2; pw.x = pk2(p1[8 * k2], p1[8 * k2 + 1]); pw.y = pk2(p1[8 * k2 + 2], p1[8 * k2 + 3]); pw.z = pk2(p1[8 * k2 + 4], p1[8 * k2 + 5]); pw.w = pk2(p1[8 * k2 + 6], p1[8 * k2 + 7]); }
;         const bf16x8 pb = __builtin_bit_cast(bf16x8, pw);
;         const bf16x8 va0 = __builtin_shufflevector(vf[ks][0], vf[ks][1], 0, 1, 2, 3, 4, 5, 6, 7), va1 = __builtin_shufflevector(vf[ks][2], vf[ks][3], 0, 1, 2, 3, 4, 5, 6, 7);
;         o0 = __builtin_amdgcn_mfma_f32_32x32x16_bf16(va0, pb, o0, 0, 0, 0);
;         o1 = __builtin_amdgcn_mfma_f32_32x32x16_bf16(va1, pb, o1, 0, 0, 0);
;     }
.LBB0_672:
	v_cvt_pk_bf16_f32 v208, v74, v0
	v_cvt_pk_bf16_f32 v209, v78, v200
	v_cvt_pk_bf16_f32 v210, v82, v204
	v_cvt_pk_bf16_f32 v211, v86, v220
	v_cvt_pk_bf16_f32 v82, v84, v206
	v_cvt_pk_bf16_f32 v83, v88, v222
	s_setprio 2
	v_mfma_f32_32x32x16_bf16 v[32:47], v[168:171], v[208:211], v[32:47]
	v_cvt_pk_bf16_f32 v84, v90, v224
	v_cvt_pk_bf16_f32 v85, v92, v226
	v_cvt_pk_bf16_f32 v65, v72, v196
	v_cvt_pk_bf16_f32 v67, v80, v202
	v_add_f32_e32 v178, v178, v228
	v_mfma_f32_32x32x16_bf16 v[16:31], v[164:167], v[208:211], v[16:31]
	v_mfma_f32_32x32x16_bf16 v[32:47], v[156:159], v[82:85], v[32:47]
	v_mfma_f32_32x32x16_bf16 v[16:31], v[160:163], v[82:85], v[16:31]
	v_cvt_pk_bf16_f32 v82, v14, v94
	v_cvt_pk_bf16_f32 v83, v64, v188
	v_cvt_pk_bf16_f32 v84, v66, v190
	v_cvt_pk_bf16_f32 v85, v70, v194
	v_cvt_pk_bf16_f32 v64, v68, v192
	v_cvt_pk_bf16_f32 v66, v76, v198
	v_mfma_f32_32x32x16_bf16 v[32:47], v[152:155], v[82:85], v[32:47]
	v_mfma_f32_32x32x16_bf16 v[16:31], v[148:151], v[82:85], v[16:31]
	v_mfma_f32_32x32x16_bf16 v[32:47], v[144:147], v[64:67], v[32:47]
	v_mfma_f32_32x32x16_bf16 v[16:31], v[10:13], v[64:67], v[16:31]
	s_setprio 0

; #define ATT_LOAD_NEXT(j, S) do { k##S = *(const u32x4*)(nk + (size_t)(j) * 64 * 512); v##S = *(const u32x4*)(nv + (size_t)(j) * 64 * 512); \
;         k2##S = *(const u32x4*)(nkr + (size_t)(j) * 64 * 32); cb##S = ncg[(j) * 64]; } while (0)
; template <int TYPE> __device__ __forceinline__ int unit(const P& p, LAS unsigned char* lds, int b, int h, int qb, int wave0, bool pre, unsigned nx, int G,
;         u32x4& kA, u32x4& vA, u32x4& k2A, float& cbA, u32x4& kB, u32x4& vB, u32x4& k2B, float& cbB) {
;     ...
;     const int inext = tk[0];
;     {
;         const bool nval = inext < 1536; const int ii = nval ? inext : 0;
;         const int nqb = 7 - ii / 192, nrem = ii % 192, nq = nrem / 64, nbh = nrem % 64, nb = nbh >> 3, nh = nbh & 7;
;         const int nT = (nq == 0) ? 1 : (nq == 1) ? 0 : 2;
;         const int nlo = (nT == 2) ? (4 * nqb - 8 > 0 ? 4 * nqb - 8 : 0) : 0;
;         const bf16* nKp = (nT == 0) ? p.KA : (nT == 1) ? p.KBN : p.KC; const bf16* nVp = (nT == 0) ? p.VA : (nT == 1) ? p.VB : p.VC;
;         const size_t nrow = (size_t)nb * SEQ + (size_t)nlo * 64;
;         const bf16* nk = nKp + (nrow + srow) * 512 + nh * 64 + sch * 8; const bf16* nv = nVp + (nrow + srow) * 512 + nh * 64 + sch * 8;
;         const bf16* nkr = p.KR + (nrow + ((tid & 255) >> 2)) * 32 + (tid & 3) * 8; const float* ncg = p.cum + (size_t)(nb * 8 + nh) * SEQ + nlo * 64 + (tid & 63);
;         ATT_LOAD_NEXT(0, A);
.LBB0_679:
	ds_read_b32 v64, v1 offset:54144
	s_add_i32 s3, s3, 2
	v_readlane_b32 s30, v254, 61
	v_readlane_b32 s31, v254, 62
	v_readlane_b32 vcc_lo, v254, 63
	s_waitcnt lgkmcnt(0)
	v_readfirstlane_b32 s2, v64
	s_cmpk_lt_i32 s2, 0x600
	s_cselect_b32 s2, s2, 0
	s_mul_hi_i32 s22, s2, 0xd5555555
	s_mul_hi_i32 s23, s2, 0x2aaaaaab
	s_lshr_b32 s25, s22, 31
	s_ashr_i32 s22, s22, 5
	s_lshr_b32 s28, s23, 31
	s_add_i32 s25, s22, s25
	s_lshr_b32 s22, s23, 5
	s_add_i32 s22, s22, s28
	s_mulk_i32 s22, 0xc0
	s_sub_i32 s23, s2, s22
	s_bfe_u32 s2, s23, 0x60019
	s_add_i32 s2, s23, s2
	s_and_b32 s2, s2, 0xffc0
	s_sub_i32 s2, s23, s2
	s_lshl_b32 s25, s25, 2
	s_sext_i32_i16 s36, s2
	s_max_i32 s25, s25, 0xffffffec
	s_ashr_i32 s22, s36, 3
	s_sub_i32 s28, s23, 64
	s_add_i32 s29, s23, 0xffffff80
	s_add_i32 s25, s25, 20
	s_cmp_lt_u32 s29, 0xffffff41
	s_cselect_b32 s44, s25, 0
	s_andn2_b32 s23, s23, 63
	s_cmp_lt_u32 s28, 0xffffff81
	v_readlane_b32 s28, v254, 36
	v_readlane_b32 s29, v254, 37
	s_cselect_b32 s25, s30, s28
	s_cselect_b32 s28, s31, s29
	v_readlane_b32 s30, v254, 38
	v_readlane_b32 s31, v254, 39
	v_readlane_b32 vcc_hi, v255, 0
	s_cselect_b32 s30, vcc_lo, s30
	s_cselect_b32 s31, vcc_hi, s31
	v_readlane_b32 vcc_lo, v254, 53
	s_cmp_eq_u32 s23, 64
	v_readlane_b32 vcc_hi, v254, 54
	s_cselect_b32 s29, vcc_hi, s28
	s_cselect_b32 s28, vcc_lo, s25
	v_readlane_b32 vcc_lo, v254, 55
	v_readlane_b32 vcc_hi, v254, 56
	s_cselect_b32 s31, vcc_hi, s31
	s_cselect_b32 s30, vcc_lo, s30
	s_ashr_i32 s23, s22, 31
	s_lshl_b64 s[22:23], s[22:23], 11
	s_lshl_b64 vcc, s[44:45], 6
	s_add_u32 s22, s22, vcc_lo
	s_addc_u32 s23, s23, vcc_hi
	v_lshl_add_u64 v[2:3], s[22:23], 0, v[174:175]
	v_lshlrev_b64 v[2:3], 10, v[2:3]
	s_lshl_b32 s25, s36, 7
	v_lshl_add_u64 v[4:5], s[28:29], 0, v[2:3]
	s_and_b32 s28, s25, 0x380
	s_mov_b32 s29, s45
	v_lshl_add_u64 v[2:3], s[30:31], 0, v[2:3]
	v_lshlrev_b32_e32 v0, 1, v245
	v_lshl_add_u64 v[2:3], v[2:3], 0, s[28:29]
	v_lshl_add_u64 v[14:15], v[2:3], 0, v[0:1]
	v_and_or_b32 v2, v244, 63, s22
	v_mov_b32_e32 v3, s23
	v_readlane_b32 s22, v254, 40
	v_lshlrev_b64 v[2:3], 6, v[2:3]
	v_readlane_b32 s23, v254, 41
	v_lshl_add_u64 v[4:5], v[4:5], 0, s[28:29]
	v_lshl_add_u64 v[184:185], v[4:5], 0, v[0:1]
	v_lshl_add_u64 v[2:3], s[22:23], 0, v[2:3]
	s_bfe_i64 s[22:23], s[2:3], 0x100000
	s_lshl_b64 s[22:23], s[22:23], 13
	v_readlane_b32 s2, v254, 42
	s_add_u32 s2, s2, s22
	v_readlane_b32 s22, v254, 50
	s_addc_u32 s25, s22, s23
	s_lshl_b32 s44, s44, 6
	v_lshlrev_b32_e32 v0, 4, v230
	s_lshl_b64 s[22:23], s[44:45], 2
	v_and_b32_e32 v0, 48, v0
	s_add_u32 s28, s2, s22
	v_lshl_add_u64 v[182:183], v[2:3], 0, v[0:1]
	s_addc_u32 s29, s25, s23
	global_load_dwordx4 v[2:5], v[184:185], off
	global_load_dwordx4 v[6:9], v[14:15], off
	global_load_dwordx4 v[10:13], v[182:183], off
	global_load_dword v230, v180, s[28:29]
	v_readfirstlane_b32 s25, v64
	s_cmp_gt_i32 s3, s41
	v_add_u32_e32 v244, v173, v172
	v_add_u32_e32 v239, v239, v243
	s_cbranch_scc1 .LBB0_685
; #define LAS __attribute__((address_space(3)))
; __device__ __forceinline__ int crow(int r, int hi) { return (r & 3) + 8 * (r >> 2) + 4 * hi; }
; template <int TYPE, int ND0, int KSTR> __device__ __forceinline__ void tile(LAS unsigned char* lds, int buf, int t, int w_lo, int w_hi, int n, int qrel, int lane, int r32, int hi,
;         const bf16x8 (&qr)[ND0], float& m_run, float& l_run, f32x16& o0, f32x16& o1, f32x16& negm) {
;     const LAS unsigned char* kb = lds + KOFF + buf * KBUF + r32 * KSTR + hi * 16;
;     bf16x8 ka[ND0], kc[ND0];
; #pragma unroll
;     for (int d0 = 0; d0 < ND0; ++d0) { ka[d0] = *(const LAS bf16x8*)(kb + d0 * 32); kc[d0] = *(const LAS bf16x8*)(kb + 32 * KSTR + d0 * 32); }
;     const LAS unsigned char* vb = lds + VOFF + buf * VBUF + (4 * hi + ((lane & 15) >> 2)) * VSTR + (16 * ((lane >> 4) & 1) + 4 * (lane & 3)) * 2;
;     s16x4 vf[4][4];
; #pragma unroll
;     for (int ks = 0; ks < 4; ++ks) { vf[ks][0] = vtr(vb + (16 * ks) * VSTR); vf[ks][1] = vtr(vb + (16 * ks + 8) * VSTR); vf[ks][2] = vtr(vb + (16 * ks) * VSTR + 64); vf[ks][3] = vtr(vb + (16 * ks + 8) * VSTR + 64); }
;     f32x4 kbv[8];
;     if (TYPE == 0) { const LAS f32x4* kbi = (const LAS f32x4*)(lds + KBOFF + buf * 256);
; #pragma unroll
;         for (int g = 0; g < 4; ++g) { kbv[g] = kbi[2 * g + hi]; kbv[4 + g] = kbi[8 + 2 * g + hi]; } }
;     asm volatile("" ::: "memory");
;     const int rel = n - t;
;     f32x16 cin = negm;
;     if (TYPE == 2 && rel >= 5) { const float c = ((const LAS float*)(lds + RELOFF))[512];
; #pragma unroll
;         for (int r = 0; r < 16; ++r) cin[r] += c; }
;     f32x16 p0 = cin, p1 = cin;
; #pragma unroll
;     for (int d0 = 0; d0 < ND0; ++d0) {
;         p0 = __builtin_amdgcn_mfma_f32_32x32x16_bf16(ka[d0], qr[d0], p0, 0, 0, 0);
;         p1 = __builtin_amdgcn_mfma_f32_32x32x16_bf16(kc[d0], qr[d0], p1, 0, 0, 0);
;     }
;     if (TYPE == 0) {
; #pragma unroll
;         for (int g = 0; g < 4; ++g)
; #pragma unroll
;             for (int j = 0; j < 4; ++j) { p0[4 * g + j] += kbv[g][j]; p1[4 * g + j] += kbv[4 + g][j]; }
;         if (t == w_hi) {
; #pragma unroll
;             for (int r = 0; r < 16; ++r) { const int kr_ = crow(r, hi); if (kr_ > qrel) p0[r] = -1e30f; if (kr_ + 32 > qrel) p1[r] = -1e30f; }
;         }
	ds_read_b128 v[64:67], v244
	ds_read_b128 v[144:147], v244 offset:32
	ds_read_b128 v[148:151], v244 offset:4608
	ds_read_b128 v[152:155], v244 offset:4640
	s_cmp_lg_u32 s3, s41
	s_waitcnt lgkmcnt(3)
	s_setprio 2
	v_mfma_f32_32x32x16_bf16 v[80:95], v[64:67], v[132:135], v[48:63]
	s_waitcnt lgkmcnt(1)
	v_mfma_f32_32x32x16_bf16 v[64:79], v[148:151], v[132:135], v[48:63]
	v_mfma_f32_32x32x16_bf16 v[80:95], v[144:147], v[128:131], v[80:95]
	ds_read_b128 v[144:147], v244 offset:64
	ds_read_b128 v[186:189], v244 offset:96
	ds_read_b128 v[190:193], v244 offset:4672
	ds_read_b128 v[194:197], v244 offset:4704
	ds_read_b64_tr_b16 v[172:173], v239 offset:26624
	ds_read_b64_tr_b16 v[174:175], v239 offset:28160
	ds_read_b64_tr_b16 v[170:171], v239 offset:28224
	ds_read_b64_tr_b16 v[168:169], v239 offset:26688
	ds_read_b64_tr_b16 v[160:161], v239 offset:29696
	ds_read_b64_tr_b16 v[162:163], v239 offset:31232
	ds_read_b64_tr_b16 v[166:167], v239 offset:31296
	ds_read_b64_tr_b16 v[164:165], v239 offset:29760
	s_waitcnt lgkmcnt(12)
	v_mfma_f32_32x32x16_bf16 v[64:79], v[152:155], v[128:131], v[64:79]
	s_waitcnt lgkmcnt(11)
	v_mfma_f32_32x32x16_bf16 v[80:95], v[144:147], v[124:127], v[80:95]
	ds_read_b64_tr_b16 v[156:157], v239 offset:32768
	ds_read_b64_tr_b16 v[158:159], v239 offset:34304
	ds_read_b64_tr_b16 v[154:155], v239 offset:34368
	ds_read_b64_tr_b16 v[152:153], v239 offset:32832
	ds_read_b64_tr_b16 v[148:149], v239 offset:35840
	ds_read_b64_tr_b16 v[150:151], v239 offset:37376
	ds_read_b64_tr_b16 v[146:147], v239 offset:37440
	ds_read_b64_tr_b16 v[144:145], v239 offset:35904
	ds_read_b128 v[198:201], v231 offset:51200
	ds_read_b128 v[202:205], v231 offset:51232
	s_waitcnt lgkmcnt(14)
	v_mfma_f32_32x32x16_bf16 v[64:79], v[190:193], v[124:127], v[64:79]
	v_mfma_f32_32x32x16_bf16 v[80:95], v[186:189], v[120:123], v[80:95]
	ds_read_b128 v[186:189], v231 offset:51264
	ds_read_b128 v[206:209], v231 offset:51296
	ds_read_b128 v[210:213], v231 offset:51328
	ds_read_b128 v[214:217], v231 offset:51360
	ds_read_b128 v[220:223], v231 offset:51392
	ds_read_b128 v[224:227], v231 offset:51424
	s_waitcnt lgkmcnt(4)
	s_nop 4
	v_pk_add_f32 v[94:95], v[208:209], v[94:95]
	v_mfma_f32_32x32x16_bf16 v[64:79], v[194:197], v[120:123], v[64:79]
	s_setprio 0
	v_add_f32_e64 v92, v206, v92
	v_add_f32_e64 v93, v207, v93
	v_add_f32_e64 v90, v188, v90
	v_add_f32_e64 v91, v189, v91
	v_add_f32_e64 v192, v186, v88
	v_add_f32_e64 v193, v187, v89
	v_pk_add_f32 v[86:87], v[204:205], v[86:87]
	v_pk_add_f32 v[84:85], v[202:203], v[84:85]
	v_pk_add_f32 v[88:89], v[200:201], v[82:83]
	v_pk_add_f32 v[80:81], v[198:199], v[80:81]
	s_waitcnt lgkmcnt(0)
	s_nop 0
	v_pk_add_f32 v[82:83], v[226:227], v[78:79]
	v_pk_add_f32 v[78:79], v[224:225], v[76:77]
	v_pk_add_f32 v[74:75], v[222:223], v[74:75]
	v_pk_add_f32 v[196:197], v[220:221], v[72:73]
	v_pk_add_f32 v[70:71], v[216:217], v[70:71]
	v_pk_add_f32 v[68:69], v[214:215], v[68:69]
	v_pk_add_f32 v[66:67], v[212:213], v[66:67]
	v_pk_add_f32 v[64:65], v[210:211], v[64:65]
	s_cbranch_scc1 .LBB0_682
	v_cndmask_b32_e64 v0, v80, v237, s[42:43]
	v_cndmask_b32_e64 v64, v64, v237, s[46:47]
	v_cndmask_b32_e64 v81, v237, v81, s[38:39]
	v_cndmask_b32_e64 v80, v0, v80, s[38:39]
	v_cndmask_b32_e64 v65, v65, v237, s[48:49]
	v_cndmask_b32_e64 v88, v88, v237, s[50:51]
	v_cndmask_b32_e64 v66, v66, v237, s[52:53]
	v_cndmask_b32_e64 v89, v89, v237, s[54:55]
	v_cndmask_b32_e64 v67, v67, v237, s[56:57]
	v_cndmask_b32_e64 v84, v84, v237, s[58:59]
	v_cndmask_b32_e64 v68, v68, v237, s[60:61]
	v_cndmask_b32_e64 v85, v85, v237, s[62:63]
	v_cndmask_b32_e64 v69, v69, v237, s[64:65]
	v_cndmask_b32_e64 v86, v86, v237, s[66:67]
	v_cndmask_b32_e64 v70, v70, v237, s[68:69]
	v_cndmask_b32_e64 v87, v87, v237, s[70:71]
	v_cndmask_b32_e64 v71, v71, v237, s[74:75]
	v_cndmask_b32_e64 v192, v192, v237, s[76:77]
	v_cndmask_b32_e64 v196, v196, v237, s[78:79]
	v_cndmask_b32_e64 v193, v193, v237, s[80:81]
	v_cndmask_b32_e64 v197, v197, v237, s[82:83]
	v_cndmask_b32_e64 v90, v90, v237, s[84:85]
	v_cndmask_b32_e64 v74, v74, v237, s[86:87]
	v_cndmask_b32_e64 v91, v91, v237, s[88:89]
	v_cndmask_b32_e64 v75, v75, v237, s[90:91]
	v_cndmask_b32_e64 v92, v92, v237, s[92:93]
	v_cndmask_b32_e64 v78, v78, v237, s[94:95]
	v_cndmask_b32_e64 v93, v93, v237, s[96:97]
	v_cndmask_b32_e64 v79, v79, v237, s[0:1]
	v_cndmask_b32_e64 v94, v94, v237, s[4:5]
	v_cndmask_b32_e64 v82, v82, v237, s[6:7]
	v_cndmask_b32_e64 v95, v95, v237, s[8:9]
	v_cndmask_b32_e64 v83, v83, v237, s[72:73]

; __device__ __forceinline__ unsigned pk2(float lo, float hi) { f32x2 v = {lo, hi}; bf16x2_t b = __builtin_convertvector(v, bf16x2_t); return __builtin_bit_cast(unsigned, b); }
; template <int TYPE, int ND0, int KSTR> __device__ __forceinline__ void tile(LAS unsigned char* lds, int buf, int t, int w_lo, int w_hi, int n, int qrel, int lane, int r32, int hi,
;         const bf16x8 (&qr)[ND0], float& m_run, float& l_run, f32x16& o0, f32x16& o1, f32x16& negm) {
;     ...
; #pragma unroll
;     for (int ks = 0; ks < 4; ++ks) {
;         u32x4 pw;
;         if (ks < 2) { pw.x = pk2(p0[8 * ks], p0[8 * ks + 1]); pw.y = pk2(p0[8 * ks + 2], p0[8 * ks + 3]); pw.z = pk2(p0[8 * ks + 4], p0[8 * ks + 5]); pw.w = pk2(p0[8 * ks + 6], p0[8 * ks + 7]); }
;         else { const int k2 = ks - 2; pw.x = pk2(p1[8 * k2], p1[8 * k2 + 1]); pw.y = pk2(p1[8 * k2 + 2], p1[8 * k2 + 3]); pw.z = pk2(p1[8 * k2 + 4], p1[8 * k2 + 5]); pw.w = pk2(p1[8 * k2 + 6], p1[8 * k2 + 7]); }
;         const bf16x8 pb = __builtin_bit_cast(bf16x8, pw);
;         const bf16x8 va0 = __builtin_shufflevector(vf[ks][0], vf[ks][1], 0, 1, 2, 3, 4, 5, 6, 7), va1 = __builtin_shufflevector(vf[ks][2], vf[ks][3], 0, 1, 2, 3, 4, 5, 6, 7);
;         o0 = __builtin_amdgcn_mfma_f32_32x32x16_bf16(va0, pb, o0, 0, 0, 0);
;         o1 = __builtin_amdgcn_mfma_f32_32x32x16_bf16(va1, pb, o1, 0, 0, 0);
;     }
.LBB0_684:
	v_cvt_pk_bf16_f32 v208, v76, v0
	v_cvt_pk_bf16_f32 v209, v80, v200
	v_cvt_pk_bf16_f32 v210, v84, v204
	v_cvt_pk_bf16_f32 v211, v88, v220
	v_cvt_pk_bf16_f32 v84, v86, v206
	v_cvt_pk_bf16_f32 v85, v90, v222
	s_setprio 2
	v_mfma_f32_32x32x16_bf16 v[32:47], v[172:175], v[208:211], v[32:47]
	v_cvt_pk_bf16_f32 v86, v92, v224
	v_cvt_pk_bf16_f32 v87, v94, v226
	v_cvt_pk_bf16_f32 v64, v64, v186
	v_cvt_pk_bf16_f32 v65, v66, v188
	v_cvt_pk_bf16_f32 v66, v68, v190
	v_cvt_pk_bf16_f32 v67, v72, v194
	v_add_f32_e32 v178, v178, v228
	v_mfma_f32_32x32x16_bf16 v[16:31], v[168:171], v[208:211], v[16:31]
	v_mfma_f32_32x32x16_bf16 v[32:47], v[160:163], v[84:87], v[32:47]
	v_mfma_f32_32x32x16_bf16 v[16:31], v[164:167], v[84:87], v[16:31]
	v_mfma_f32_32x32x16_bf16 v[32:47], v[156:159], v[64:67], v[32:47]
	v_mfma_f32_32x32x16_bf16 v[16:31], v[152:155], v[64:67], v[16:31]
	v_cvt_pk_bf16_f32 v64, v70, v192
	v_cvt_pk_bf16_f32 v65, v74, v196
	v_cvt_pk_bf16_f32 v66, v78, v198
	v_cvt_pk_bf16_f32 v67, v82, v202
	s_nop 1
	v_mfma_f32_32x32x16_bf16 v[32:47], v[148:151], v[64:67], v[32:47]
	v_mfma_f32_32x32x16_bf16 v[16:31], v[144:147], v[64:67], v[16:31]
	s_setprio 0
	s_branch .LBB0_686

; #define LAS __attribute__((address_space(3)))
; __device__ __forceinline__ int crow(int r, int hi) { return (r & 3) + 8 * (r >> 2) + 4 * hi; }
; template <int TYPE, int ND0, int KSTR> __device__ __forceinline__ void tile(LAS unsigned char* lds, int buf, int t, int w_lo, int w_hi, int n, int qrel, int lane, int r32, int hi,
;         const bf16x8 (&qr)[ND0], float& m_run, float& l_run, f32x16& o0, f32x16& o1, f32x16& negm) {
;     const LAS unsigned char* kb = lds + KOFF + buf * KBUF + r32 * KSTR + hi * 16;
;     bf16x8 ka[ND0], kc[ND0];
; #pragma unroll
;     for (int d0 = 0; d0 < ND0; ++d0) { ka[d0] = *(const LAS bf16x8*)(kb + d0 * 32); kc[d0] = *(const LAS bf16x8*)(kb + 32 * KSTR + d0 * 32); }
;     const LAS unsigned char* vb = lds + VOFF + buf * VBUF + (4 * hi + ((lane & 15) >> 2)) * VSTR + (16 * ((lane >> 4) & 1) + 4 * (lane & 3)) * 2;
;     s16x4 vf[4][4];
; #pragma unroll
;     for (int ks = 0; ks < 4; ++ks) { vf[ks][0] = vtr(vb + (16 * ks) * VSTR); vf[ks][1] = vtr(vb + (16 * ks + 8) * VSTR); vf[ks][2] = vtr(vb + (16 * ks) * VSTR + 64); vf[ks][3] = vtr(vb + (16 * ks + 8) * VSTR + 64); }
;     f32x4 kbv[8];
;     if (TYPE == 0) { const LAS f32x4* kbi = (const LAS f32x4*)(lds + KBOFF + buf * 256);
; #pragma unroll
;         for (int g = 0; g < 4; ++g) { kbv[g] = kbi[2 * g + hi]; kbv[4 + g] = kbi[8 + 2 * g + hi]; } }
;     asm volatile("" ::: "memory");
;     const int rel = n - t;
;     f32x16 cin = negm;
;     if (TYPE == 2 && rel >= 5) { const float c = ((const LAS float*)(lds + RELOFF))[512];
; #pragma unroll
;         for (int r = 0; r < 16; ++r) cin[r] += c; }
;     f32x16 p0 = cin, p1 = cin;
; #pragma unroll
;     for (int d0 = 0; d0 < ND0; ++d0) {
;         p0 = __builtin_amdgcn_mfma_f32_32x32x16_bf16(ka[d0], qr[d0], p0, 0, 0, 0);
;         p1 = __builtin_amdgcn_mfma_f32_32x32x16_bf16(kc[d0], qr[d0], p1, 0, 0, 0);
;     }
;     if (TYPE == 0) {
; #pragma unroll
;         for (int g = 0; g < 4; ++g)
; #pragma unroll
;             for (int j = 0; j < 4; ++j) { p0[4 * g + j] += kbv[g][j]; p1[4 * g + j] += kbv[4 + g][j]; }
;         if (t == w_hi) {
; #pragma unroll
;             for (int r = 0; r < 16; ++r) { const int kr_ = crow(r, hi); if (kr_ > qrel) p0[r] = -1e30f; if (kr_ + 32 > qrel) p1[r] = -1e30f; }
;         }
.LBB0_688:
	s_or_b64 exec, exec, s[28:29]
	v_add_co_u32_e32 v66, vcc, 0x10000, v184
	s_waitcnt lgkmcnt(0)
	s_nop 0
	v_addc_co_u32_e32 v67, vcc, 0, v185, vcc
	v_add_co_u32_e32 v14, vcc, 0x10000, v14
	s_barrier
	s_nop 0
	v_addc_co_u32_e32 v15, vcc, 0, v15, vcc
	global_load_dwordx4 v[84:87], v[14:15], off
	v_add_co_u32_e32 v14, vcc, 0x1000, v182
	global_load_dwordx4 v[80:83], v[66:67], off
	s_nop 0
	v_addc_co_u32_e32 v15, vcc, 0, v183, vcc
	global_load_dwordx4 v[88:91], v[14:15], off
	global_load_dword v196, v[64:65], off offset:256
	s_cmp_ge_i32 s3, s41
	s_cbranch_scc1 .LBB0_694
	ds_read_b128 v[92:95], v244 offset:13312
	ds_read_b128 v[136:139], v244 offset:13344
	s_or_b32 s2, s3, 1
	s_cmp_lg_u32 s2, s41
	s_waitcnt lgkmcnt(1)
	s_setprio 2
	v_mfma_f32_32x32x16_bf16 v[64:79], v[92:95], v[132:135], v[48:63]
	ds_read_b128 v[92:95], v244 offset:17920
	ds_read_b128 v[140:143], v244 offset:17952
	s_waitcnt lgkmcnt(1)
	v_mfma_f32_32x32x16_bf16 v[48:63], v[92:95], v[132:135], v[48:63]
	ds_read_b128 v[92:95], v244 offset:13376
	ds_read_b128 v[156:159], v244 offset:13408
	ds_read_b128 v[164:167], v244 offset:17984
	ds_read_b128 v[168:171], v244 offset:18016
	v_mfma_f32_32x32x16_bf16 v[64:79], v[136:139], v[128:131], v[64:79]
	s_waitcnt lgkmcnt(4)
	v_mfma_f32_32x32x16_bf16 v[48:63], v[140:143], v[128:131], v[48:63]
	ds_read_b64_tr_b16 v[152:153], v239 offset:38912
	ds_read_b64_tr_b16 v[154:155], v239 offset:40448
	ds_read_b64_tr_b16 v[150:151], v239 offset:40512
	ds_read_b64_tr_b16 v[148:149], v239 offset:38976
	ds_read_b64_tr_b16 v[140:141], v239 offset:41984
	ds_read_b64_tr_b16 v[142:143], v239 offset:43520
	ds_read_b64_tr_b16 v[146:147], v239 offset:43584
	ds_read_b64_tr_b16 v[144:145], v239 offset:42048
	s_waitcnt lgkmcnt(11)
	v_mfma_f32_32x32x16_bf16 v[64:79], v[92:95], v[124:127], v[64:79]
	ds_read_b64_tr_b16 v[136:137], v239 offset:45056
	ds_read_b64_tr_b16 v[138:139], v239 offset:46592
	ds_read_b64_tr_b16 v[134:135], v239 offset:46656
	ds_read_b64_tr_b16 v[132:133], v239 offset:45120
	ds_read_b64_tr_b16 v[128:129], v239 offset:48128
	ds_read_b64_tr_b16 v[130:131], v239 offset:49664
	ds_read_b64_tr_b16 v[94:95], v239 offset:49728
	ds_read_b64_tr_b16 v[92:93], v239 offset:48192
	ds_read_b128 v[172:175], v231 offset:51456
	ds_read_b128 v[180:183], v231 offset:51488
	s_waitcnt lgkmcnt(14)
	v_mfma_f32_32x32x16_bf16 v[48:63], v[164:167], v[124:127], v[48:63]
	v_mfma_f32_32x32x16_bf16 v[64:79], v[156:159], v[120:123], v[64:79]
	ds_read_b128 v[156:159], v231 offset:51520
	ds_read_b128 v[160:163], v231 offset:51552
	ds_read_b128 v[184:187], v231 offset:51584
	ds_read_b128 v[188:191], v231 offset:51616
	ds_read_b128 v[192:195], v231 offset:51648
	ds_read_b128 v[198:201], v231 offset:51680
	s_waitcnt lgkmcnt(4)
	s_nop 4
	v_pk_add_f32 v[162:163], v[162:163], v[78:79]
	v_mfma_f32_32x32x16_bf16 v[48:63], v[168:171], v[120:123], v[48:63]
	s_setprio 0
	v_add_f32_e64 v76, v160, v76
	v_add_f32_e64 v77, v161, v77
	v_add_f32_e64 v74, v158, v74
	v_add_f32_e64 v75, v159, v75
	v_add_f32_e64 v72, v156, v72
	v_add_f32_e64 v73, v157, v73
	v_pk_add_f32 v[70:71], v[182:183], v[70:71]
	v_pk_add_f32 v[68:69], v[180:181], v[68:69]
	v_pk_add_f32 v[66:67], v[174:175], v[66:67]
	v_pk_add_f32 v[14:15], v[172:173], v[64:65]
	s_waitcnt lgkmcnt(0)
	s_nop 0
	v_pk_add_f32 v[64:65], v[200:201], v[62:63]
	v_pk_add_f32 v[60:61], v[198:199], v[60:61]
	v_pk_add_f32 v[156:157], v[194:195], v[58:59]
	v_pk_add_f32 v[56:57], v[192:193], v[56:57]
	v_pk_add_f32 v[54:55], v[190:191], v[54:55]
	v_pk_add_f32 v[52:53], v[188:189], v[52:53]
	v_pk_add_f32 v[50:51], v[186:187], v[50:51]
	v_pk_add_f32 v[48:49], v[184:185], v[48:49]
	s_cbranch_scc1 .LBB0_691
	v_cndmask_b32_e64 v0, v14, v237, s[42:43]
	v_cndmask_b32_e64 v48, v48, v237, s[46:47]
	v_cndmask_b32_e64 v15, v237, v15, s[38:39]
	v_cndmask_b32_e64 v14, v0, v14, s[38:39]
	v_cndmask_b32_e64 v49, v49, v237, s[48:49]
	v_cndmask_b32_e64 v66, v66, v237, s[50:51]
	v_cndmask_b32_e64 v50, v50, v237, s[52:53]
	v_cndmask_b32_e64 v67, v67, v237, s[54:55]
	v_cndmask_b32_e64 v51, v51, v237, s[56:57]
	v_cndmask_b32_e64 v68, v68, v237, s[58:59]
	v_cndmask_b32_e64 v52, v52, v237, s[60:61]
	v_cndmask_b32_e64 v69, v69, v237, s[62:63]
	v_cndmask_b32_e64 v53, v53, v237, s[64:65]
	v_cndmask_b32_e64 v70, v70, v237, s[66:67]
	v_cndmask_b32_e64 v54, v54, v237, s[68:69]
	v_cndmask_b32_e64 v71, v71, v237, s[70:71]
	v_cndmask_b32_e64 v55, v55, v237, s[74:75]
	v_cndmask_b32_e64 v72, v72, v237, s[76:77]
	v_cndmask_b32_e64 v56, v56, v237, s[78:79]
	v_cndmask_b32_e64 v73, v73, v237, s[80:81]
	v_cndmask_b32_e64 v57, v57, v237, s[82:83]
	v_cndmask_b32_e64 v74, v74, v237, s[84:85]
	v_cndmask_b32_e64 v156, v156, v237, s[86:87]
	v_cndmask_b32_e64 v75, v75, v237, s[88:89]
	v_cndmask_b32_e64 v157, v157, v237, s[90:91]
	v_cndmask_b32_e64 v76, v76, v237, s[92:93]
	v_cndmask_b32_e64 v60, v60, v237, s[94:95]
	v_cndmask_b32_e64 v77, v77, v237, s[96:97]
	v_cndmask_b32_e64 v61, v61, v237, s[0:1]
	v_cndmask_b32_e64 v162, v162, v237, s[4:5]
	v_cndmask_b32_e64 v64, v64, v237, s[6:7]
	v_cndmask_b32_e64 v163, v163, v237, s[8:9]
	v_cndmask_b32_e64 v65, v65, v237, s[72:73]

; __device__ __forceinline__ unsigned pk2(float lo, float hi) { f32x2 v = {lo, hi}; bf16x2_t b = __builtin_convertvector(v, bf16x2_t); return __builtin_bit_cast(unsigned, b); }
; template <int TYPE, int ND0, int KSTR> __device__ __forceinline__ void tile(LAS unsigned char* lds, int buf, int t, int w_lo, int w_hi, int n, int qrel, int lane, int r32, int hi,
;         const bf16x8 (&qr)[ND0], float& m_run, float& l_run, f32x16& o0, f32x16& o1, f32x16& negm) {
;     ...
; #pragma unroll
;     for (int ks = 0; ks < 4; ++ks) {
;         u32x4 pw;
;         if (ks < 2) { pw.x = pk2(p0[8 * ks], p0[8 * ks + 1]); pw.y = pk2(p0[8 * ks + 2], p0[8 * ks + 3]); pw.z = pk2(p0[8 * ks + 4], p0[8 * ks + 5]); pw.w = pk2(p0[8 * ks + 6], p0[8 * ks + 7]); }
;         else { const int k2 = ks - 2; pw.x = pk2(p1[8 * k2], p1[8 * k2 + 1]); pw.y = pk2(p1[8 * k2 + 2], p1[8 * k2 + 3]); pw.z = pk2(p1[8 * k2 + 4], p1[8 * k2 + 5]); pw.w = pk2(p1[8 * k2 + 6], p1[8 * k2 + 7]); }
;         const bf16x8 pb = __builtin_bit_cast(bf16x8, pw);
;         const bf16x8 va0 = __builtin_shufflevector(vf[ks][0], vf[ks][1], 0, 1, 2, 3, 4, 5, 6, 7), va1 = __builtin_shufflevector(vf[ks][2], vf[ks][3], 0, 1, 2, 3, 4, 5, 6, 7);
;         o0 = __builtin_amdgcn_mfma_f32_32x32x16_bf16(va0, pb, o0, 0, 0, 0);
;         o1 = __builtin_amdgcn_mfma_f32_32x32x16_bf16(va1, pb, o1, 0, 0, 0);
;     }
.LBB0_693:
	v_add_f32_e32 v178, v178, v180
	v_cvt_pk_bf16_f32 v180, v58, v0
	v_cvt_pk_bf16_f32 v181, v62, v160
	v_cvt_pk_bf16_f32 v182, v66, v164
	v_cvt_pk_bf16_f32 v183, v70, v168
	v_cvt_pk_bf16_f32 v66, v68, v166
	v_cvt_pk_bf16_f32 v67, v72, v170
	s_setprio 2
	v_mfma_f32_32x32x16_bf16 v[32:47], v[152:155], v[180:183], v[32:47]
	v_cvt_pk_bf16_f32 v68, v74, v172
	v_cvt_pk_bf16_f32 v69, v76, v174
	v_cvt_pk_bf16_f32 v49, v56, v156
	v_cvt_pk_bf16_f32 v51, v64, v162
	v_mfma_f32_32x32x16_bf16 v[16:31], v[148:151], v[180:183], v[16:31]
	v_mfma_f32_32x32x16_bf16 v[32:47], v[140:143], v[66:69], v[32:47]
	v_mfma_f32_32x32x16_bf16 v[16:31], v[144:147], v[66:69], v[16:31]
	v_cvt_pk_bf16_f32 v66, v14, v78
	v_cvt_pk_bf16_f32 v67, v48, v120
	v_cvt_pk_bf16_f32 v68, v50, v122
	v_cvt_pk_bf16_f32 v69, v54, v126
	v_cvt_pk_bf16_f32 v48, v52, v124
	v_cvt_pk_bf16_f32 v50, v60, v158
	v_mfma_f32_32x32x16_bf16 v[32:47], v[136:139], v[66:69], v[32:47]
	v_mfma_f32_32x32x16_bf16 v[16:31], v[132:135], v[66:69], v[16:31]
	v_mfma_f32_32x32x16_bf16 v[32:47], v[128:131], v[48:51], v[32:47]
	v_mfma_f32_32x32x16_bf16 v[16:31], v[92:95], v[48:51], v[16:31]
	s_setprio 0

; #define LAS __attribute__((address_space(3)))
; template <int TYPE, int ND0, int KSTR> __device__ __forceinline__ void tile(LAS unsigned char* lds, int buf, int t, int w_lo, int w_hi, int n, int qrel, int lane, int r32, int hi,
;         const bf16x8 (&qr)[ND0], float& m_run, float& l_run, f32x16& o0, f32x16& o1, f32x16& negm) {
;     const LAS unsigned char* kb = lds + KOFF + buf * KBUF + r32 * KSTR + hi * 16;
;     bf16x8 ka[ND0], kc[ND0];
; #pragma unroll
;     for (int d0 = 0; d0 < ND0; ++d0) { ka[d0] = *(const LAS bf16x8*)(kb + d0 * 32); kc[d0] = *(const LAS bf16x8*)(kb + 32 * KSTR + d0 * 32); }
;     const LAS unsigned char* vb = lds + VOFF + buf * VBUF + (4 * hi + ((lane & 15) >> 2)) * VSTR + (16 * ((lane >> 4) & 1) + 4 * (lane & 3)) * 2;
;     s16x4 vf[4][4];
; #pragma unroll
;     for (int ks = 0; ks < 4; ++ks) { vf[ks][0] = vtr(vb + (16 * ks) * VSTR); vf[ks][1] = vtr(vb + (16 * ks + 8) * VSTR); vf[ks][2] = vtr(vb + (16 * ks) * VSTR + 64); vf[ks][3] = vtr(vb + (16 * ks + 8) * VSTR + 64); }
;     f32x4 kbv[8];
;     if (TYPE == 0) { const LAS f32x4* kbi = (const LAS f32x4*)(lds + KBOFF + buf * 256);
; #pragma unroll
;         for (int g = 0; g < 4; ++g) { kbv[g] = kbi[2 * g + hi]; kbv[4 + g] = kbi[8 + 2 * g + hi]; } }
;     asm volatile("" ::: "memory");
;     const int rel = n - t;
;     f32x16 cin = negm;
;     if (TYPE == 2 && rel >= 5) { const float c = ((const LAS float*)(lds + RELOFF))[512];
; #pragma unroll
;         for (int r = 0; r < 16; ++r) cin[r] += c; }
;     f32x16 p0 = cin, p1 = cin;
; #pragma unroll
;     for (int d0 = 0; d0 < ND0; ++d0) {
;         p0 = __builtin_amdgcn_mfma_f32_32x32x16_bf16(ka[d0], qr[d0], p0, 0, 0, 0);
;         p1 = __builtin_amdgcn_mfma_f32_32x32x16_bf16(kc[d0], qr[d0], p1, 0, 0, 0);
;     }
;     if (TYPE == 0) {
; #pragma unroll
;         for (int g = 0; g < 4; ++g)
; #pragma unroll
;             for (int j = 0; j < 4; ++j) { p0[4 * g + j] += kbv[g][j]; p1[4 * g + j] += kbv[4 + g][j]; }
;         if (t == w_hi) {
; #pragma unroll
;             for (int r = 0; r < 16; ++r) { const int kr_ = crow(r, hi); if (kr_ > qrel) p0[r] = -1e30f; if (kr_ + 32 > qrel) p1[r] = -1e30f; }
;         }
;     }
;     if (TYPE == 2 && rel < 5) {
;         const LAS float* rb = (const LAS float*)(lds + RELOFF) + (qrel + 64 * rel + 256 - 4 * hi - 59);
; #pragma unroll
.LBB0_704:
	s_sub_i32 s44, s4, 64
	s_lshl_b64 s[6:7], s[44:45], 10
	s_waitcnt vmcnt(3)
	v_lshl_add_u64 v[2:3], v[174:175], 0, s[6:7]
	v_lshl_add_u64 v[4:5], v[176:177], 0, s[6:7]
	s_lshl_b64 s[6:7], s[44:45], 6
	global_load_dwordx4 v[6:9], v[2:3], off
	global_load_dwordx4 v[10:13], v[4:5], off
	v_lshl_add_u64 v[2:3], v[180:181], 0, s[6:7]
	global_load_dwordx4 v[2:5], v[2:3], off
	s_cmp_gt_i32 s3, s9
	s_cbranch_scc1 .LBB0_710
	v_add_u32_e32 v0, v227, v170
	ds_read_b128 v[80:83], v0
	s_waitcnt vmcnt(6)
	ds_read_b128 v[108:111], v0 offset:32
	ds_read_b128 v[112:115], v0 offset:6656
	ds_read_b128 v[116:119], v0 offset:6688
	s_cmp_lg_u32 s3, 0
	s_waitcnt lgkmcnt(3)
	s_setprio 2
	v_mfma_f32_32x32x16_bf16 v[64:79], v[80:83], v[140:143], v[48:63]
	s_waitcnt lgkmcnt(1)
	v_mfma_f32_32x32x16_bf16 v[80:95], v[112:115], v[140:143], v[48:63]
	v_mfma_f32_32x32x16_bf16 v[64:79], v[108:111], v[136:139], v[64:79]
	ds_read_b128 v[108:111], v0 offset:64
	ds_read_b128 v[112:115], v0 offset:96
	s_waitcnt lgkmcnt(2)
	v_mfma_f32_32x32x16_bf16 v[80:95], v[116:119], v[136:139], v[80:95]
	s_waitcnt lgkmcnt(1)
	v_mfma_f32_32x32x16_bf16 v[64:79], v[108:111], v[132:135], v[64:79]
	ds_read_b128 v[108:111], v0 offset:6720
	ds_read_b128 v[116:119], v0 offset:6752
	s_waitcnt lgkmcnt(1)
	v_mfma_f32_32x32x16_bf16 v[80:95], v[108:111], v[132:135], v[80:95]
	s_waitcnt vmcnt(5)
	v_mfma_f32_32x32x16_bf16 v[64:79], v[112:115], v[128:131], v[64:79]
	ds_read_b128 v[108:111], v0 offset:128
	ds_read_b128 v[112:115], v0 offset:160
	s_waitcnt lgkmcnt(2)
	v_mfma_f32_32x32x16_bf16 v[80:95], v[116:119], v[128:131], v[80:95]
	s_waitcnt vmcnt(4) lgkmcnt(1)
	v_mfma_f32_32x32x16_bf16 v[64:79], v[108:111], v[124:127], v[64:79]
	ds_read_b128 v[108:111], v0 offset:6784
	ds_read_b128 v[182:185], v0 offset:6816
	v_add_u32_e32 v0, v228, v229
	ds_read_b64_tr_b16 v[160:161], v0 offset:26624
	ds_read_b64_tr_b16 v[162:163], v0 offset:28160
	ds_read_b64_tr_b16 v[158:159], v0 offset:28224
	ds_read_b64_tr_b16 v[156:157], v0 offset:26688
	ds_read_b64_tr_b16 v[152:153], v0 offset:29696
	ds_read_b64_tr_b16 v[154:155], v0 offset:31232
	ds_read_b64_tr_b16 v[150:151], v0 offset:31296
	ds_read_b64_tr_b16 v[148:149], v0 offset:29760
	s_waitcnt lgkmcnt(9)
	v_mfma_f32_32x32x16_bf16 v[80:95], v[108:111], v[124:127], v[80:95]
	s_waitcnt vmcnt(3)
	v_mfma_f32_32x32x16_bf16 v[64:79], v[112:115], v[120:123], v[64:79]
	ds_read_b64_tr_b16 v[116:117], v0 offset:32768
	ds_read_b64_tr_b16 v[118:119], v0 offset:34304
	ds_read_b64_tr_b16 v[146:147], v0 offset:34368
	ds_read_b64_tr_b16 v[144:145], v0 offset:32832
	ds_read_b64_tr_b16 v[112:113], v0 offset:35840
	ds_read_b64_tr_b16 v[114:115], v0 offset:37376
	ds_read_b64_tr_b16 v[110:111], v0 offset:37440
	ds_read_b64_tr_b16 v[108:109], v0 offset:35904
	s_waitcnt lgkmcnt(14)
	v_mfma_f32_32x32x16_bf16 v[80:95], v[182:185], v[120:123], v[80:95]
	s_setprio 0
	s_cbranch_scc1 .LBB0_707
	s_nop 10
	v_max_f32_e32 v0, v81, v81
	v_max_f32_e32 v14, v65, v65
	v_max_f32_e32 v0, v14, v0
	v_max_f32_e32 v14, v82, v82
	v_max_f32_e32 v15, v66, v66
	v_max_f32_e32 v14, v15, v14
	v_max_f32_e32 v15, v83, v83
	v_max_f32_e32 v48, v67, v67
	v_max3_f32 v0, v64, v80, v0
	v_max_f32_e32 v15, v48, v15
	v_max3_f32 v0, v0, v14, v15
	v_max_f32_e32 v14, v84, v84
	v_max_f32_e32 v15, v68, v68
	v_max_f32_e32 v14, v15, v14
	v_max_f32_e32 v15, v85, v85
	v_max_f32_e32 v48, v69, v69
	v_max_f32_e32 v15, v48, v15
	v_max3_f32 v0, v0, v14, v15
	v_max_f32_e32 v14, v86, v86
	v_max_f32_e32 v15, v70, v70
	v_max_f32_e32 v14, v15, v14
	v_max_f32_e32 v15, v87, v87
	v_max_f32_e32 v48, v71, v71
	v_max_f32_e32 v15, v48, v15
	v_max3_f32 v0, v0, v14, v15
	v_max_f32_e32 v14, v88, v88
	v_max_f32_e32 v15, v72, v72
	v_max_f32_e32 v14, v15, v14
	v_max_f32_e32 v15, v89, v89
	v_max_f32_e32 v48, v73, v73
	v_max_f32_e32 v15, v48, v15
	v_max3_f32 v0, v0, v14, v15
	v_max_f32_e32 v14, v90, v90
	v_max_f32_e32 v15, v74, v74
	v_max_f32_e32 v14, v15, v14
	v_max_f32_e32 v15, v91, v91
	v_max_f32_e32 v48, v75, v75
	v_max_f32_e32 v15, v48, v15
	v_max3_f32 v0, v0, v14, v15
	v_max_f32_e32 v14, v92, v92
	v_max_f32_e32 v15, v76, v76
	v_max_f32_e32 v14, v15, v14
	v_max_f32_e32 v15, v93, v93
	v_max_f32_e32 v48, v77, v77
	v_max_f32_e32 v15, v48, v15
	v_max3_f32 v0, v0, v14, v15
	v_max_f32_e32 v14, v94, v94
	v_max_f32_e32 v15, v78, v78
	v_max_f32_e32 v14, v15, v14
	v_max_f32_e32 v15, v95, v95
	v_max_f32_e32 v48, v79, v79
	v_max_f32_e32 v15, v48, v15
	v_max3_f32 v0, v0, v14, v15
	v_mov_b32_e32 v14, v0
	s_nop 1
	v_permlane32_swap_b32_e32 v0, v14
	v_max_f32_e32 v14, v14, v14
	v_max_f32_e32 v0, v0, v0
	v_max_f32_e32 v171, v0, v14
	v_xor_b32_e32 v48, 0x80000000, v171
	v_sub_f32_e32 v79, v79, v171
	v_sub_f32_e32 v78, v78, v171
	v_sub_f32_e32 v77, v77, v171
	v_sub_f32_e32 v76, v76, v171
	v_sub_f32_e32 v75, v75, v171
	v_sub_f32_e32 v74, v74, v171
	v_sub_f32_e32 v73, v73, v171
	v_sub_f32_e32 v72, v72, v171
	v_sub_f32_e32 v71, v71, v171
	v_sub_f32_e32 v70, v70, v171
	v_sub_f32_e32 v69, v69, v171
	v_sub_f32_e32 v68, v68, v171
	v_sub_f32_e32 v67, v67, v171
	v_sub_f32_e32 v66, v66, v171
	v_sub_f32_e32 v65, v65, v171
	v_sub_f32_e32 v64, v64, v171
	v_sub_f32_e32 v95, v95, v171
	v_sub_f32_e32 v94, v94, v171
	v_sub_f32_e32 v93, v93, v171
	v_sub_f32_e32 v92, v92, v171
	v_sub_f32_e32 v91, v91, v171
	v_sub_f32_e32 v90, v90, v171
	v_sub_f32_e32 v89, v89, v171
	v_sub_f32_e32 v88, v88, v171
	v_sub_f32_e32 v87, v87, v171
	v_sub_f32_e32 v86, v86, v171
	v_sub_f32_e32 v85, v85, v171
	v_sub_f32_e32 v84, v84, v171
	v_sub_f32_e32 v83, v83, v171
	v_sub_f32_e32 v82, v82, v171
	v_sub_f32_e32 v81, v81, v171
	v_sub_f32_e32 v80, v80, v171
	v_mov_b32_e32 v49, v48
	v_mov_b32_e32 v50, v48
	v_mov_b32_e32 v51, v48
	v_mov_b32_e32 v52, v48
	v_mov_b32_e32 v53, v48
	v_mov_b32_e32 v54, v48
	v_mov_b32_e32 v55, v48
	v_mov_b32_e32 v56, v48
	v_mov_b32_e32 v57, v48
	v_mov_b32_e32 v58, v48
	v_mov_b32_e32 v59, v48
	v_mov_b32_e32 v60, v48
	v_mov_b32_e32 v61, v48
	v_mov_b32_e32 v62, v48
	v_mov_b32_e32 v63, v48

; __device__ __forceinline__ unsigned pk2(float lo, float hi) { f32x2 v = {lo, hi}; bf16x2_t b = __builtin_convertvector(v, bf16x2_t); return __builtin_bit_cast(unsigned, b); }
; template <int TYPE, int ND0, int KSTR> __device__ __forceinline__ void tile(LAS unsigned char* lds, int buf, int t, int w_lo, int w_hi, int n, int qrel, int lane, int r32, int hi,
;         const bf16x8 (&qr)[ND0], float& m_run, float& l_run, f32x16& o0, f32x16& o1, f32x16& negm) {
;     ...
; #pragma unroll
;     for (int ks = 0; ks < 4; ++ks) {
;         u32x4 pw;
;         if (ks < 2) { pw.x = pk2(p0[8 * ks], p0[8 * ks + 1]); pw.y = pk2(p0[8 * ks + 2], p0[8 * ks + 3]); pw.z = pk2(p0[8 * ks + 4], p0[8 * ks + 5]); pw.w = pk2(p0[8 * ks + 6], p0[8 * ks + 7]); }
;         else { const int k2 = ks - 2; pw.x = pk2(p1[8 * k2], p1[8 * k2 + 1]); pw.y = pk2(p1[8 * k2 + 2], p1[8 * k2 + 3]); pw.z = pk2(p1[8 * k2 + 4], p1[8 * k2 + 5]); pw.w = pk2(p1[8 * k2 + 6], p1[8 * k2 + 7]); }
;         const bf16x8 pb = __builtin_bit_cast(bf16x8, pw);
;         const bf16x8 va0 = __builtin_shufflevector(vf[ks][0], vf[ks][1], 0, 1, 2, 3, 4, 5, 6, 7), va1 = __builtin_shufflevector(vf[ks][2], vf[ks][3], 0, 1, 2, 3, 4, 5, 6, 7);
;         o0 = __builtin_amdgcn_mfma_f32_32x32x16_bf16(va0, pb, o0, 0, 0, 0);
;         o1 = __builtin_amdgcn_mfma_f32_32x32x16_bf16(va1, pb, o1, 0, 0, 0);
;     }
.LBB0_709:
	v_cvt_pk_bf16_f32 v208, v182, v0
	v_cvt_pk_bf16_f32 v209, v80, v196
	v_cvt_pk_bf16_f32 v210, v82, v198
	v_cvt_pk_bf16_f32 v211, v184, v202
	v_cvt_pk_bf16_f32 v80, v84, v200
	v_cvt_pk_bf16_f32 v81, v86, v204
	s_setprio 2
	v_mfma_f32_32x32x16_bf16 v[32:47], v[160:163], v[208:211], v[32:47]
	v_cvt_pk_bf16_f32 v82, v88, v206
	v_cvt_pk_bf16_f32 v83, v78, v220
	v_cvt_pk_bf16_f32 v78, v14, v186
	v_cvt_pk_bf16_f32 v79, v64, v188
	v_cvt_pk_bf16_f32 v64, v68, v192
	v_cvt_pk_bf16_f32 v65, v72, v90
	v_cvt_pk_bf16_f32 v67, v76, v94
	s_waitcnt lgkmcnt(12)
	v_mfma_f32_32x32x16_bf16 v[16:31], v[156:159], v[208:211], v[16:31]
	v_add_f32_e32 v166, v166, v222
	s_waitcnt lgkmcnt(10)
	v_mfma_f32_32x32x16_bf16 v[32:47], v[152:155], v[80:83], v[32:47]
	s_waitcnt lgkmcnt(8)
	v_mfma_f32_32x32x16_bf16 v[16:31], v[148:151], v[80:83], v[16:31]
	v_cvt_pk_bf16_f32 v80, v66, v190
	v_cvt_pk_bf16_f32 v81, v70, v194
	v_cvt_pk_bf16_f32 v66, v74, v92
	s_waitcnt lgkmcnt(6)
	v_mfma_f32_32x32x16_bf16 v[32:47], v[116:119], v[78:81], v[32:47]
	s_waitcnt lgkmcnt(4)
	v_mfma_f32_32x32x16_bf16 v[16:31], v[144:147], v[78:81], v[16:31]
	s_waitcnt lgkmcnt(2)
	v_mfma_f32_32x32x16_bf16 v[32:47], v[112:115], v[64:67], v[32:47]
	s_waitcnt lgkmcnt(0)
	v_mfma_f32_32x32x16_bf16 v[16:31], v[108:111], v[64:67], v[16:31]
	s_setprio 0

; #define LAS __attribute__((address_space(3)))
; __device__ __forceinline__ s16x4 vtr(const LAS unsigned char* p) { return __builtin_bit_cast(s16x4, __builtin_amdgcn_ds_read_tr16_b64_v4i16((LAS v4i16_t*)p)); }
; template <int TYPE, int ND0, int KSTR> __device__ __forceinline__ void tile(LAS unsigned char* lds, int buf, int t, int w_lo, int w_hi, int n, int qrel, int lane, int r32, int hi,
;         const bf16x8 (&qr)[ND0], float& m_run, float& l_run, f32x16& o0, f32x16& o1, f32x16& negm) {
;     const LAS unsigned char* kb = lds + KOFF + buf * KBUF + r32 * KSTR + hi * 16;
;     bf16x8 ka[ND0], kc[ND0];
; #pragma unroll
;     for (int d0 = 0; d0 < ND0; ++d0) { ka[d0] = *(const LAS bf16x8*)(kb + d0 * 32); kc[d0] = *(const LAS bf16x8*)(kb + 32 * KSTR + d0 * 32); }
;     const LAS unsigned char* vb = lds + VOFF + buf * VBUF + (4 * hi + ((lane & 15) >> 2)) * VSTR + (16 * ((lane >> 4) & 1) + 4 * (lane & 3)) * 2;
;     s16x4 vf[4][4];
; #pragma unroll
;     for (int ks = 0; ks < 4; ++ks) { vf[ks][0] = vtr(vb + (16 * ks) * VSTR); vf[ks][1] = vtr(vb + (16 * ks + 8) * VSTR); vf[ks][2] = vtr(vb + (16 * ks) * VSTR + 64); vf[ks][3] = vtr(vb + (16 * ks + 8) * VSTR + 64); }
;     f32x4 kbv[8];
;     if (TYPE == 0) { const LAS f32x4* kbi = (const LAS f32x4*)(lds + KBOFF + buf * 256);
; #pragma unroll
;         for (int g = 0; g < 4; ++g) { kbv[g] = kbi[2 * g + hi]; kbv[4 + g] = kbi[8 + 2 * g + hi]; } }
;     asm volatile("" ::: "memory");
;     const int rel = n - t;
;     f32x16 cin = negm;
;     if (TYPE == 2 && rel >= 5) { const float c = ((const LAS float*)(lds + RELOFF))[512];
; #pragma unroll
;         for (int r = 0; r < 16; ++r) cin[r] += c; }
;     f32x16 p0 = cin, p1 = cin;
; #pragma unroll
;     for (int d0 = 0; d0 < ND0; ++d0) {
;         p0 = __builtin_amdgcn_mfma_f32_32x32x16_bf16(ka[d0], qr[d0], p0, 0, 0, 0);
;         p1 = __builtin_amdgcn_mfma_f32_32x32x16_bf16(kc[d0], qr[d0], p1, 0, 0, 0);
;     }
;     ...
;     float ls = 0.f;
; #pragma unroll
;     for (int r = 0; r < 16; ++r) { p0[r] = __builtin_amdgcn_exp2f(p0[r]); p1[r] = __builtin_amdgcn_exp2f(p1[r]); ls += p0[r] + p1[r]; }
;     const float lrow = hsum(ls);
;     if (__builtin_amdgcn_ballot_w64(lrow > 1099511627776.0f) != 0ull) {
.LBB0_712:
	s_or_b64 exec, exec, s[6:7]
	s_mov_b32 s5, s45
	s_lshl_b64 s[6:7], s[4:5], 10
	v_lshl_add_u64 v[14:15], v[174:175], 0, s[6:7]
	v_lshl_add_u64 v[64:65], v[176:177], 0, s[6:7]
	s_lshl_b64 s[6:7], s[4:5], 6
	s_waitcnt lgkmcnt(0)
	s_barrier
	global_load_dwordx4 v[96:99], v[14:15], off
	global_load_dwordx4 v[104:107], v[64:65], off
	v_lshl_add_u64 v[14:15], v[180:181], 0, s[6:7]
	global_load_dwordx4 v[100:103], v[14:15], off
	s_cmp_ge_i32 s3, s9
	s_cbranch_scc1 .LBB0_716
	v_add_u32_e32 v0, v227, v170
	ds_read_b128 v[80:83], v0 offset:13312
	ds_read_b128 v[108:111], v0 offset:13344
	ds_read_b128 v[112:115], v0 offset:19968
	ds_read_b128 v[116:119], v0 offset:20000
	v_add_u32_e32 v15, v228, v229
	s_mov_b32 s5, 0x53800000
	s_waitcnt lgkmcnt(3)
	s_setprio 2
	v_mfma_f32_32x32x16_bf16 v[64:79], v[80:83], v[140:143], v[48:63]
	s_waitcnt lgkmcnt(1)
	v_mfma_f32_32x32x16_bf16 v[80:95], v[112:115], v[140:143], v[48:63]
	v_mfma_f32_32x32x16_bf16 v[64:79], v[108:111], v[136:139], v[64:79]
	ds_read_b128 v[108:111], v0 offset:13376
	ds_read_b128 v[112:115], v0 offset:13408
	s_waitcnt lgkmcnt(2)
	v_mfma_f32_32x32x16_bf16 v[80:95], v[116:119], v[136:139], v[80:95]
	s_waitcnt lgkmcnt(1)
	v_mfma_f32_32x32x16_bf16 v[64:79], v[108:111], v[132:135], v[64:79]
	ds_read_b128 v[108:111], v0 offset:20032
	ds_read_b128 v[116:119], v0 offset:20064
	s_waitcnt lgkmcnt(1)
	v_mfma_f32_32x32x16_bf16 v[80:95], v[108:111], v[132:135], v[80:95]
	v_mfma_f32_32x32x16_bf16 v[64:79], v[112:115], v[128:131], v[64:79]
	ds_read_b128 v[108:111], v0 offset:13440
	ds_read_b128 v[112:115], v0 offset:13472
	s_waitcnt lgkmcnt(2)
	v_mfma_f32_32x32x16_bf16 v[80:95], v[116:119], v[128:131], v[80:95]
	s_waitcnt lgkmcnt(1)
	v_mfma_f32_32x32x16_bf16 v[64:79], v[108:111], v[124:127], v[64:79]
	ds_read_b128 v[108:111], v0 offset:20096
	ds_read_b128 v[116:119], v0 offset:20128
	s_waitcnt lgkmcnt(1)
	v_mfma_f32_32x32x16_bf16 v[80:95], v[108:111], v[124:127], v[80:95]
	s_waitcnt vmcnt(6)
	v_mfma_f32_32x32x16_bf16 v[64:79], v[112:115], v[120:123], v[64:79]
	ds_read_b64_tr_b16 v[112:113], v15 offset:38912
	ds_read_b64_tr_b16 v[114:115], v15 offset:40448
	ds_read_b64_tr_b16 v[110:111], v15 offset:40512
	ds_read_b64_tr_b16 v[108:109], v15 offset:38976
	s_waitcnt lgkmcnt(4)
	v_mfma_f32_32x32x16_bf16 v[80:95], v[116:119], v[120:123], v[80:95]
	s_setprio 0
	s_nop 5
	v_exp_f32_e32 v146, v64
	v_exp_f32_e32 v190, v65
	v_exp_f32_e32 v148, v66
	v_exp_f32_e32 v194, v67
	v_exp_f32_e32 v150, v68
	v_exp_f32_e32 v198, v69
	v_exp_f32_e32 v154, v70
	v_exp_f32_e32 v14, v80
	v_exp_f32_e32 v0, v81
	v_exp_f32_e32 v116, v82
	v_exp_f32_e32 v118, v84
	v_add_f32_e32 v191, v146, v14
	v_pk_add_f32 v[64:65], v[190:191], v[0:1]
	v_add_f32_e32 v195, v148, v116
	v_pk_add_f32 v[162:163], v[64:65], v[64:65] op_sel_hi:[0,1]
	v_exp_f32_e32 v162, v83
	v_add_f32_e32 v199, v150, v118
	v_exp_f32_e32 v144, v86
	v_exp_f32_e32 v200, v71
	v_pk_add_f32 v[64:65], v[194:195], v[162:163]
	v_exp_f32_e32 v152, v72
	v_pk_add_f32 v[182:183], v[64:65], v[64:65] op_sel_hi:[0,1]
	v_exp_f32_e32 v182, v85
	v_add_f32_e32 v201, v154, v144
	v_exp_f32_e32 v88, v88
	v_exp_f32_e32 v202, v73
	v_pk_add_f32 v[64:65], v[198:199], v[182:183]
	v_exp_f32_e32 v156, v74
	v_pk_add_f32 v[184:185], v[64:65], v[64:65] op_sel_hi:[0,1]
	v_exp_f32_e32 v184, v87
	v_add_f32_e32 v203, v152, v88
	v_exp_f32_e32 v90, v90
	v_exp_f32_e32 v204, v75
	v_pk_add_f32 v[64:65], v[200:201], v[184:185]
	v_exp_f32_e32 v158, v76
	v_pk_add_f32 v[186:187], v[64:65], v[64:65] op_sel_hi:[0,1]
	v_exp_f32_e32 v186, v89
	v_add_f32_e32 v205, v156, v90
	v_exp_f32_e32 v92, v92
	v_exp_f32_e32 v206, v77
	v_pk_add_f32 v[64:65], v[202:203], v[186:187]
	v_exp_f32_e32 v160, v78
	v_pk_add_f32 v[188:189], v[64:65], v[64:65] op_sel_hi:[0,1]
	v_exp_f32_e32 v188, v91
	v_add_f32_e32 v207, v158, v92
	v_exp_f32_e32 v94, v94
	v_exp_f32_e32 v220, v79
	v_pk_add_f32 v[72:73], v[204:205], v[188:189]
	ds_read_b64_tr_b16 v[84:85], v15 offset:41984
	ds_read_b64_tr_b16 v[86:87], v15 offset:43520
	ds_read_b64_tr_b16 v[82:83], v15 offset:43584
	ds_read_b64_tr_b16 v[80:81], v15 offset:42048
	v_pk_add_f32 v[192:193], v[72:73], v[72:73] op_sel_hi:[0,1]
	v_exp_f32_e32 v192, v93
	ds_read_b64_tr_b16 v[68:69], v15 offset:45056
	ds_read_b64_tr_b16 v[70:71], v15 offset:46592
	ds_read_b64_tr_b16 v[66:67], v15 offset:46656
	ds_read_b64_tr_b16 v[64:65], v15 offset:45120
	v_add_f32_e32 v221, v160, v94
	v_pk_add_f32 v[72:73], v[206:207], v[192:193]
	s_nop 0
	v_pk_add_f32 v[196:197], v[72:73], v[72:73] op_sel_hi:[0,1]
	v_exp_f32_e32 v196, v95
	ds_read_b64_tr_b16 v[76:77], v15 offset:48128
	ds_read_b64_tr_b16 v[78:79], v15 offset:49664
	ds_read_b64_tr_b16 v[74:75], v15 offset:49728
	ds_read_b64_tr_b16 v[72:73], v15 offset:48192
	v_pk_add_f32 v[208:209], v[220:221], v[196:197]
	s_nop 0
	v_pk_add_f32 v[222:223], v[208:209], v[208:209] op_sel:[0,1] op_sel_hi:[1,0]
	s_nop 0
	v_mov_b32_e32 v15, v222
	v_mov_b32_e32 v89, v222
	s_nop 1
	v_permlane32_swap_b32_e32 v15, v89
	v_add_f32_e32 v15, v15, v89
	v_cmp_lt_f32_e32 vcc, s5, v15
	s_cbranch_vccz .LBB0_715
; __device__ __forceinline__ unsigned pk2(float lo, float hi) { f32x2 v = {lo, hi}; bf16x2_t b = __builtin_convertvector(v, bf16x2_t); return __builtin_bit_cast(unsigned, b); }
; __device__ __forceinline__ float hmax(float m) { auto rr = __builtin_amdgcn_permlane32_swap(__float_as_uint(m), __float_as_uint(m), false, false); return fmaxf(__uint_as_float(rr[0]), __uint_as_float(rr[1])); }
; template <int TYPE, int ND0, int KSTR> __device__ __forceinline__ void tile(LAS unsigned char* lds, int buf, int t, int w_lo, int w_hi, int n, int qrel, int lane, int r32, int hi,
;         const bf16x8 (&qr)[ND0], float& m_run, float& l_run, f32x16& o0, f32x16& o1, f32x16& negm) {
;     ...
;     if (__builtin_amdgcn_ballot_w64(lrow > 1099511627776.0f) != 0ull) {
;         float pm = fmaxf(p0[0], p1[0]);
; #pragma unroll
;         for (int r = 1; r < 16; ++r) pm = fmaxf(pm, fmaxf(p0[r], p1[r]));
;         pm = hmax(pm);
;         const float dl = (lrow > 1099511627776.0f) ? __builtin_amdgcn_logf(pm) : 0.f;
;         const float sc = __builtin_amdgcn_exp2f(-dl);
;         m_run += dl; l_run *= sc; ls *= sc;
; #pragma unroll
;         for (int r = 0; r < 16; ++r) { p0[r] *= sc; p1[r] *= sc; o0[r] *= sc; o1[r] *= sc; negm[r] = -m_run; }
;     }
;     l_run += ls;
; #pragma unroll
;     for (int ks = 0; ks < 4; ++ks) {
;         u32x4 pw;
;         if (ks < 2) { pw.x = pk2(p0[8 * ks], p0[8 * ks + 1]); pw.y = pk2(p0[8 * ks + 2], p0[8 * ks + 3]); pw.z = pk2(p0[8 * ks + 4], p0[8 * ks + 5]); pw.w = pk2(p0[8 * ks + 6], p0[8 * ks + 7]); }
;         else { const int k2 = ks - 2; pw.x = pk2(p1[8 * k2], p1[8 * k2 + 1]); pw.y = pk2(p1[8 * k2 + 2], p1[8 * k2 + 3]); pw.z = pk2(p1[8 * k2 + 4], p1[8 * k2 + 5]); pw.w = pk2(p1[8 * k2 + 6], p1[8 * k2 + 7]); }
;         const bf16x8 pb = __builtin_bit_cast(bf16x8, pw);
;         const bf16x8 va0 = __builtin_shufflevector(vf[ks][0], vf[ks][1], 0, 1, 2, 3, 4, 5, 6, 7), va1 = __builtin_shufflevector(vf[ks][2], vf[ks][3], 0, 1, 2, 3, 4, 5, 6, 7);
;         o0 = __builtin_amdgcn_mfma_f32_32x32x16_bf16(va0, pb, o0, 0, 0, 0);
;         o1 = __builtin_amdgcn_mfma_f32_32x32x16_bf16(va1, pb, o1, 0, 0, 0);
;     }
	v_max_f32_e32 v15, v0, v0
	v_max_f32_e32 v48, v190, v190
	v_max_f32_e32 v15, v48, v15
	v_max_f32_e32 v48, v116, v116
	v_max_f32_e32 v49, v148, v148
	v_max_f32_e32 v48, v49, v48
	v_max_f32_e32 v49, v162, v162
	v_max_f32_e32 v50, v194, v194
	v_max3_f32 v15, v146, v14, v15
	v_max_f32_e32 v49, v50, v49
	v_max3_f32 v15, v15, v48, v49
	v_max_f32_e32 v48, v118, v118
	v_max_f32_e32 v49, v150, v150
	v_max_f32_e32 v48, v49, v48
	v_max_f32_e32 v49, v182, v182
	v_max_f32_e32 v50, v198, v198
	v_max_f32_e32 v49, v50, v49
	v_max3_f32 v15, v15, v48, v49
	v_max_f32_e32 v48, v144, v144
	v_max_f32_e32 v49, v154, v154
	v_max_f32_e32 v48, v49, v48
	v_max_f32_e32 v49, v184, v184
	v_max_f32_e32 v50, v200, v200
	v_max_f32_e32 v49, v50, v49
	v_max3_f32 v15, v15, v48, v49
	v_max_f32_e32 v48, v88, v88
	v_max_f32_e32 v49, v152, v152
	v_max_f32_e32 v48, v49, v48
	v_max_f32_e32 v49, v186, v186
	v_max_f32_e32 v50, v202, v202
	v_max_f32_e32 v49, v50, v49
	v_max3_f32 v15, v15, v48, v49
	v_max_f32_e32 v48, v90, v90
	v_max_f32_e32 v49, v156, v156
	v_max_f32_e32 v48, v49, v48
	v_max_f32_e32 v49, v188, v188
	v_max_f32_e32 v50, v204, v204
	v_max_f32_e32 v49, v50, v49
	v_max3_f32 v15, v15, v48, v49
	v_max_f32_e32 v48, v92, v92
	v_max_f32_e32 v49, v158, v158
	v_max_f32_e32 v48, v49, v48
	v_max_f32_e32 v49, v192, v192
	v_max_f32_e32 v50, v206, v206
	v_max_f32_e32 v49, v50, v49
	v_max3_f32 v15, v15, v48, v49
	v_max_f32_e32 v48, v94, v94
	v_max_f32_e32 v49, v160, v160
	v_max_f32_e32 v48, v49, v48
	v_max_f32_e32 v49, v196, v196
	v_max_f32_e32 v50, v220, v220
	v_max_f32_e32 v49, v50, v49
	v_max3_f32 v15, v15, v48, v49
	v_mov_b32_e32 v48, v15
	s_nop 1
	v_permlane32_swap_b32_e32 v15, v48
	v_max_f32_e32 v48, v48, v48
	v_max_f32_e32 v15, v15, v15
	v_max_f32_e32 v15, v15, v48
	v_log_f32_e32 v15, v15
	v_mov_b32_e32 v167, v222
	v_mov_b32_e32 v161, v220
	v_mov_b32_e32 v159, v206
	v_cndmask_b32_e32 v15, 0, v15, vcc
	v_exp_f32_e64 v208, -v15
	v_add_f32_e32 v171, v171, v15
	v_mov_b32_e32 v157, v204
	v_mov_b32_e32 v153, v202
	v_mov_b32_e32 v155, v200
	v_mov_b32_e32 v151, v198
	v_mov_b32_e32 v149, v194
	v_mov_b32_e32 v147, v190
	v_mov_b32_e32 v95, v196
	v_mov_b32_e32 v93, v192
	v_mov_b32_e32 v91, v188
	v_mov_b32_e32 v89, v186
	v_mov_b32_e32 v145, v184
	v_mov_b32_e32 v119, v182
	v_mov_b32_e32 v117, v162
	v_mov_b32_e32 v15, v0
	v_xor_b32_e32 v48, 0x80000000, v171
	v_pk_mul_f32 v[160:161], v[160:161], v[208:209] op_sel_hi:[1,0]
	v_pk_mul_f32 v[158:159], v[158:159], v[208:209] op_sel_hi:[1,0]
	v_pk_mul_f32 v[156:157], v[156:157], v[208:209] op_sel_hi:[1,0]
	v_pk_mul_f32 v[152:153], v[152:153], v[208:209] op_sel_hi:[1,0]
	v_pk_mul_f32 v[154:155], v[154:155], v[208:209] op_sel_hi:[1,0]
	v_pk_mul_f32 v[150:151], v[150:151], v[208:209] op_sel_hi:[1,0]
	v_pk_mul_f32 v[148:149], v[148:149], v[208:209] op_sel_hi:[1,0]
	v_pk_mul_f32 v[146:147], v[146:147], v[208:209] op_sel_hi:[1,0]
	v_pk_mul_f32 v[94:95], v[94:95], v[208:209] op_sel_hi:[1,0]
	v_pk_mul_f32 v[92:93], v[92:93], v[208:209] op_sel_hi:[1,0]
	v_pk_mul_f32 v[90:91], v[90:91], v[208:209] op_sel_hi:[1,0]
	v_pk_mul_f32 v[88:89], v[88:89], v[208:209] op_sel_hi:[1,0]
	v_pk_mul_f32 v[144:145], v[144:145], v[208:209] op_sel_hi:[1,0]
	v_pk_mul_f32 v[118:119], v[118:119], v[208:209] op_sel_hi:[1,0]
	v_pk_mul_f32 v[116:117], v[116:117], v[208:209] op_sel_hi:[1,0]
	v_pk_mul_f32 v[14:15], v[14:15], v[208:209] op_sel_hi:[1,0]
	v_pk_mul_f32 v[166:167], v[166:167], v[208:209] op_sel_hi:[1,0]
	v_pk_mul_f32 v[46:47], v[46:47], v[208:209] op_sel_hi:[1,0]
	v_pk_mul_f32 v[44:45], v[44:45], v[208:209] op_sel_hi:[1,0]
	v_pk_mul_f32 v[42:43], v[42:43], v[208:209] op_sel_hi:[1,0]
	v_pk_mul_f32 v[40:41], v[40:41], v[208:209] op_sel_hi:[1,0]
	v_pk_mul_f32 v[38:39], v[38:39], v[208:209] op_sel_hi:[1,0]
	v_pk_mul_f32 v[36:37], v[36:37], v[208:209] op_sel_hi:[1,0]
	v_pk_mul_f32 v[34:35], v[34:35], v[208:209] op_sel_hi:[1,0]
	v_pk_mul_f32 v[32:33], v[32:33], v[208:209] op_sel_hi:[1,0]
	v_pk_mul_f32 v[30:31], v[30:31], v[208:209] op_sel_hi:[1,0]
	v_pk_mul_f32 v[28:29], v[28:29], v[208:209] op_sel_hi:[1,0]
	v_pk_mul_f32 v[26:27], v[26:27], v[208:209] op_sel_hi:[1,0]
	v_pk_mul_f32 v[24:25], v[24:25], v[208:209] op_sel_hi:[1,0]
	v_pk_mul_f32 v[22:23], v[22:23], v[208:209] op_sel_hi:[1,0]
	v_pk_mul_f32 v[20:21], v[20:21], v[208:209] op_sel_hi:[1,0]
	v_pk_mul_f32 v[18:19], v[18:19], v[208:209] op_sel_hi:[1,0]
	v_pk_mul_f32 v[16:17], v[16:17], v[208:209] op_sel_hi:[1,0]
	v_mov_b32_e32 v49, v48
	v_mov_b32_e32 v50, v48
	v_mov_b32_e32 v51, v48
	v_mov_b32_e32 v52, v48
	v_mov_b32_e32 v53, v48
	v_mov_b32_e32 v54, v48
	v_mov_b32_e32 v55, v48
	v_mov_b32_e32 v56, v48
	v_mov_b32_e32 v57, v48
	v_mov_b32_e32 v58, v48
	v_mov_b32_e32 v59, v48
	v_mov_b32_e32 v60, v48
	v_mov_b32_e32 v61, v48
	v_mov_b32_e32 v62, v48
	v_mov_b32_e32 v63, v48
	v_mov_b32_e32 v0, v15
	v_mov_b32_e32 v162, v117
	v_mov_b32_e32 v182, v119
	v_mov_b32_e32 v184, v145
	v_mov_b32_e32 v186, v89
	v_mov_b32_e32 v188, v91
	v_mov_b32_e32 v192, v93
	v_mov_b32_e32 v196, v95
	v_mov_b32_e32 v190, v147
	v_mov_b32_e32 v194, v149
	v_mov_b32_e32 v198, v151
	v_mov_b32_e32 v200, v155
	v_mov_b32_e32 v202, v153
	v_mov_b32_e32 v204, v157
	v_mov_b32_e32 v206, v159
	v_mov_b32_e32 v220, v161
	v_mov_b32_e32 v222, v167
.LBB0_715:
	v_cvt_pk_bf16_f32 v146, v146, v190
	v_cvt_pk_bf16_f32 v147, v148, v194
	v_cvt_pk_bf16_f32 v148, v150, v198
	v_cvt_pk_bf16_f32 v149, v154, v200
	v_add_f32_e32 v166, v166, v222
	s_waitcnt lgkmcnt(14)
	s_setprio 2
	v_mfma_f32_32x32x16_bf16 v[32:47], v[112:115], v[146:149], v[32:47]
	s_waitcnt lgkmcnt(12)
	v_mfma_f32_32x32x16_bf16 v[16:31], v[108:111], v[146:149], v[16:31]
	v_cvt_pk_bf16_f32 v108, v152, v202
	v_cvt_pk_bf16_f32 v109, v156, v204
	v_cvt_pk_bf16_f32 v110, v158, v206
	v_cvt_pk_bf16_f32 v111, v160, v220
	s_waitcnt lgkmcnt(10)
	s_nop 0
	v_mfma_f32_32x32x16_bf16 v[32:47], v[84:87], v[108:111], v[32:47]
	s_waitcnt lgkmcnt(8)
	v_mfma_f32_32x32x16_bf16 v[16:31], v[80:83], v[108:111], v[16:31]
	v_cvt_pk_bf16_f32 v80, v14, v0
	v_cvt_pk_bf16_f32 v81, v116, v162
	v_cvt_pk_bf16_f32 v82, v118, v182
	v_cvt_pk_bf16_f32 v83, v144, v184
	s_waitcnt lgkmcnt(6)
	s_nop 0
	v_mfma_f32_32x32x16_bf16 v[32:47], v[68:71], v[80:83], v[32:47]
	s_waitcnt lgkmcnt(4)
	v_mfma_f32_32x32x16_bf16 v[16:31], v[64:67], v[80:83], v[16:31]
	v_cvt_pk_bf16_f32 v64, v88, v186
	v_cvt_pk_bf16_f32 v65, v90, v188
	v_cvt_pk_bf16_f32 v66, v92, v192
	v_cvt_pk_bf16_f32 v67, v94, v196
	s_waitcnt lgkmcnt(2)
	s_nop 0
	v_mfma_f32_32x32x16_bf16 v[32:47], v[76:79], v[64:67], v[32:47]
	s_waitcnt lgkmcnt(0)
	v_mfma_f32_32x32x16_bf16 v[16:31], v[72:75], v[64:67], v[16:31]
	s_setprio 0

; template <int TYPE, int ND0, int KSTR> __device__ __forceinline__ void tile(LAS unsigned char* lds, int buf, int t, int w_lo, int w_hi, int n, int qrel, int lane, int r32, int hi,
;         const bf16x8 (&qr)[ND0], float& m_run, float& l_run, f32x16& o0, f32x16& o1, f32x16& negm) {
;     const LAS unsigned char* kb = lds + KOFF + buf * KBUF + r32 * KSTR + hi * 16;
;     bf16x8 ka[ND0], kc[ND0];
; #pragma unroll
;     for (int d0 = 0; d0 < ND0; ++d0) { ka[d0] = *(const LAS bf16x8*)(kb + d0 * 32); kc[d0] = *(const LAS bf16x8*)(kb + 32 * KSTR + d0 * 32); }
;     const LAS unsigned char* vb = lds + VOFF + buf * VBUF + (4 * hi + ((lane & 15) >> 2)) * VSTR + (16 * ((lane >> 4) & 1) + 4 * (lane & 3)) * 2;
;     s16x4 vf[4][4];
; #pragma unroll
;     for (int ks = 0; ks < 4; ++ks) { vf[ks][0] = vtr(vb + (16 * ks) * VSTR); vf[ks][1] = vtr(vb + (16 * ks + 8) * VSTR); vf[ks][2] = vtr(vb + (16 * ks) * VSTR + 64); vf[ks][3] = vtr(vb + (16 * ks + 8) * VSTR + 64); }
;     f32x4 kbv[8];
;     if (TYPE == 0) { const LAS f32x4* kbi = (const LAS f32x4*)(lds + KBOFF + buf * 256);
; #pragma unroll
;         for (int g = 0; g < 4; ++g) { kbv[g] = kbi[2 * g + hi]; kbv[4 + g] = kbi[8 + 2 * g + hi]; } }
; template <int TYPE> __device__ __forceinline__ int unit(const P& p, LAS unsigned char* lds, int b, int h, int qb, int wave0, bool pre, unsigned nx, int G,
;         u32x4& kA, u32x4& vA, u32x4& k2A, float& cbA, u32x4& kB, u32x4& vB, u32x4& k2B, float& cbB) {
;     ...
;     const int inext = tk[0];
;     {
;         const bool nval = inext < 1536; const int ii = nval ? inext : 0;
;         const int nqb = 7 - ii / 192, nrem = ii % 192, nq = nrem / 64, nbh = nrem % 64, nb = nbh >> 3, nh = nbh & 7;
;         const int nT = (nq == 0) ? 1 : (nq == 1) ? 0 : 2;
;         const int nlo = (nT == 2) ? (4 * nqb - 8 > 0 ? 4 * nqb - 8 : 0) : 0;
;         const bf16* nKp = (nT == 0) ? p.KA : (nT == 1) ? p.KBN : p.KC; const bf16* nVp = (nT == 0) ? p.VA : (nT == 1) ? p.VB : p.VC;
;         const size_t nrow = (size_t)nb * SEQ + (size_t)nlo * 64;
;         const bf16* nk = nKp + (nrow + srow) * 512 + nh * 64 + sch * 8; const bf16* nv = nVp + (nrow + srow) * 512 + nh * 64 + sch * 8;
;         const bf16* nkr = p.KR + (nrow + ((tid & 255) >> 2)) * 32 + (tid & 3) * 8; const float* ncg = p.cum + (size_t)(nb * 8 + nh) * SEQ + nlo * 64 + (tid & 63);
;         ATT_LOAD_NEXT(0, A);
.LBB0_722:
	ds_read_b32 v64, v1 offset:54144
	v_readlane_b32 s22, v254, 61
	v_readlane_b32 s23, v254, 62
	v_readlane_b32 s24, v254, 63
	v_readlane_b32 s25, v255, 0
	s_waitcnt lgkmcnt(0)
	v_readfirstlane_b32 s2, v64
	s_cmpk_lt_i32 s2, 0x600
	s_cselect_b32 s2, s2, 0
	s_mul_hi_i32 s4, s2, 0x2aaaaaab
	s_lshr_b32 s7, s4, 31
	s_lshr_b32 s4, s4, 5
	s_mul_hi_i32 s3, s2, 0xd5555555
	s_add_i32 s4, s4, s7
	s_lshr_b32 s5, s3, 31
	s_ashr_i32 s3, s3, 5
	s_mulk_i32 s4, 0xc0
	s_add_i32 s3, s3, s5
	s_sub_i32 s5, s2, s4
	s_bfe_u32 s2, s5, 0x60019
	s_add_i32 s2, s5, s2
	s_and_b32 s2, s2, 0xffc0
	s_sub_i32 s2, s5, s2
	s_lshl_b32 s3, s3, 2
	s_sext_i32_i16 s7, s2
	s_max_i32 s3, s3, 0xffffffec
	s_ashr_i32 s4, s7, 3
	s_sub_i32 s10, s5, 64
	s_add_i32 s11, s5, 0xffffff80
	s_add_i32 s3, s3, 20
	s_cmp_lt_u32 s11, 0xffffff41
	s_cselect_b32 s44, s3, 0
	s_andn2_b32 s5, s5, 63
	s_cmp_lt_u32 s10, 0xffffff81
	v_readlane_b32 s10, v254, 36
	v_readlane_b32 s11, v254, 37
	s_cselect_b32 s3, s22, s10
	s_cselect_b32 s10, s23, s11
	v_readlane_b32 s22, v254, 38
	v_readlane_b32 s23, v254, 39
	s_cselect_b32 s22, s24, s22
	s_cselect_b32 s23, s25, s23
	v_readlane_b32 s24, v254, 53
	s_cmp_eq_u32 s5, 64
	v_readlane_b32 s25, v254, 54
	s_cselect_b32 s11, s25, s10
	s_cselect_b32 s10, s24, s3
	v_readlane_b32 s24, v254, 55
	v_readlane_b32 s25, v254, 56
	s_cselect_b32 s23, s25, s23
	s_cselect_b32 s22, s24, s22
	s_ashr_i32 s5, s4, 31
	s_lshl_b64 s[4:5], s[4:5], 11
	s_lshl_b64 s[24:25], s[44:45], 6
	s_add_u32 s4, s4, s24
	s_addc_u32 s5, s5, s25
	s_waitcnt vmcnt(3)
	v_lshl_add_u64 v[2:3], s[4:5], 0, v[172:173]
	v_lshlrev_b64 v[2:3], 10, v[2:3]
	s_lshl_b32 s3, s7, 7
	v_lshl_add_u64 v[4:5], s[10:11], 0, v[2:3]
	s_and_b32 s10, s3, 0x380
	s_mov_b32 s11, s45
	v_lshl_add_u64 v[2:3], s[22:23], 0, v[2:3]
	v_lshlrev_b32_e32 v0, 1, v231
	v_lshl_add_u64 v[2:3], v[2:3], 0, s[10:11]
	v_lshl_add_u64 v[14:15], v[2:3], 0, v[0:1]
	v_mov_b32_e32 v3, s5
	v_or_b32_e32 v2, s4, v179
	v_readlane_b32 s4, v254, 40
	v_lshlrev_b64 v[2:3], 6, v[2:3]
	v_readlane_b32 s5, v254, 41
	s_bfe_i64 s[2:3], s[2:3], 0x100000
	s_lshl_b64 s[2:3], s[2:3], 13
	v_lshl_add_u64 v[2:3], s[4:5], 0, v[2:3]
	v_readlane_b32 s4, v254, 42
	s_add_u32 s4, s4, s2
	v_readlane_b32 s2, v254, 50
	s_addc_u32 s5, s2, s3
	s_lshl_b32 s44, s44, 6
	v_lshl_add_u64 v[4:5], v[4:5], 0, s[10:11]
	s_lshl_b64 s[2:3], s[44:45], 2
	v_lshl_add_u64 v[118:119], v[4:5], 0, v[0:1]
	v_lshlrev_b32_e32 v0, 1, v230
	s_add_u32 s4, s4, s2
	v_lshl_add_u64 v[116:117], v[2:3], 0, v[0:1]
	s_addc_u32 s5, s5, s3
	v_lshlrev_b32_e32 v144, 2, v178
	global_load_dwordx4 v[2:5], v[118:119], off
	global_load_dwordx4 v[6:9], v[14:15], off
	global_load_dwordx4 v[10:13], v[116:117], off
	global_load_dword v239, v144, s[4:5]
	v_readfirstlane_b32 s25, v64
	s_cmp_gt_i32 s6, s9
	v_add_u32_e32 v220, v227, v170
	v_add_u32_e32 v219, v228, v229
	s_cbranch_scc1 .LBB0_726
	ds_read_b128 v[80:83], v220
	ds_read_b128 v[108:111], v220 offset:32
	ds_read_b128 v[112:115], v220 offset:6656
	ds_read_b128 v[146:149], v220 offset:6688
	s_mov_b32 s2, 0x53800000
	s_waitcnt lgkmcnt(3)
	s_setprio 2
	v_mfma_f32_32x32x16_bf16 v[64:79], v[80:83], v[140:143], v[48:63]
	s_waitcnt lgkmcnt(1)
	v_mfma_f32_32x32x16_bf16 v[80:95], v[112:115], v[140:143], v[48:63]
	v_mfma_f32_32x32x16_bf16 v[64:79], v[108:111], v[136:139], v[64:79]
	ds_read_b128 v[108:111], v220 offset:64
	ds_read_b128 v[112:115], v220 offset:96
	s_waitcnt lgkmcnt(2)
	v_mfma_f32_32x32x16_bf16 v[80:95], v[146:149], v[136:139], v[80:95]
	s_waitcnt lgkmcnt(1)
	v_mfma_f32_32x32x16_bf16 v[64:79], v[108:111], v[132:135], v[64:79]
	ds_read_b128 v[108:111], v220 offset:6720
	ds_read_b128 v[146:149], v220 offset:6752
	s_waitcnt lgkmcnt(1)
	v_mfma_f32_32x32x16_bf16 v[80:95], v[108:111], v[132:135], v[80:95]
	v_mfma_f32_32x32x16_bf16 v[64:79], v[112:115], v[128:131], v[64:79]
	ds_read_b128 v[108:111], v220 offset:128
	ds_read_b128 v[112:115], v220 offset:160
	s_waitcnt lgkmcnt(2)
	v_mfma_f32_32x32x16_bf16 v[80:95], v[146:149], v[128:131], v[80:95]
	s_waitcnt lgkmcnt(1)
	v_mfma_f32_32x32x16_bf16 v[64:79], v[108:111], v[124:127], v[64:79]
	ds_read_b128 v[108:111], v220 offset:6784
	ds_read_b128 v[146:149], v220 offset:6816
	s_waitcnt lgkmcnt(1)
	v_mfma_f32_32x32x16_bf16 v[80:95], v[108:111], v[124:127], v[80:95]
	v_mfma_f32_32x32x16_bf16 v[64:79], v[112:115], v[120:123], v[64:79]
	ds_read_b64_tr_b16 v[112:113], v219 offset:26624
	ds_read_b64_tr_b16 v[114:115], v219 offset:28160
	ds_read_b64_tr_b16 v[110:111], v219 offset:28224
	ds_read_b64_tr_b16 v[108:109], v219 offset:26688
	s_waitcnt lgkmcnt(4)
; #define LAS __attribute__((address_space(3)))
; __device__ __forceinline__ int crow(int r, int hi) { return (r & 3) + 8 * (r >> 2) + 4 * hi; }
; __device__ __forceinline__ float hmax(float m) { auto rr = __builtin_amdgcn_permlane32_swap(__float_as_uint(m), __float_as_uint(m), false, false); return fmaxf(__uint_as_float(rr[0]), __uint_as_float(rr[1])); }
; __device__ __forceinline__ float hsum(float m) { auto rr = __builtin_amdgcn_permlane32_swap(__float_as_uint(m), __float_as_uint(m), false, false); return __uint_as_float(rr[0]) + __uint_as_float(rr[1]); }
; template <int TYPE, int ND0, int KSTR> __device__ __forceinline__ void tile(LAS unsigned char* lds, int buf, int t, int w_lo, int w_hi, int n, int qrel, int lane, int r32, int hi,
;         const bf16x8 (&qr)[ND0], float& m_run, float& l_run, f32x16& o0, f32x16& o1, f32x16& negm) {
;     ...
;         p0 = __builtin_amdgcn_mfma_f32_32x32x16_bf16(ka[d0], qr[d0], p0, 0, 0, 0);
;         p1 = __builtin_amdgcn_mfma_f32_32x32x16_bf16(kc[d0], qr[d0], p1, 0, 0, 0);
;     }
;     if (TYPE == 0) {
; #pragma unroll
;         for (int g = 0; g < 4; ++g)
; #pragma unroll
;             for (int j = 0; j < 4; ++j) { p0[4 * g + j] += kbv[g][j]; p1[4 * g + j] += kbv[4 + g][j]; }
;         if (t == w_hi) {
; #pragma unroll
;             for (int r = 0; r < 16; ++r) { const int kr_ = crow(r, hi); if (kr_ > qrel) p0[r] = -1e30f; if (kr_ + 32 > qrel) p1[r] = -1e30f; }
;         }
;     }
;     if (TYPE == 2 && rel < 5) {
;         const LAS float* rb = (const LAS float*)(lds + RELOFF) + (qrel + 64 * rel + 256 - 4 * hi - 59);
; #pragma unroll
;         for (int r = 0; r < 16; ++r) { p0[r] += rb[59 - ((r & 3) + 8 * (r >> 2))]; p1[r] += rb[27 - ((r & 3) + 8 * (r >> 2))]; }
;     }
;     if (t == w_lo) {
;         float mx = fmaxf(p0[0], p1[0]);
; #pragma unroll
;         for (int r = 1; r < 16; ++r) mx = fmaxf(mx, fmaxf(p0[r], p1[r]));
;         mx = hmax(mx); m_run = mx;
; #pragma unroll
;         for (int r = 0; r < 16; ++r) { p0[r] -= mx; p1[r] -= mx; negm[r] = -mx; }
;     }
;     float ls = 0.f;
; #pragma unroll
;     for (int r = 0; r < 16; ++r) { p0[r] = __builtin_amdgcn_exp2f(p0[r]); p1[r] = __builtin_amdgcn_exp2f(p1[r]); ls += p0[r] + p1[r]; }
;     const float lrow = hsum(ls);
	v_mfma_f32_32x32x16_bf16 v[80:95], v[146:149], v[120:123], v[80:95]
	s_setprio 0
	s_nop 5
	v_exp_f32_e32 v154, v64
	v_exp_f32_e32 v186, v65
	v_exp_f32_e32 v156, v66
	v_exp_f32_e32 v190, v67
	v_exp_f32_e32 v158, v68
	v_exp_f32_e32 v194, v69
	v_exp_f32_e32 v162, v70
	v_exp_f32_e32 v146, v80
	v_exp_f32_e32 v0, v81
	v_exp_f32_e32 v148, v82
	v_exp_f32_e32 v150, v84
	v_add_f32_e32 v187, v154, v146
	v_pk_add_f32 v[64:65], v[186:187], v[0:1]
	v_add_f32_e32 v191, v156, v148
	v_pk_add_f32 v[176:177], v[64:65], v[64:65] op_sel_hi:[0,1]
	v_exp_f32_e32 v176, v83
	v_add_f32_e32 v195, v158, v150
	v_exp_f32_e32 v152, v86
	v_exp_f32_e32 v196, v71
	v_pk_add_f32 v[64:65], v[190:191], v[176:177]
	v_exp_f32_e32 v160, v72
	v_pk_add_f32 v[178:179], v[64:65], v[64:65] op_sel_hi:[0,1]
	v_exp_f32_e32 v178, v85
	v_add_f32_e32 v197, v162, v152
	v_exp_f32_e32 v88, v88
	v_exp_f32_e32 v198, v73
	v_pk_add_f32 v[64:65], v[194:195], v[178:179]
	v_exp_f32_e32 v170, v74
	v_pk_add_f32 v[180:181], v[64:65], v[64:65] op_sel_hi:[0,1]
	v_exp_f32_e32 v180, v87
	v_add_f32_e32 v199, v160, v88
	v_exp_f32_e32 v90, v90
	v_exp_f32_e32 v200, v75
	v_pk_add_f32 v[64:65], v[196:197], v[180:181]
	v_exp_f32_e32 v172, v76
	v_pk_add_f32 v[182:183], v[64:65], v[64:65] op_sel_hi:[0,1]
	v_exp_f32_e32 v182, v89
	v_add_f32_e32 v201, v170, v90
	v_exp_f32_e32 v92, v92
	v_exp_f32_e32 v202, v77
	v_pk_add_f32 v[64:65], v[198:199], v[182:183]
	v_exp_f32_e32 v174, v78
	v_pk_add_f32 v[184:185], v[64:65], v[64:65] op_sel_hi:[0,1]
	v_exp_f32_e32 v184, v91
	v_add_f32_e32 v203, v172, v92
	v_exp_f32_e32 v94, v94
	v_exp_f32_e32 v204, v79
	v_pk_add_f32 v[72:73], v[200:201], v[184:185]
	ds_read_b64_tr_b16 v[84:85], v219 offset:29696
	ds_read_b64_tr_b16 v[86:87], v219 offset:31232
	ds_read_b64_tr_b16 v[82:83], v219 offset:31296
	ds_read_b64_tr_b16 v[80:81], v219 offset:29760
	v_pk_add_f32 v[188:189], v[72:73], v[72:73] op_sel_hi:[0,1]
	v_exp_f32_e32 v188, v93
	ds_read_b64_tr_b16 v[68:69], v219 offset:32768
	ds_read_b64_tr_b16 v[70:71], v219 offset:34304
	ds_read_b64_tr_b16 v[66:67], v219 offset:34368
	ds_read_b64_tr_b16 v[64:65], v219 offset:32832
	v_add_f32_e32 v205, v174, v94
	v_pk_add_f32 v[72:73], v[202:203], v[188:189]
	s_nop 0
	v_pk_add_f32 v[192:193], v[72:73], v[72:73] op_sel_hi:[0,1]
	v_exp_f32_e32 v192, v95
	ds_read_b64_tr_b16 v[76:77], v219 offset:35840
	ds_read_b64_tr_b16 v[78:79], v219 offset:37376
	ds_read_b64_tr_b16 v[74:75], v219 offset:37440
	ds_read_b64_tr_b16 v[72:73], v219 offset:35904
	v_pk_add_f32 v[206:207], v[204:205], v[192:193]
	s_nop 0
	v_pk_add_f32 v[206:207], v[206:207], v[206:207] op_sel:[0,1] op_sel_hi:[1,0]
	s_nop 0
	v_mov_b32_e32 v89, v206
	v_mov_b32_e32 v91, v206
	s_nop 1
	v_permlane32_swap_b32_e32 v89, v91
	v_add_f32_e32 v89, v89, v91
	v_cmp_lt_f32_e32 vcc, s2, v89
	s_cbranch_vccz .LBB0_725
; __device__ __forceinline__ unsigned pk2(float lo, float hi) { f32x2 v = {lo, hi}; bf16x2_t b = __builtin_convertvector(v, bf16x2_t); return __builtin_bit_cast(unsigned, b); }
; __device__ __forceinline__ float hmax(float m) { auto rr = __builtin_amdgcn_permlane32_swap(__float_as_uint(m), __float_as_uint(m), false, false); return fmaxf(__uint_as_float(rr[0]), __uint_as_float(rr[1])); }
; template <int TYPE, int ND0, int KSTR> __device__ __forceinline__ void tile(LAS unsigned char* lds, int buf, int t, int w_lo, int w_hi, int n, int qrel, int lane, int r32, int hi,
;         const bf16x8 (&qr)[ND0], float& m_run, float& l_run, f32x16& o0, f32x16& o1, f32x16& negm) {
;     ...
;     if (__builtin_amdgcn_ballot_w64(lrow > 1099511627776.0f) != 0ull) {
;         float pm = fmaxf(p0[0], p1[0]);
; #pragma unroll
;         for (int r = 1; r < 16; ++r) pm = fmaxf(pm, fmaxf(p0[r], p1[r]));
;         pm = hmax(pm);
;         const float dl = (lrow > 1099511627776.0f) ? __builtin_amdgcn_logf(pm) : 0.f;
;         const float sc = __builtin_amdgcn_exp2f(-dl);
;         m_run += dl; l_run *= sc; ls *= sc;
; #pragma unroll
;         for (int r = 0; r < 16; ++r) { p0[r] *= sc; p1[r] *= sc; o0[r] *= sc; o1[r] *= sc; negm[r] = -m_run; }
;     }
;     l_run += ls;
; #pragma unroll
;     for (int ks = 0; ks < 4; ++ks) {
;         u32x4 pw;
;         if (ks < 2) { pw.x = pk2(p0[8 * ks], p0[8 * ks + 1]); pw.y = pk2(p0[8 * ks + 2], p0[8 * ks + 3]); pw.z = pk2(p0[8 * ks + 4], p0[8 * ks + 5]); pw.w = pk2(p0[8 * ks + 6], p0[8 * ks + 7]); }
;         else { const int k2 = ks - 2; pw.x = pk2(p1[8 * k2], p1[8 * k2 + 1]); pw.y = pk2(p1[8 * k2 + 2], p1[8 * k2 + 3]); pw.z = pk2(p1[8 * k2 + 4], p1[8 * k2 + 5]); pw.w = pk2(p1[8 * k2 + 6], p1[8 * k2 + 7]); }
;         const bf16x8 pb = __builtin_bit_cast(bf16x8, pw);
;         const bf16x8 va0 = __builtin_shufflevector(vf[ks][0], vf[ks][1], 0, 1, 2, 3, 4, 5, 6, 7), va1 = __builtin_shufflevector(vf[ks][2], vf[ks][3], 0, 1, 2, 3, 4, 5, 6, 7);
;         o0 = __builtin_amdgcn_mfma_f32_32x32x16_bf16(va0, pb, o0, 0, 0, 0);
;         o1 = __builtin_amdgcn_mfma_f32_32x32x16_bf16(va1, pb, o1, 0, 0, 0);
;     }
	v_max_f32_e32 v48, v0, v0
	v_max_f32_e32 v49, v186, v186
	v_max_f32_e32 v48, v49, v48
	v_max_f32_e32 v49, v148, v148
	v_max_f32_e32 v50, v156, v156
	v_max_f32_e32 v49, v50, v49
	v_max_f32_e32 v50, v176, v176
	v_max_f32_e32 v51, v190, v190
	v_max3_f32 v48, v154, v146, v48
	v_max_f32_e32 v50, v51, v50
	v_max3_f32 v48, v48, v49, v50
	v_max_f32_e32 v49, v150, v150
	v_max_f32_e32 v50, v158, v158
	v_max_f32_e32 v49, v50, v49
	v_max_f32_e32 v50, v178, v178
	v_max_f32_e32 v51, v194, v194
	v_max_f32_e32 v50, v51, v50
	v_max3_f32 v48, v48, v49, v50
	v_max_f32_e32 v49, v152, v152
	v_max_f32_e32 v50, v162, v162
	v_max_f32_e32 v49, v50, v49
	v_max_f32_e32 v50, v180, v180
	v_max_f32_e32 v51, v196, v196
	v_max_f32_e32 v50, v51, v50
	v_max3_f32 v48, v48, v49, v50
	v_max_f32_e32 v49, v88, v88
	v_max_f32_e32 v50, v160, v160
	v_max_f32_e32 v49, v50, v49
	v_max_f32_e32 v50, v182, v182
	v_max_f32_e32 v51, v198, v198
	v_max_f32_e32 v50, v51, v50
	v_max3_f32 v48, v48, v49, v50
	v_max_f32_e32 v49, v90, v90
	v_max_f32_e32 v50, v170, v170
	v_max_f32_e32 v49, v50, v49
	v_max_f32_e32 v50, v184, v184
	v_max_f32_e32 v51, v200, v200
	v_max_f32_e32 v50, v51, v50
	v_max3_f32 v48, v48, v49, v50
	v_max_f32_e32 v49, v92, v92
	v_max_f32_e32 v50, v172, v172
	v_max_f32_e32 v49, v50, v49
	v_max_f32_e32 v50, v188, v188
	v_max_f32_e32 v51, v202, v202
	v_max_f32_e32 v50, v51, v50
	v_max3_f32 v48, v48, v49, v50
	v_max_f32_e32 v49, v94, v94
	v_max_f32_e32 v50, v174, v174
	v_max_f32_e32 v49, v50, v49
	v_max_f32_e32 v50, v192, v192
	v_max_f32_e32 v51, v204, v204
	v_max_f32_e32 v50, v51, v50
	v_max3_f32 v48, v48, v49, v50
	v_mov_b32_e32 v49, v48
	s_nop 1
	v_permlane32_swap_b32_e32 v48, v49
	v_max_f32_e32 v49, v49, v49
	v_max_f32_e32 v48, v48, v48
	v_max_f32_e32 v48, v48, v49
	v_log_f32_e32 v48, v48
	v_mov_b32_e32 v167, v206
	v_mov_b32_e32 v175, v204
	v_mov_b32_e32 v173, v202
	v_cndmask_b32_e32 v48, 0, v48, vcc
	v_exp_f32_e64 v206, -v48
	v_add_f32_e32 v48, v171, v48
	v_mov_b32_e32 v171, v200
	v_mov_b32_e32 v161, v198
	v_mov_b32_e32 v163, v196
	v_mov_b32_e32 v159, v194
	v_mov_b32_e32 v157, v190
	v_mov_b32_e32 v155, v186
	v_mov_b32_e32 v95, v192
	v_mov_b32_e32 v93, v188
	v_mov_b32_e32 v91, v184
	v_mov_b32_e32 v89, v182
	v_mov_b32_e32 v153, v180
	v_mov_b32_e32 v151, v178
	v_mov_b32_e32 v149, v176
	v_mov_b32_e32 v147, v0
	v_xor_b32_e32 v48, 0x80000000, v48
	v_pk_mul_f32 v[174:175], v[174:175], v[206:207] op_sel_hi:[1,0]
	v_pk_mul_f32 v[172:173], v[172:173], v[206:207] op_sel_hi:[1,0]
	v_pk_mul_f32 v[170:171], v[170:171], v[206:207] op_sel_hi:[1,0]
	v_pk_mul_f32 v[160:161], v[160:161], v[206:207] op_sel_hi:[1,0]
	v_pk_mul_f32 v[162:163], v[162:163], v[206:207] op_sel_hi:[1,0]
	v_pk_mul_f32 v[158:159], v[158:159], v[206:207] op_sel_hi:[1,0]
	v_pk_mul_f32 v[156:157], v[156:157], v[206:207] op_sel_hi:[1,0]
	v_pk_mul_f32 v[154:155], v[154:155], v[206:207] op_sel_hi:[1,0]
	v_pk_mul_f32 v[94:95], v[94:95], v[206:207] op_sel_hi:[1,0]
	v_pk_mul_f32 v[92:93], v[92:93], v[206:207] op_sel_hi:[1,0]
	v_pk_mul_f32 v[90:91], v[90:91], v[206:207] op_sel_hi:[1,0]
	v_pk_mul_f32 v[88:89], v[88:89], v[206:207] op_sel_hi:[1,0]
	v_pk_mul_f32 v[152:153], v[152:153], v[206:207] op_sel_hi:[1,0]
	v_pk_mul_f32 v[150:151], v[150:151], v[206:207] op_sel_hi:[1,0]
	v_pk_mul_f32 v[148:149], v[148:149], v[206:207] op_sel_hi:[1,0]
	v_pk_mul_f32 v[146:147], v[146:147], v[206:207] op_sel_hi:[1,0]
	v_pk_mul_f32 v[166:167], v[166:167], v[206:207] op_sel_hi:[1,0]
	v_pk_mul_f32 v[46:47], v[46:47], v[206:207] op_sel_hi:[1,0]
	v_pk_mul_f32 v[44:45], v[44:45], v[206:207] op_sel_hi:[1,0]
	v_pk_mul_f32 v[42:43], v[42:43], v[206:207] op_sel_hi:[1,0]
	v_pk_mul_f32 v[40:41], v[40:41], v[206:207] op_sel_hi:[1,0]
	v_pk_mul_f32 v[38:39], v[38:39], v[206:207] op_sel_hi:[1,0]
	v_pk_mul_f32 v[36:37], v[36:37], v[206:207] op_sel_hi:[1,0]
	v_pk_mul_f32 v[34:35], v[34:35], v[206:207] op_sel_hi:[1,0]
	v_pk_mul_f32 v[32:33], v[32:33], v[206:207] op_sel_hi:[1,0]
	v_pk_mul_f32 v[30:31], v[30:31], v[206:207] op_sel_hi:[1,0]
	v_pk_mul_f32 v[28:29], v[28:29], v[206:207] op_sel_hi:[1,0]
	v_pk_mul_f32 v[26:27], v[26:27], v[206:207] op_sel_hi:[1,0]
	v_pk_mul_f32 v[24:25], v[24:25], v[206:207] op_sel_hi:[1,0]
	v_pk_mul_f32 v[22:23], v[22:23], v[206:207] op_sel_hi:[1,0]
	v_pk_mul_f32 v[20:21], v[20:21], v[206:207] op_sel_hi:[1,0]
	v_pk_mul_f32 v[18:19], v[18:19], v[206:207] op_sel_hi:[1,0]
	v_pk_mul_f32 v[16:17], v[16:17], v[206:207] op_sel_hi:[1,0]
	v_mov_b32_e32 v49, v48
	v_mov_b32_e32 v50, v48
	v_mov_b32_e32 v51, v48
	v_mov_b32_e32 v52, v48
	v_mov_b32_e32 v53, v48
	v_mov_b32_e32 v54, v48
	v_mov_b32_e32 v55, v48
	v_mov_b32_e32 v56, v48
	v_mov_b32_e32 v57, v48
	v_mov_b32_e32 v58, v48
	v_mov_b32_e32 v59, v48
	v_mov_b32_e32 v60, v48
	v_mov_b32_e32 v61, v48
	v_mov_b32_e32 v62, v48
	v_mov_b32_e32 v63, v48
	v_mov_b32_e32 v0, v147
	v_mov_b32_e32 v176, v149
	v_mov_b32_e32 v178, v151
	v_mov_b32_e32 v180, v153
	v_mov_b32_e32 v182, v89
	v_mov_b32_e32 v184, v91
	v_mov_b32_e32 v188, v93
	v_mov_b32_e32 v192, v95
	v_mov_b32_e32 v186, v155
	v_mov_b32_e32 v190, v157
	v_mov_b32_e32 v194, v159
	v_mov_b32_e32 v196, v163
	v_mov_b32_e32 v198, v161
	v_mov_b32_e32 v200, v171
	v_mov_b32_e32 v202, v173
	v_mov_b32_e32 v204, v175
	v_mov_b32_e32 v206, v167
.LBB0_725:
	v_cvt_pk_bf16_f32 v154, v154, v186
	v_cvt_pk_bf16_f32 v155, v156, v190
	v_cvt_pk_bf16_f32 v156, v158, v194
	v_cvt_pk_bf16_f32 v157, v162, v196
	v_add_f32_e32 v166, v166, v206
	s_waitcnt lgkmcnt(14)
	s_setprio 2
	v_mfma_f32_32x32x16_bf16 v[32:47], v[112:115], v[154:157], v[32:47]
	s_waitcnt lgkmcnt(12)
	v_mfma_f32_32x32x16_bf16 v[16:31], v[108:111], v[154:157], v[16:31]
	v_cvt_pk_bf16_f32 v108, v160, v198
	v_cvt_pk_bf16_f32 v109, v170, v200
	v_cvt_pk_bf16_f32 v110, v172, v202
	v_cvt_pk_bf16_f32 v111, v174, v204
	s_waitcnt lgkmcnt(10)
	s_nop 0
	v_mfma_f32_32x32x16_bf16 v[32:47], v[84:87], v[108:111], v[32:47]
	s_waitcnt lgkmcnt(8)
	v_mfma_f32_32x32x16_bf16 v[16:31], v[80:83], v[108:111], v[16:31]
	v_cvt_pk_bf16_f32 v80, v146, v0
	v_cvt_pk_bf16_f32 v81, v148, v176
	v_cvt_pk_bf16_f32 v82, v150, v178
	v_cvt_pk_bf16_f32 v83, v152, v180
	s_waitcnt lgkmcnt(6)
	s_nop 0
	v_mfma_f32_32x32x16_bf16 v[32:47], v[68:71], v[80:83], v[32:47]
	s_waitcnt lgkmcnt(4)
	v_mfma_f32_32x32x16_bf16 v[16:31], v[64:67], v[80:83], v[16:31]
	v_cvt_pk_bf16_f32 v64, v88, v182
	v_cvt_pk_bf16_f32 v65, v90, v184
	v_cvt_pk_bf16_f32 v66, v92, v188
	v_cvt_pk_bf16_f32 v67, v94, v192
	s_waitcnt lgkmcnt(2)
	s_nop 0
	v_mfma_f32_32x32x16_bf16 v[32:47], v[76:79], v[64:67], v[32:47]
	s_waitcnt lgkmcnt(0)
	v_mfma_f32_32x32x16_bf16 v[16:31], v[72:75], v[64:67], v[16:31]
	s_setprio 0

; template <int TYPE, int ND0, int KSTR> __device__ __forceinline__ void tile(LAS unsigned char* lds, int buf, int t, int w_lo, int w_hi, int n, int qrel, int lane, int r32, int hi,
;         const bf16x8 (&qr)[ND0], float& m_run, float& l_run, f32x16& o0, f32x16& o1, f32x16& negm) {
;     const LAS unsigned char* kb = lds + KOFF + buf * KBUF + r32 * KSTR + hi * 16;
;     bf16x8 ka[ND0], kc[ND0];
; #pragma unroll
;     for (int d0 = 0; d0 < ND0; ++d0) { ka[d0] = *(const LAS bf16x8*)(kb + d0 * 32); kc[d0] = *(const LAS bf16x8*)(kb + 32 * KSTR + d0 * 32); }
;     const LAS unsigned char* vb = lds + VOFF + buf * VBUF + (4 * hi + ((lane & 15) >> 2)) * VSTR + (16 * ((lane >> 4) & 1) + 4 * (lane & 3)) * 2;
;     s16x4 vf[4][4];
; #pragma unroll
;     for (int ks = 0; ks < 4; ++ks) { vf[ks][0] = vtr(vb + (16 * ks) * VSTR); vf[ks][1] = vtr(vb + (16 * ks + 8) * VSTR); vf[ks][2] = vtr(vb + (16 * ks) * VSTR + 64); vf[ks][3] = vtr(vb + (16 * ks + 8) * VSTR + 64); }
;     f32x4 kbv[8];
;     if (TYPE == 0) { const LAS f32x4* kbi = (const LAS f32x4*)(lds + KBOFF + buf * 256);
; #pragma unroll
;         for (int g = 0; g < 4; ++g) { kbv[g] = kbi[2 * g + hi]; kbv[4 + g] = kbi[8 + 2 * g + hi]; } }
;     asm volatile("" ::: "memory");
;     const int rel = n - t;
;     f32x16 cin = negm;
;     if (TYPE == 2 && rel >= 5) { const float c = ((const LAS float*)(lds + RELOFF))[512];
; #pragma unroll
;         for (int r = 0; r < 16; ++r) cin[r] += c; }
;     f32x16 p0 = cin, p1 = cin;
; #pragma unroll
;     for (int d0 = 0; d0 < ND0; ++d0) {
;         p0 = __builtin_amdgcn_mfma_f32_32x32x16_bf16(ka[d0], qr[d0], p0, 0, 0, 0);
;         p1 = __builtin_amdgcn_mfma_f32_32x32x16_bf16(kc[d0], qr[d0], p1, 0, 0, 0);
;     }
;     if (TYPE == 0) {
; #pragma unroll
;         for (int g = 0; g < 4; ++g)
; #pragma unroll
;             for (int j = 0; j < 4; ++j) { p0[4 * g + j] += kbv[g][j]; p1[4 * g + j] += kbv[4 + g][j]; }
;         if (t == w_hi) {
; template <int TYPE> __device__ __forceinline__ int unit(const P& p, LAS unsigned char* lds, int b, int h, int qb, int wave0, bool pre, unsigned nx, int G,
;         u32x4& kA, u32x4& vA, u32x4& k2A, float& cbA, u32x4& kB, u32x4& vB, u32x4& k2B, float& cbB) {
;     ...
;         ATT_LOAD_NEXT(1, B);
;         if (t + 1 >= w_lo && t + 1 <= w_hi) tile<TYPE, ND0, KSTR>(lds, 1, t + 1, w_lo, w_hi, n, qrel, lane, r32, hi, qr, m_run, l_run, o0, o1, negm);
.LBB0_728:
	s_or_b64 exec, exec, s[4:5]
	v_add_co_u32_e32 v66, vcc, 0x10000, v118
	s_waitcnt lgkmcnt(0)
	s_nop 0
	v_addc_co_u32_e32 v67, vcc, 0, v119, vcc
	v_add_co_u32_e32 v14, vcc, 0x10000, v14
	s_barrier
	s_nop 0
	v_addc_co_u32_e32 v15, vcc, 0, v15, vcc
	global_load_dwordx4 v[84:87], v[14:15], off
	v_add_co_u32_e32 v14, vcc, 0x1000, v116
	global_load_dwordx4 v[80:83], v[66:67], off
	s_nop 0
	v_addc_co_u32_e32 v15, vcc, 0, v117, vcc
	global_load_dwordx4 v[88:91], v[14:15], off
	global_load_dword v238, v[64:65], off offset:256
	s_cmp_ge_i32 s6, s9
	s_cbranch_scc1 .LBB0_587
	ds_read_b128 v[92:95], v220 offset:13312
	ds_read_b128 v[96:99], v220 offset:13344
	s_mov_b32 s0, 0x53800000
	s_waitcnt lgkmcnt(1)
	s_setprio 2
	v_mfma_f32_32x32x16_bf16 v[64:79], v[92:95], v[140:143], v[48:63]
	ds_read_b128 v[92:95], v220 offset:19968
	s_waitcnt vmcnt(8)
	ds_read_b128 v[100:103], v220 offset:20000
	s_waitcnt lgkmcnt(1)
	v_mfma_f32_32x32x16_bf16 v[48:63], v[92:95], v[140:143], v[48:63]
	v_mfma_f32_32x32x16_bf16 v[64:79], v[96:99], v[136:139], v[64:79]
	ds_read_b128 v[92:95], v220 offset:13376
	ds_read_b128 v[96:99], v220 offset:13408
	s_waitcnt lgkmcnt(2)
	v_mfma_f32_32x32x16_bf16 v[48:63], v[100:103], v[136:139], v[48:63]
	s_waitcnt lgkmcnt(1)
	v_mfma_f32_32x32x16_bf16 v[64:79], v[92:95], v[132:135], v[64:79]
	ds_read_b128 v[92:95], v220 offset:20032
	ds_read_b128 v[100:103], v220 offset:20064
	s_waitcnt lgkmcnt(1)
	v_mfma_f32_32x32x16_bf16 v[48:63], v[92:95], v[132:135], v[48:63]
	v_mfma_f32_32x32x16_bf16 v[64:79], v[96:99], v[128:131], v[64:79]
	ds_read_b128 v[92:95], v220 offset:13440
	ds_read_b128 v[96:99], v220 offset:13472
	s_waitcnt lgkmcnt(2)
	v_mfma_f32_32x32x16_bf16 v[48:63], v[100:103], v[128:131], v[48:63]
	s_waitcnt lgkmcnt(1)
	v_mfma_f32_32x32x16_bf16 v[64:79], v[92:95], v[124:127], v[64:79]
	ds_read_b128 v[92:95], v220 offset:20096
	ds_read_b128 v[100:103], v220 offset:20128
	s_waitcnt lgkmcnt(1)
	v_mfma_f32_32x32x16_bf16 v[48:63], v[92:95], v[124:127], v[48:63]
	v_mfma_f32_32x32x16_bf16 v[64:79], v[96:99], v[120:123], v[64:79]
	ds_read_b64_tr_b16 v[96:97], v219 offset:38912
	ds_read_b64_tr_b16 v[98:99], v219 offset:40448
	ds_read_b64_tr_b16 v[94:95], v219 offset:40512
	ds_read_b64_tr_b16 v[92:93], v219 offset:38976
	s_waitcnt lgkmcnt(4)
	v_mfma_f32_32x32x16_bf16 v[48:63], v[100:103], v[120:123], v[48:63]
	s_setprio 0
	s_nop 5
	v_exp_f32_e32 v106, v64
	v_exp_f32_e32 v132, v65
	v_exp_f32_e32 v108, v66
	v_exp_f32_e32 v136, v67
	v_exp_f32_e32 v110, v68
	v_exp_f32_e32 v140, v69
	v_exp_f32_e32 v114, v70
	v_exp_f32_e32 v14, v48
	v_exp_f32_e32 v0, v49
	v_exp_f32_e32 v100, v50
	v_exp_f32_e32 v102, v52
	v_add_f32_e32 v133, v106, v14
	v_pk_add_f32 v[48:49], v[132:133], v[0:1]
	v_add_f32_e32 v137, v108, v100
	v_pk_add_f32 v[122:123], v[48:49], v[48:49] op_sel_hi:[0,1]
	v_exp_f32_e32 v122, v51
	v_add_f32_e32 v141, v110, v102
	v_exp_f32_e32 v104, v54
	v_exp_f32_e32 v142, v71
	v_pk_add_f32 v[48:49], v[136:137], v[122:123]
	v_exp_f32_e32 v112, v72
	v_pk_add_f32 v[124:125], v[48:49], v[48:49] op_sel_hi:[0,1]
	v_exp_f32_e32 v124, v53
	v_add_f32_e32 v143, v114, v104
	v_exp_f32_e32 v72, v56
	v_exp_f32_e32 v144, v73
	v_pk_add_f32 v[48:49], v[140:141], v[124:125]
	v_exp_f32_e32 v116, v74
	v_pk_add_f32 v[126:127], v[48:49], v[48:49] op_sel_hi:[0,1]
	v_exp_f32_e32 v126, v55
	v_add_f32_e32 v145, v112, v72
	v_exp_f32_e32 v74, v58
	v_exp_f32_e32 v146, v75
	v_pk_add_f32 v[48:49], v[142:143], v[126:127]
	v_exp_f32_e32 v118, v76
	v_pk_add_f32 v[128:129], v[48:49], v[48:49] op_sel_hi:[0,1]
	v_exp_f32_e32 v128, v57
	v_add_f32_e32 v147, v116, v74
	v_exp_f32_e32 v76, v60
	v_exp_f32_e32 v148, v77
	v_pk_add_f32 v[48:49], v[144:145], v[128:129]
	v_exp_f32_e32 v120, v78
	v_pk_add_f32 v[130:131], v[48:49], v[48:49] op_sel_hi:[0,1]
	v_exp_f32_e32 v130, v59
	v_add_f32_e32 v149, v118, v76
	v_exp_f32_e32 v78, v62
	v_exp_f32_e32 v150, v79
	v_pk_add_f32 v[56:57], v[146:147], v[130:131]
	ds_read_b64_tr_b16 v[68:69], v219 offset:41984
	ds_read_b64_tr_b16 v[70:71], v219 offset:43520
	ds_read_b64_tr_b16 v[66:67], v219 offset:43584
	ds_read_b64_tr_b16 v[64:65], v219 offset:42048
	v_pk_add_f32 v[134:135], v[56:57], v[56:57] op_sel_hi:[0,1]
	v_exp_f32_e32 v134, v61
	ds_read_b64_tr_b16 v[52:53], v219 offset:45056
	ds_read_b64_tr_b16 v[54:55], v219 offset:46592
	ds_read_b64_tr_b16 v[50:51], v219 offset:46656
	ds_read_b64_tr_b16 v[48:49], v219 offset:45120
	v_add_f32_e32 v151, v120, v78
	v_pk_add_f32 v[56:57], v[148:149], v[134:135]
	s_nop 0
	v_pk_add_f32 v[138:139], v[56:57], v[56:57] op_sel_hi:[0,1]
	v_exp_f32_e32 v138, v63
	ds_read_b64_tr_b16 v[60:61], v219 offset:48128
	ds_read_b64_tr_b16 v[62:63], v219 offset:49664
	ds_read_b64_tr_b16 v[58:59], v219 offset:49728
	ds_read_b64_tr_b16 v[56:57], v219 offset:48192
	v_pk_add_f32 v[152:153], v[150:151], v[138:139]
	s_nop 0
	v_pk_add_f32 v[152:153], v[152:153], v[152:153] op_sel:[0,1] op_sel_hi:[1,0]
	s_nop 0
	v_mov_b32_e32 v15, v152
	v_mov_b32_e32 v73, v152
	s_nop 1
	v_permlane32_swap_b32_e32 v15, v73
	v_add_f32_e32 v15, v15, v73
	v_cmp_lt_f32_e32 vcc, s0, v15
	s_cbranch_vccz .LBB0_586
; __device__ __forceinline__ float hmax(float m) { auto rr = __builtin_amdgcn_permlane32_swap(__float_as_uint(m), __float_as_uint(m), false, false); return fmaxf(__uint_as_float(rr[0]), __uint_as_float(rr[1])); }
; template <int TYPE, int ND0, int KSTR> __device__ __forceinline__ void tile(LAS unsigned char* lds, int buf, int t, int w_lo, int w_hi, int n, int qrel, int lane, int r32, int hi,
;         const bf16x8 (&qr)[ND0], float& m_run, float& l_run, f32x16& o0, f32x16& o1, f32x16& negm) {
;     ...
;     if (__builtin_amdgcn_ballot_w64(lrow > 1099511627776.0f) != 0ull) {
;         float pm = fmaxf(p0[0], p1[0]);
; #pragma unroll
;         for (int r = 1; r < 16; ++r) pm = fmaxf(pm, fmaxf(p0[r], p1[r]));
;         pm = hmax(pm);
;         const float dl = (lrow > 1099511627776.0f) ? __builtin_amdgcn_logf(pm) : 0.f;
;         const float sc = __builtin_amdgcn_exp2f(-dl);
;         m_run += dl; l_run *= sc; ls *= sc;
; #pragma unroll
;         for (int r = 0; r < 16; ++r) { p0[r] *= sc; p1[r] *= sc; o0[r] *= sc; o1[r] *= sc; negm[r] = -m_run; }
;     }
	v_max_f32_e32 v15, v0, v0
	v_max_f32_e32 v73, v132, v132
	v_max_f32_e32 v15, v73, v15
	v_max_f32_e32 v73, v100, v100
	v_max_f32_e32 v75, v108, v108
	v_max_f32_e32 v73, v75, v73
	v_max_f32_e32 v75, v122, v122
	v_max_f32_e32 v77, v136, v136
	v_max3_f32 v15, v106, v14, v15
	v_max_f32_e32 v75, v77, v75
	v_max3_f32 v15, v15, v73, v75
	v_max_f32_e32 v73, v102, v102
	v_max_f32_e32 v75, v110, v110
	v_max_f32_e32 v73, v75, v73
	v_max_f32_e32 v75, v124, v124
	v_max_f32_e32 v77, v140, v140
	v_max_f32_e32 v75, v77, v75
	v_max3_f32 v15, v15, v73, v75
	v_max_f32_e32 v73, v104, v104
	v_max_f32_e32 v75, v114, v114
	v_max_f32_e32 v73, v75, v73
	v_max_f32_e32 v75, v126, v126
	v_max_f32_e32 v77, v142, v142
	v_max_f32_e32 v75, v77, v75
	v_max3_f32 v15, v15, v73, v75
	v_max_f32_e32 v73, v72, v72
	v_max_f32_e32 v75, v112, v112
	v_max_f32_e32 v73, v75, v73
	v_max_f32_e32 v75, v128, v128
	v_max_f32_e32 v77, v144, v144
	v_max_f32_e32 v75, v77, v75
	v_max3_f32 v15, v15, v73, v75
	v_max_f32_e32 v73, v74, v74
	v_max_f32_e32 v75, v116, v116
	v_max_f32_e32 v73, v75, v73
	v_max_f32_e32 v75, v130, v130
	v_max_f32_e32 v77, v146, v146
	v_max_f32_e32 v75, v77, v75
	v_max3_f32 v15, v15, v73, v75
	v_max_f32_e32 v73, v76, v76
	v_max_f32_e32 v75, v118, v118
	v_max_f32_e32 v73, v75, v73
	v_max_f32_e32 v75, v134, v134
	v_max_f32_e32 v77, v148, v148
	v_max_f32_e32 v75, v77, v75
	v_max3_f32 v15, v15, v73, v75
	v_max_f32_e32 v73, v78, v78
	v_max_f32_e32 v75, v120, v120
	v_max_f32_e32 v73, v75, v73
	v_max_f32_e32 v75, v138, v138
	v_max_f32_e32 v77, v150, v150
	v_max_f32_e32 v75, v77, v75
	v_max3_f32 v15, v15, v73, v75
	v_mov_b32_e32 v73, v15
	s_nop 1
	v_permlane32_swap_b32_e32 v15, v73
	v_max_f32_e32 v73, v73, v73
	v_max_f32_e32 v15, v15, v15
	v_max_f32_e32 v15, v15, v73
	v_log_f32_e32 v15, v15
	v_bfrev_b32_e32 v73, 1
	v_mov_b32_e32 v167, v152
	v_mov_b32_e32 v121, v150
	v_cndmask_b32_e64 v15, v73, -v15, vcc
	v_exp_f32_e32 v152, v15
	v_mov_b32_e32 v119, v148
	v_mov_b32_e32 v117, v146
	v_mov_b32_e32 v113, v144
	v_mov_b32_e32 v115, v142
	v_mov_b32_e32 v111, v140
	v_mov_b32_e32 v109, v136
	v_mov_b32_e32 v107, v132
	v_mov_b32_e32 v79, v138
	v_mov_b32_e32 v77, v134
	v_mov_b32_e32 v75, v130
	v_mov_b32_e32 v73, v128
	v_mov_b32_e32 v105, v126
	v_mov_b32_e32 v103, v124
	v_mov_b32_e32 v101, v122
	v_mov_b32_e32 v15, v0
	v_pk_mul_f32 v[120:121], v[120:121], v[152:153] op_sel_hi:[1,0]
	v_pk_mul_f32 v[118:119], v[118:119], v[152:153] op_sel_hi:[1,0]
	v_pk_mul_f32 v[116:117], v[116:117], v[152:153] op_sel_hi:[1,0]
	v_pk_mul_f32 v[112:113], v[112:113], v[152:153] op_sel_hi:[1,0]
	v_pk_mul_f32 v[114:115], v[114:115], v[152:153] op_sel_hi:[1,0]
	v_pk_mul_f32 v[110:111], v[110:111], v[152:153] op_sel_hi:[1,0]
	v_pk_mul_f32 v[108:109], v[108:109], v[152:153] op_sel_hi:[1,0]
	v_pk_mul_f32 v[106:107], v[106:107], v[152:153] op_sel_hi:[1,0]
	v_pk_mul_f32 v[78:79], v[78:79], v[152:153] op_sel_hi:[1,0]
	v_pk_mul_f32 v[76:77], v[76:77], v[152:153] op_sel_hi:[1,0]
	v_pk_mul_f32 v[74:75], v[74:75], v[152:153] op_sel_hi:[1,0]
	v_pk_mul_f32 v[72:73], v[72:73], v[152:153] op_sel_hi:[1,0]
	v_pk_mul_f32 v[104:105], v[104:105], v[152:153] op_sel_hi:[1,0]
	v_pk_mul_f32 v[102:103], v[102:103], v[152:153] op_sel_hi:[1,0]
	v_pk_mul_f32 v[100:101], v[100:101], v[152:153] op_sel_hi:[1,0]
	v_pk_mul_f32 v[14:15], v[14:15], v[152:153] op_sel_hi:[1,0]
	v_pk_mul_f32 v[166:167], v[166:167], v[152:153] op_sel_hi:[1,0]
	v_pk_mul_f32 v[46:47], v[46:47], v[152:153] op_sel_hi:[1,0]
	v_pk_mul_f32 v[44:45], v[44:45], v[152:153] op_sel_hi:[1,0]
	v_pk_mul_f32 v[42:43], v[42:43], v[152:153] op_sel_hi:[1,0]
	v_pk_mul_f32 v[40:41], v[40:41], v[152:153] op_sel_hi:[1,0]
	v_pk_mul_f32 v[38:39], v[38:39], v[152:153] op_sel_hi:[1,0]
	v_pk_mul_f32 v[36:37], v[36:37], v[152:153] op_sel_hi:[1,0]
	v_pk_mul_f32 v[34:35], v[34:35], v[152:153] op_sel_hi:[1,0]
	v_pk_mul_f32 v[32:33], v[32:33], v[152:153] op_sel_hi:[1,0]
	v_pk_mul_f32 v[30:31], v[30:31], v[152:153] op_sel_hi:[1,0]
	v_pk_mul_f32 v[28:29], v[28:29], v[152:153] op_sel_hi:[1,0]
	v_pk_mul_f32 v[26:27], v[26:27], v[152:153] op_sel_hi:[1,0]
	v_pk_mul_f32 v[24:25], v[24:25], v[152:153] op_sel_hi:[1,0]
	v_pk_mul_f32 v[22:23], v[22:23], v[152:153] op_sel_hi:[1,0]
	v_pk_mul_f32 v[20:21], v[20:21], v[152:153] op_sel_hi:[1,0]
	v_pk_mul_f32 v[18:19], v[18:19], v[152:153] op_sel_hi:[1,0]
	v_pk_mul_f32 v[16:17], v[16:17], v[152:153] op_sel_hi:[1,0]
	v_mov_b32_e32 v0, v15
	v_mov_b32_e32 v122, v101
	v_mov_b32_e32 v124, v103
	v_mov_b32_e32 v126, v105
	v_mov_b32_e32 v128, v73
	v_mov_b32_e32 v130, v75
	v_mov_b32_e32 v134, v77
	v_mov_b32_e32 v138, v79
	v_mov_b32_e32 v132, v107
	v_mov_b32_e32 v136, v109
	v_mov_b32_e32 v140, v111
	v_mov_b32_e32 v142, v115
	v_mov_b32_e32 v144, v113
	v_mov_b32_e32 v146, v117
	v_mov_b32_e32 v148, v119
	v_mov_b32_e32 v150, v121
	v_mov_b32_e32 v152, v167
	s_branch .LBB0_586
